# K-loop segment hand-off: load segment raises priority before its closing barrier, redundant lgkmcnt(0) behind the barrier removed, MMA segment drops priority after its closing barrier (plus no mid-seg
# speedup vs baseline: 1.0111x; 1.0106x over previous
.LBB0_552:
	s_add_u32 s54, s44, 0xfff80080
	s_addc_u32 s55, s45, -1
	s_waitcnt lgkmcnt(0)
	s_add_i32 s82, 0, 0x10000
	s_cmp_eq_u32 s76, 28
	s_cselect_b32 s57, s41, s55
	s_cselect_b32 s56, s43, s54
	v_add_u32_e32 v161, s82, v159
	s_cselect_b32 s55, s35, s75
	s_cselect_b32 s54, s47, s74
	s_add_i32 vcc_lo, 0, 0x14000
	ds_read_b128 v[144:147], v161
	ds_read_b128 v[148:151], v161 offset:1024
	ds_read_b128 v[152:155], v161 offset:2048
	ds_read_b128 v[162:165], v161 offset:3072
	v_add_u32_e32 v161, vcc_lo, v159
	ds_read_b128 v[166:169], v161
	ds_read_b128 v[170:173], v161 offset:1024
	ds_read_b128 v[174:177], v161 offset:2048
	ds_read_b128 v[190:193], v161 offset:3072
	v_lshl_add_u64 v[178:179], s[44:45], 0, v[140:141]
	s_add_i32 m0, s58, 0xc000
	ds_read_b128 v[194:197], v160
	ds_read_b128 v[198:201], v160 offset:1024
	ds_read_b128 v[202:205], v160 offset:2048
	ds_read_b128 v[206:209], v160 offset:3072
	ds_read_b128 v[210:213], v160 offset:4096
	ds_read_b128 v[214:217], v160 offset:5120
	ds_read_b128 v[218:221], v160 offset:6144
	ds_read_b128 v[238:241], v160 offset:7168
	global_load_lds_dwordx4 v[178:179], off
	v_lshl_add_u64 v[178:179], s[44:45], 0, v[142:143]
	s_add_i32 m0, s58, 0xe000
	s_nop 0
	global_load_lds_dwordx4 v[178:179], off
	s_waitcnt vmcnt(8)
	s_waitcnt lgkmcnt(0)
	s_setprio 1
	s_barrier
	v_mfma_f32_16x16x32_bf16 v[126:129], v[144:147], v[194:197], v[126:129]
	v_mfma_f32_16x16x32_bf16 v[122:125], v[152:155], v[194:197], v[122:125]
	v_mfma_f32_16x16x32_bf16 v[110:113], v[144:147], v[202:205], v[110:113]
	v_mfma_f32_16x16x32_bf16 v[106:109], v[152:155], v[202:205], v[106:109]
	v_mfma_f32_16x16x32_bf16 v[94:97], v[144:147], v[210:213], v[94:97]
	v_mfma_f32_16x16x32_bf16 v[90:93], v[152:155], v[210:213], v[90:93]
	v_mfma_f32_16x16x32_bf16 v[78:81], v[144:147], v[218:221], v[78:81]
	v_mfma_f32_16x16x32_bf16 v[74:77], v[152:155], v[218:221], v[74:77]
	v_mfma_f32_16x16x32_bf16 v[126:129], v[148:151], v[198:201], v[126:129]
	v_mfma_f32_16x16x32_bf16 v[122:125], v[162:165], v[198:201], v[122:125]
	v_mfma_f32_16x16x32_bf16 v[110:113], v[148:151], v[206:209], v[110:113]
	v_mfma_f32_16x16x32_bf16 v[106:109], v[162:165], v[206:209], v[106:109]
	v_mfma_f32_16x16x32_bf16 v[94:97], v[148:151], v[214:217], v[94:97]
	v_mfma_f32_16x16x32_bf16 v[90:93], v[162:165], v[214:217], v[90:93]
	v_mfma_f32_16x16x32_bf16 v[78:81], v[148:151], v[238:241], v[78:81]
	v_mfma_f32_16x16x32_bf16 v[74:77], v[162:165], v[238:241], v[74:77]
	v_mfma_f32_16x16x32_bf16 v[118:121], v[166:169], v[194:197], v[118:121]
	v_mfma_f32_16x16x32_bf16 v[114:117], v[174:177], v[194:197], v[114:117]
	v_mfma_f32_16x16x32_bf16 v[102:105], v[166:169], v[202:205], v[102:105]
	v_mfma_f32_16x16x32_bf16 v[98:101], v[174:177], v[202:205], v[98:101]
	v_mfma_f32_16x16x32_bf16 v[86:89], v[166:169], v[210:213], v[86:89]
	v_mfma_f32_16x16x32_bf16 v[82:85], v[174:177], v[210:213], v[82:85]
	v_mfma_f32_16x16x32_bf16 v[70:73], v[166:169], v[218:221], v[70:73]
	v_mfma_f32_16x16x32_bf16 v[66:69], v[174:177], v[218:221], v[66:69]
	v_mfma_f32_16x16x32_bf16 v[118:121], v[170:173], v[198:201], v[118:121]
	v_mfma_f32_16x16x32_bf16 v[114:117], v[190:193], v[198:201], v[114:117]
	v_mfma_f32_16x16x32_bf16 v[102:105], v[170:173], v[206:209], v[102:105]
	v_mfma_f32_16x16x32_bf16 v[98:101], v[190:193], v[206:209], v[98:101]
	v_mfma_f32_16x16x32_bf16 v[86:89], v[170:173], v[214:217], v[86:89]
	v_mfma_f32_16x16x32_bf16 v[82:85], v[190:193], v[214:217], v[82:85]
	v_mfma_f32_16x16x32_bf16 v[70:73], v[170:173], v[238:241], v[70:73]
	v_mfma_f32_16x16x32_bf16 v[66:69], v[190:193], v[238:241], v[66:69]
	s_barrier
	s_setprio 0
	s_add_i32 s82, s82, s9
	v_lshl_add_u64 v[178:179], s[54:55], 0, v[134:135]
	s_mov_b32 m0, s82
	ds_read_b128 v[194:197], v160 offset:16384
	ds_read_b128 v[198:201], v160 offset:17408
	ds_read_b128 v[202:205], v160 offset:18432
	ds_read_b128 v[206:209], v160 offset:19456
	ds_read_b128 v[210:213], v160 offset:20480
	ds_read_b128 v[214:217], v160 offset:21504
	ds_read_b128 v[218:221], v160 offset:22528
	ds_read_b128 v[238:241], v160 offset:23552
	global_load_lds_dwordx4 v[178:179], off
	s_add_i32 m0, s82, 0x2000
	s_add_u32 s82, s54, 0x80000
	v_lshl_add_u64 v[222:223], s[54:55], 0, v[138:139]
	s_addc_u32 s83, s55, 0
	s_add_i32 vcc_lo, vcc_lo, s9
	global_load_lds_dwordx4 v[222:223], off
	v_lshl_add_u64 v[242:243], s[82:83], 0, v[134:135]
	s_mov_b32 m0, vcc_lo
	v_lshl_add_u64 v[244:245], s[56:57], 0, v[136:137]
	global_load_lds_dwordx4 v[242:243], off
	v_lshl_add_u64 v[242:243], s[82:83], 0, v[138:139]
	s_add_i32 m0, vcc_lo, 0x2000
	s_nop 0
	global_load_lds_dwordx4 v[242:243], off
	v_lshl_add_u64 v[242:243], s[56:57], 0, v[132:133]
	s_mov_b32 m0, s58
	s_nop 0
	global_load_lds_dwordx4 v[242:243], off
	s_mov_b32 m0, s59
	s_nop 0
	global_load_lds_dwordx4 v[244:245], off
	s_waitcnt vmcnt(8)
	s_waitcnt lgkmcnt(0)
	s_setprio 1
	s_barrier
	v_mfma_f32_16x16x32_bf16 v[62:65], v[144:147], v[194:197], v[62:65]
	v_mfma_f32_16x16x32_bf16 v[58:61], v[152:155], v[194:197], v[58:61]
	v_mfma_f32_16x16x32_bf16 v[46:49], v[144:147], v[202:205], v[46:49]
	v_mfma_f32_16x16x32_bf16 v[42:45], v[152:155], v[202:205], v[42:45]
	v_mfma_f32_16x16x32_bf16 v[30:33], v[144:147], v[210:213], v[30:33]
	v_mfma_f32_16x16x32_bf16 v[26:29], v[152:155], v[210:213], v[26:29]
	v_mfma_f32_16x16x32_bf16 v[14:17], v[144:147], v[218:221], v[14:17]
	v_mfma_f32_16x16x32_bf16 v[10:13], v[152:155], v[218:221], v[10:13]
	v_mfma_f32_16x16x32_bf16 v[62:65], v[148:151], v[198:201], v[62:65]
	v_mfma_f32_16x16x32_bf16 v[58:61], v[162:165], v[198:201], v[58:61]
	v_mfma_f32_16x16x32_bf16 v[46:49], v[148:151], v[206:209], v[46:49]
	v_mfma_f32_16x16x32_bf16 v[42:45], v[162:165], v[206:209], v[42:45]
	v_mfma_f32_16x16x32_bf16 v[30:33], v[148:151], v[214:217], v[30:33]
	v_mfma_f32_16x16x32_bf16 v[26:29], v[162:165], v[214:217], v[26:29]
	v_mfma_f32_16x16x32_bf16 v[14:17], v[148:151], v[238:241], v[14:17]
	v_mfma_f32_16x16x32_bf16 v[10:13], v[162:165], v[238:241], v[10:13]
	v_mfma_f32_16x16x32_bf16 v[54:57], v[166:169], v[194:197], v[54:57]
	v_mfma_f32_16x16x32_bf16 v[50:53], v[174:177], v[194:197], v[50:53]
	v_mfma_f32_16x16x32_bf16 v[38:41], v[166:169], v[202:205], v[38:41]
	v_mfma_f32_16x16x32_bf16 v[34:37], v[174:177], v[202:205], v[34:37]
	v_mfma_f32_16x16x32_bf16 v[22:25], v[166:169], v[210:213], v[22:25]
	v_mfma_f32_16x16x32_bf16 v[18:21], v[174:177], v[210:213], v[18:21]
	v_mfma_f32_16x16x32_bf16 v[6:9], v[166:169], v[218:221], v[6:9]
	v_mfma_f32_16x16x32_bf16 v[2:5], v[174:177], v[218:221], v[2:5]
	v_mfma_f32_16x16x32_bf16 v[54:57], v[170:173], v[198:201], v[54:57]
	v_mfma_f32_16x16x32_bf16 v[50:53], v[190:193], v[198:201], v[50:53]
	v_mfma_f32_16x16x32_bf16 v[38:41], v[170:173], v[206:209], v[38:41]
	v_mfma_f32_16x16x32_bf16 v[34:37], v[190:193], v[206:209], v[34:37]
	v_mfma_f32_16x16x32_bf16 v[22:25], v[170:173], v[214:217], v[22:25]
	v_mfma_f32_16x16x32_bf16 v[18:21], v[190:193], v[214:217], v[18:21]
	v_mfma_f32_16x16x32_bf16 v[6:9], v[170:173], v[238:241], v[6:9]
	v_mfma_f32_16x16x32_bf16 v[2:5], v[190:193], v[238:241], v[2:5]
	s_barrier
	s_setprio 0
	s_add_i32 s82, 0, 0x18000
	v_add_u32_e32 v161, s82, v159
	s_add_i32 s83, 0, 0x1c000
	ds_read_b128 v[144:147], v161
	ds_read_b128 v[148:151], v161 offset:1024
	ds_read_b128 v[152:155], v161 offset:2048
	ds_read_b128 v[162:165], v161 offset:3072
	v_add_u32_e32 v161, s83, v159
	ds_read_b128 v[166:169], v161
	ds_read_b128 v[170:173], v161 offset:1024
	ds_read_b128 v[174:177], v161 offset:2048
	ds_read_b128 v[190:193], v161 offset:3072
	s_add_u32 s56, s56, 0x80000
	s_addc_u32 s57, s57, 0
	s_mov_b32 m0, s60
	v_lshl_add_u64 v[246:247], s[56:57], 0, v[132:133]
	ds_read_b128 v[194:197], v160 offset:32768
	ds_read_b128 v[198:201], v160 offset:33792
	ds_read_b128 v[202:205], v160 offset:34816
	ds_read_b128 v[206:209], v160 offset:35840
	ds_read_b128 v[210:213], v160 offset:36864
	ds_read_b128 v[214:217], v160 offset:37888
	ds_read_b128 v[218:221], v160 offset:38912
	ds_read_b128 v[238:241], v160 offset:39936
	global_load_lds_dwordx4 v[246:247], off
	v_lshl_add_u64 v[246:247], s[56:57], 0, v[136:137]
	s_mov_b32 m0, s61
	s_nop 0
	global_load_lds_dwordx4 v[246:247], off
	s_waitcnt vmcnt(8)
	s_waitcnt lgkmcnt(0)
	s_setprio 1
	s_barrier
	v_mfma_f32_16x16x32_bf16 v[126:129], v[144:147], v[194:197], v[126:129]
	v_mfma_f32_16x16x32_bf16 v[122:125], v[152:155], v[194:197], v[122:125]
	v_mfma_f32_16x16x32_bf16 v[110:113], v[144:147], v[202:205], v[110:113]
	v_mfma_f32_16x16x32_bf16 v[106:109], v[152:155], v[202:205], v[106:109]
	v_mfma_f32_16x16x32_bf16 v[94:97], v[144:147], v[210:213], v[94:97]
	v_mfma_f32_16x16x32_bf16 v[90:93], v[152:155], v[210:213], v[90:93]
	v_mfma_f32_16x16x32_bf16 v[78:81], v[144:147], v[218:221], v[78:81]
	v_mfma_f32_16x16x32_bf16 v[74:77], v[152:155], v[218:221], v[74:77]
	v_mfma_f32_16x16x32_bf16 v[126:129], v[148:151], v[198:201], v[126:129]
	v_mfma_f32_16x16x32_bf16 v[122:125], v[162:165], v[198:201], v[122:125]
	v_mfma_f32_16x16x32_bf16 v[110:113], v[148:151], v[206:209], v[110:113]
	v_mfma_f32_16x16x32_bf16 v[106:109], v[162:165], v[206:209], v[106:109]
	v_mfma_f32_16x16x32_bf16 v[94:97], v[148:151], v[214:217], v[94:97]
	v_mfma_f32_16x16x32_bf16 v[90:93], v[162:165], v[214:217], v[90:93]
	v_mfma_f32_16x16x32_bf16 v[78:81], v[148:151], v[238:241], v[78:81]
	v_mfma_f32_16x16x32_bf16 v[74:77], v[162:165], v[238:241], v[74:77]
	v_mfma_f32_16x16x32_bf16 v[118:121], v[166:169], v[194:197], v[118:121]
	v_mfma_f32_16x16x32_bf16 v[114:117], v[174:177], v[194:197], v[114:117]
	v_mfma_f32_16x16x32_bf16 v[102:105], v[166:169], v[202:205], v[102:105]
	v_mfma_f32_16x16x32_bf16 v[98:101], v[174:177], v[202:205], v[98:101]
	v_mfma_f32_16x16x32_bf16 v[86:89], v[166:169], v[210:213], v[86:89]
	v_mfma_f32_16x16x32_bf16 v[82:85], v[174:177], v[210:213], v[82:85]
	v_mfma_f32_16x16x32_bf16 v[70:73], v[166:169], v[218:221], v[70:73]
	v_mfma_f32_16x16x32_bf16 v[66:69], v[174:177], v[218:221], v[66:69]
	v_mfma_f32_16x16x32_bf16 v[118:121], v[170:173], v[198:201], v[118:121]
	v_mfma_f32_16x16x32_bf16 v[114:117], v[190:193], v[198:201], v[114:117]
	v_mfma_f32_16x16x32_bf16 v[102:105], v[170:173], v[206:209], v[102:105]
	v_mfma_f32_16x16x32_bf16 v[98:101], v[190:193], v[206:209], v[98:101]
	v_mfma_f32_16x16x32_bf16 v[86:89], v[170:173], v[214:217], v[86:89]
	v_mfma_f32_16x16x32_bf16 v[82:85], v[190:193], v[214:217], v[82:85]
	v_mfma_f32_16x16x32_bf16 v[70:73], v[170:173], v[238:241], v[70:73]
	v_mfma_f32_16x16x32_bf16 v[66:69], v[190:193], v[238:241], v[66:69]
	s_barrier
	s_setprio 0
	s_add_i32 s56, s82, s9
	v_lshl_add_u64 v[178:179], v[178:179], 0, s[16:17]
	s_mov_b32 m0, s56
	ds_read_b128 v[194:197], v160 offset:49152
	ds_read_b128 v[198:201], v160 offset:50176
	ds_read_b128 v[202:205], v160 offset:51200
	ds_read_b128 v[206:209], v160 offset:52224
	ds_read_b128 v[210:213], v160 offset:53248
	ds_read_b128 v[214:217], v160 offset:54272
	ds_read_b128 v[218:221], v160 offset:55296
	ds_read_b128 v[238:241], v160 offset:56320
	global_load_lds_dwordx4 v[178:179], off
	s_add_i32 m0, s56, 0x2000
	s_add_u32 s54, s54, 0x80080
	v_lshl_add_u64 v[178:179], v[222:223], 0, s[16:17]
	s_addc_u32 s55, s55, 0
	s_add_i32 s56, s83, s9
	global_load_lds_dwordx4 v[178:179], off
	v_lshl_add_u64 v[178:179], s[54:55], 0, v[134:135]
	s_mov_b32 m0, s56
	s_nop 0
	global_load_lds_dwordx4 v[178:179], off
	v_lshl_add_u64 v[178:179], s[54:55], 0, v[138:139]
	s_add_i32 m0, s56, 0x2000
	s_nop 0
	global_load_lds_dwordx4 v[178:179], off
	v_lshl_add_u64 v[178:179], v[242:243], 0, s[16:17]
	s_mov_b32 m0, s64
	s_nop 0
	global_load_lds_dwordx4 v[178:179], off
	v_lshl_add_u64 v[178:179], v[244:245], 0, s[16:17]
	s_mov_b32 m0, s69
	s_nop 0
	global_load_lds_dwordx4 v[178:179], off
	s_waitcnt vmcnt(8)
	s_waitcnt lgkmcnt(0)
	s_setprio 1
	s_barrier
	v_mfma_f32_16x16x32_bf16 v[62:65], v[144:147], v[194:197], v[62:65]
	v_mfma_f32_16x16x32_bf16 v[58:61], v[152:155], v[194:197], v[58:61]
	v_mfma_f32_16x16x32_bf16 v[46:49], v[144:147], v[202:205], v[46:49]
	v_mfma_f32_16x16x32_bf16 v[42:45], v[152:155], v[202:205], v[42:45]
	v_mfma_f32_16x16x32_bf16 v[30:33], v[144:147], v[210:213], v[30:33]
	v_mfma_f32_16x16x32_bf16 v[26:29], v[152:155], v[210:213], v[26:29]
	v_mfma_f32_16x16x32_bf16 v[14:17], v[144:147], v[218:221], v[14:17]
	v_mfma_f32_16x16x32_bf16 v[10:13], v[152:155], v[218:221], v[10:13]
	v_mfma_f32_16x16x32_bf16 v[62:65], v[148:151], v[198:201], v[62:65]
	v_mfma_f32_16x16x32_bf16 v[58:61], v[162:165], v[198:201], v[58:61]
	v_mfma_f32_16x16x32_bf16 v[46:49], v[148:151], v[206:209], v[46:49]
	v_mfma_f32_16x16x32_bf16 v[42:45], v[162:165], v[206:209], v[42:45]
	v_mfma_f32_16x16x32_bf16 v[30:33], v[148:151], v[214:217], v[30:33]
	v_mfma_f32_16x16x32_bf16 v[26:29], v[162:165], v[214:217], v[26:29]
	v_mfma_f32_16x16x32_bf16 v[14:17], v[148:151], v[238:241], v[14:17]
	v_mfma_f32_16x16x32_bf16 v[10:13], v[162:165], v[238:241], v[10:13]
	v_mfma_f32_16x16x32_bf16 v[54:57], v[166:169], v[194:197], v[54:57]
	v_mfma_f32_16x16x32_bf16 v[50:53], v[174:177], v[194:197], v[50:53]
	v_mfma_f32_16x16x32_bf16 v[38:41], v[166:169], v[202:205], v[38:41]
	v_mfma_f32_16x16x32_bf16 v[34:37], v[174:177], v[202:205], v[34:37]
	v_mfma_f32_16x16x32_bf16 v[22:25], v[166:169], v[210:213], v[22:25]
	v_mfma_f32_16x16x32_bf16 v[18:21], v[174:177], v[210:213], v[18:21]
	v_mfma_f32_16x16x32_bf16 v[6:9], v[166:169], v[218:221], v[6:9]
	v_mfma_f32_16x16x32_bf16 v[2:5], v[174:177], v[218:221], v[2:5]
	v_mfma_f32_16x16x32_bf16 v[54:57], v[170:173], v[198:201], v[54:57]
	v_mfma_f32_16x16x32_bf16 v[50:53], v[190:193], v[198:201], v[50:53]
	v_mfma_f32_16x16x32_bf16 v[38:41], v[170:173], v[206:209], v[38:41]
	v_mfma_f32_16x16x32_bf16 v[34:37], v[190:193], v[206:209], v[34:37]
	v_mfma_f32_16x16x32_bf16 v[22:25], v[170:173], v[214:217], v[22:25]
	v_mfma_f32_16x16x32_bf16 v[18:21], v[190:193], v[214:217], v[18:21]
	v_mfma_f32_16x16x32_bf16 v[6:9], v[170:173], v[238:241], v[6:9]
	v_mfma_f32_16x16x32_bf16 v[2:5], v[190:193], v[238:241], v[2:5]
	s_barrier
	s_setprio 0
	s_add_i32 s76, s76, 2
	s_add_u32 s44, s44, 0x100
	s_addc_u32 s45, s45, 0
	s_add_u32 s74, s74, 0x100
	s_addc_u32 s75, s75, 0
	s_cmp_gt_u32 s76, 29
	s_cbranch_scc0 .LBB0_552
	s_and_b64 vcc, exec, s[30:31]
	s_cbranch_vccz .LBB0_555
	s_barrier

.LBB0_824:
	s_add_i32 s64, s40, 2
	s_add_u32 s69, s34, 0x80
	s_addc_u32 s41, s35, 0
	s_add_i32 s74, 0, 0x10000
	s_cmp_eq_u32 s57, s40
	s_cselect_b32 s41, s29, s41
	s_cselect_b32 s40, s28, s69
	v_add_u32_e32 v148, s74, v146
	s_cselect_b32 s71, s31, s63
	s_cselect_b32 s70, s30, s62
	s_add_i32 s69, 0, 0x14000
	ds_read_b128 v[154:157], v148
	ds_read_b128 v[158:161], v148 offset:1024
	ds_read_b128 v[162:165], v148 offset:2048
	ds_read_b128 v[166:169], v148 offset:3072
	v_add_u32_e32 v148, s69, v146
	ds_read_b128 v[170:173], v148
	ds_read_b128 v[174:177], v148 offset:1024
	ds_read_b128 v[190:193], v148 offset:2048
	ds_read_b128 v[194:197], v148 offset:3072
	v_lshl_add_u64 v[148:149], s[34:35], 0, v[140:141]
	s_add_i32 m0, s45, 0xc000
	ds_read_b128 v[198:201], v147
	ds_read_b128 v[202:205], v147 offset:1024
	ds_read_b128 v[206:209], v147 offset:2048
	ds_read_b128 v[210:213], v147 offset:3072
	ds_read_b128 v[214:217], v147 offset:4096
	ds_read_b128 v[218:221], v147 offset:5120
	ds_read_b128 v[238:241], v147 offset:6144
	ds_read_b128 v[242:245], v147 offset:7168
	global_load_lds_dwordx4 v[148:149], off
	v_lshl_add_u64 v[148:149], s[34:35], 0, v[142:143]
	s_add_i32 m0, s45, 0xe000
	s_nop 0
	global_load_lds_dwordx4 v[148:149], off
	s_waitcnt vmcnt(8)
	s_waitcnt lgkmcnt(0)
	s_setprio 1
	s_barrier
	v_mfma_f32_16x16x32_bf16 v[126:129], v[154:157], v[198:201], v[126:129]
	v_mfma_f32_16x16x32_bf16 v[122:125], v[162:165], v[198:201], v[122:125]
	v_mfma_f32_16x16x32_bf16 v[110:113], v[154:157], v[206:209], v[110:113]
	v_mfma_f32_16x16x32_bf16 v[106:109], v[162:165], v[206:209], v[106:109]
	v_mfma_f32_16x16x32_bf16 v[94:97], v[154:157], v[214:217], v[94:97]
	v_mfma_f32_16x16x32_bf16 v[90:93], v[162:165], v[214:217], v[90:93]
	v_mfma_f32_16x16x32_bf16 v[78:81], v[154:157], v[238:241], v[78:81]
	v_mfma_f32_16x16x32_bf16 v[74:77], v[162:165], v[238:241], v[74:77]
	v_mfma_f32_16x16x32_bf16 v[126:129], v[158:161], v[202:205], v[126:129]
	v_mfma_f32_16x16x32_bf16 v[122:125], v[166:169], v[202:205], v[122:125]
	v_mfma_f32_16x16x32_bf16 v[110:113], v[158:161], v[210:213], v[110:113]
	v_mfma_f32_16x16x32_bf16 v[106:109], v[166:169], v[210:213], v[106:109]
	v_mfma_f32_16x16x32_bf16 v[94:97], v[158:161], v[218:221], v[94:97]
	v_mfma_f32_16x16x32_bf16 v[90:93], v[166:169], v[218:221], v[90:93]
	v_mfma_f32_16x16x32_bf16 v[78:81], v[158:161], v[242:245], v[78:81]
	v_mfma_f32_16x16x32_bf16 v[74:77], v[166:169], v[242:245], v[74:77]
	v_mfma_f32_16x16x32_bf16 v[118:121], v[170:173], v[198:201], v[118:121]
	v_mfma_f32_16x16x32_bf16 v[114:117], v[190:193], v[198:201], v[114:117]
	v_mfma_f32_16x16x32_bf16 v[102:105], v[170:173], v[206:209], v[102:105]
	v_mfma_f32_16x16x32_bf16 v[98:101], v[190:193], v[206:209], v[98:101]
	v_mfma_f32_16x16x32_bf16 v[86:89], v[170:173], v[214:217], v[86:89]
	v_mfma_f32_16x16x32_bf16 v[82:85], v[190:193], v[214:217], v[82:85]
	v_mfma_f32_16x16x32_bf16 v[70:73], v[170:173], v[238:241], v[70:73]
	v_mfma_f32_16x16x32_bf16 v[66:69], v[190:193], v[238:241], v[66:69]
	v_mfma_f32_16x16x32_bf16 v[118:121], v[174:177], v[202:205], v[118:121]
	v_mfma_f32_16x16x32_bf16 v[114:117], v[194:197], v[202:205], v[114:117]
	v_mfma_f32_16x16x32_bf16 v[102:105], v[174:177], v[210:213], v[102:105]
	v_mfma_f32_16x16x32_bf16 v[98:101], v[194:197], v[210:213], v[98:101]
	v_mfma_f32_16x16x32_bf16 v[86:89], v[174:177], v[218:221], v[86:89]
	v_mfma_f32_16x16x32_bf16 v[82:85], v[194:197], v[218:221], v[82:85]
	v_mfma_f32_16x16x32_bf16 v[70:73], v[174:177], v[242:245], v[70:73]
	v_mfma_f32_16x16x32_bf16 v[66:69], v[194:197], v[242:245], v[66:69]
	s_barrier
	s_setprio 0
	s_add_i32 s74, s74, s44
	v_lshl_add_u64 v[148:149], s[70:71], 0, v[136:137]
	s_mov_b32 m0, s74
	ds_read_b128 v[198:201], v147 offset:16384
	ds_read_b128 v[202:205], v147 offset:17408
	ds_read_b128 v[206:209], v147 offset:18432
	ds_read_b128 v[210:213], v147 offset:19456
	ds_read_b128 v[214:217], v147 offset:20480
	ds_read_b128 v[218:221], v147 offset:21504
	ds_read_b128 v[238:241], v147 offset:22528
	ds_read_b128 v[242:245], v147 offset:23552
	global_load_lds_dwordx4 v[148:149], off
	s_add_i32 m0, s74, 0x2000
	v_lshl_add_u64 v[178:179], s[70:71], 0, v[132:133]
	s_add_u32 s70, s70, s10
	s_addc_u32 s71, s71, s11
	s_add_i32 s69, s69, s44
	global_load_lds_dwordx4 v[178:179], off
	v_lshl_add_u64 v[222:223], s[70:71], 0, v[136:137]
	s_mov_b32 m0, s69
	v_lshl_add_u64 v[246:247], s[70:71], 0, v[132:133]
	global_load_lds_dwordx4 v[222:223], off
	s_add_i32 m0, s69, 0x2000
	v_lshl_add_u64 v[248:249], s[40:41], 0, v[138:139]
	global_load_lds_dwordx4 v[246:247], off
	s_mov_b32 m0, s45
	v_lshl_add_u64 v[250:251], s[40:41], 0, v[134:135]
	global_load_lds_dwordx4 v[248:249], off
	s_mov_b32 m0, s46
	s_nop 0
	global_load_lds_dwordx4 v[250:251], off
	s_waitcnt vmcnt(8)
	s_waitcnt lgkmcnt(0)
	s_setprio 1
	s_barrier
	v_mfma_f32_16x16x32_bf16 v[62:65], v[154:157], v[198:201], v[62:65]
	v_mfma_f32_16x16x32_bf16 v[58:61], v[162:165], v[198:201], v[58:61]
	v_mfma_f32_16x16x32_bf16 v[46:49], v[154:157], v[206:209], v[46:49]
	v_mfma_f32_16x16x32_bf16 v[42:45], v[162:165], v[206:209], v[42:45]
	v_mfma_f32_16x16x32_bf16 v[30:33], v[154:157], v[214:217], v[30:33]
	v_mfma_f32_16x16x32_bf16 v[26:29], v[162:165], v[214:217], v[26:29]
	v_mfma_f32_16x16x32_bf16 v[14:17], v[154:157], v[238:241], v[14:17]
	v_mfma_f32_16x16x32_bf16 v[10:13], v[162:165], v[238:241], v[10:13]
	v_mfma_f32_16x16x32_bf16 v[62:65], v[158:161], v[202:205], v[62:65]
	v_mfma_f32_16x16x32_bf16 v[58:61], v[166:169], v[202:205], v[58:61]
	v_mfma_f32_16x16x32_bf16 v[46:49], v[158:161], v[210:213], v[46:49]
	v_mfma_f32_16x16x32_bf16 v[42:45], v[166:169], v[210:213], v[42:45]
	v_mfma_f32_16x16x32_bf16 v[30:33], v[158:161], v[218:221], v[30:33]
	v_mfma_f32_16x16x32_bf16 v[26:29], v[166:169], v[218:221], v[26:29]
	v_mfma_f32_16x16x32_bf16 v[14:17], v[158:161], v[242:245], v[14:17]
	v_mfma_f32_16x16x32_bf16 v[10:13], v[166:169], v[242:245], v[10:13]
	v_mfma_f32_16x16x32_bf16 v[54:57], v[170:173], v[198:201], v[54:57]
	v_mfma_f32_16x16x32_bf16 v[50:53], v[190:193], v[198:201], v[50:53]
	v_mfma_f32_16x16x32_bf16 v[38:41], v[170:173], v[206:209], v[38:41]
	v_mfma_f32_16x16x32_bf16 v[34:37], v[190:193], v[206:209], v[34:37]
	v_mfma_f32_16x16x32_bf16 v[22:25], v[170:173], v[214:217], v[22:25]
	v_mfma_f32_16x16x32_bf16 v[18:21], v[190:193], v[214:217], v[18:21]
	v_mfma_f32_16x16x32_bf16 v[6:9], v[170:173], v[238:241], v[6:9]
	v_mfma_f32_16x16x32_bf16 v[2:5], v[190:193], v[238:241], v[2:5]
	v_mfma_f32_16x16x32_bf16 v[54:57], v[174:177], v[202:205], v[54:57]
	v_mfma_f32_16x16x32_bf16 v[50:53], v[194:197], v[202:205], v[50:53]
	v_mfma_f32_16x16x32_bf16 v[38:41], v[174:177], v[210:213], v[38:41]
	v_mfma_f32_16x16x32_bf16 v[34:37], v[194:197], v[210:213], v[34:37]
	v_mfma_f32_16x16x32_bf16 v[22:25], v[174:177], v[218:221], v[22:25]
	v_mfma_f32_16x16x32_bf16 v[18:21], v[194:197], v[218:221], v[18:21]
	v_mfma_f32_16x16x32_bf16 v[6:9], v[174:177], v[242:245], v[6:9]
	v_mfma_f32_16x16x32_bf16 v[2:5], v[194:197], v[242:245], v[2:5]
	s_barrier
	s_setprio 0
	s_add_i32 s69, 0, 0x18000
	v_add_u32_e32 v151, s69, v146
	s_add_i32 s70, 0, 0x1c000
	ds_read_b128 v[154:157], v151
	ds_read_b128 v[158:161], v151 offset:1024
	ds_read_b128 v[162:165], v151 offset:2048
	ds_read_b128 v[166:169], v151 offset:3072
	v_add_u32_e32 v151, s70, v146
	ds_read_b128 v[170:173], v151
	ds_read_b128 v[174:177], v151 offset:1024
	ds_read_b128 v[190:193], v151 offset:2048
	ds_read_b128 v[194:197], v151 offset:3072
	s_add_u32 s40, s40, s10
	s_addc_u32 s41, s41, s11
	s_mov_b32 m0, s47
	v_lshl_add_u64 v[252:253], s[40:41], 0, v[138:139]
	ds_read_b128 v[198:201], v147 offset:32768
	ds_read_b128 v[202:205], v147 offset:33792
	ds_read_b128 v[206:209], v147 offset:34816
	ds_read_b128 v[210:213], v147 offset:35840
	ds_read_b128 v[214:217], v147 offset:36864
	ds_read_b128 v[218:221], v147 offset:37888
	ds_read_b128 v[238:241], v147 offset:38912
	ds_read_b128 v[242:245], v147 offset:39936
	global_load_lds_dwordx4 v[252:253], off
	v_lshl_add_u64 v[252:253], s[40:41], 0, v[134:135]
	s_mov_b32 m0, s48
	s_nop 0
	global_load_lds_dwordx4 v[252:253], off
	s_waitcnt vmcnt(8)
	s_waitcnt lgkmcnt(0)
	s_setprio 1
	s_barrier
	v_mfma_f32_16x16x32_bf16 v[126:129], v[154:157], v[198:201], v[126:129]
	v_mfma_f32_16x16x32_bf16 v[122:125], v[162:165], v[198:201], v[122:125]
	v_mfma_f32_16x16x32_bf16 v[110:113], v[154:157], v[206:209], v[110:113]
	v_mfma_f32_16x16x32_bf16 v[106:109], v[162:165], v[206:209], v[106:109]
	v_mfma_f32_16x16x32_bf16 v[94:97], v[154:157], v[214:217], v[94:97]
	v_mfma_f32_16x16x32_bf16 v[90:93], v[162:165], v[214:217], v[90:93]
	v_mfma_f32_16x16x32_bf16 v[78:81], v[154:157], v[238:241], v[78:81]
	v_mfma_f32_16x16x32_bf16 v[74:77], v[162:165], v[238:241], v[74:77]
	v_mfma_f32_16x16x32_bf16 v[126:129], v[158:161], v[202:205], v[126:129]
	v_mfma_f32_16x16x32_bf16 v[122:125], v[166:169], v[202:205], v[122:125]
	v_mfma_f32_16x16x32_bf16 v[110:113], v[158:161], v[210:213], v[110:113]
	v_mfma_f32_16x16x32_bf16 v[106:109], v[166:169], v[210:213], v[106:109]
	v_mfma_f32_16x16x32_bf16 v[94:97], v[158:161], v[218:221], v[94:97]
	v_mfma_f32_16x16x32_bf16 v[90:93], v[166:169], v[218:221], v[90:93]
	v_mfma_f32_16x16x32_bf16 v[78:81], v[158:161], v[242:245], v[78:81]
	v_mfma_f32_16x16x32_bf16 v[74:77], v[166:169], v[242:245], v[74:77]
	v_mfma_f32_16x16x32_bf16 v[118:121], v[170:173], v[198:201], v[118:121]
	v_mfma_f32_16x16x32_bf16 v[114:117], v[190:193], v[198:201], v[114:117]
	v_mfma_f32_16x16x32_bf16 v[102:105], v[170:173], v[206:209], v[102:105]
	v_mfma_f32_16x16x32_bf16 v[98:101], v[190:193], v[206:209], v[98:101]
	v_mfma_f32_16x16x32_bf16 v[86:89], v[170:173], v[214:217], v[86:89]
	v_mfma_f32_16x16x32_bf16 v[82:85], v[190:193], v[214:217], v[82:85]
	v_mfma_f32_16x16x32_bf16 v[70:73], v[170:173], v[238:241], v[70:73]
	v_mfma_f32_16x16x32_bf16 v[66:69], v[190:193], v[238:241], v[66:69]
	v_mfma_f32_16x16x32_bf16 v[118:121], v[174:177], v[202:205], v[118:121]
	v_mfma_f32_16x16x32_bf16 v[114:117], v[194:197], v[202:205], v[114:117]
	v_mfma_f32_16x16x32_bf16 v[102:105], v[174:177], v[210:213], v[102:105]
	v_mfma_f32_16x16x32_bf16 v[98:101], v[194:197], v[210:213], v[98:101]
	v_mfma_f32_16x16x32_bf16 v[86:89], v[174:177], v[218:221], v[86:89]
	v_mfma_f32_16x16x32_bf16 v[82:85], v[194:197], v[218:221], v[82:85]
	v_mfma_f32_16x16x32_bf16 v[70:73], v[174:177], v[242:245], v[70:73]
	v_mfma_f32_16x16x32_bf16 v[66:69], v[194:197], v[242:245], v[66:69]
	s_barrier
	s_setprio 0
	s_add_i32 s40, s69, s44
	v_lshl_add_u64 v[148:149], v[148:149], 0, s[16:17]
	s_mov_b32 m0, s40
	ds_read_b128 v[198:201], v147 offset:49152
	ds_read_b128 v[202:205], v147 offset:50176
	ds_read_b128 v[206:209], v147 offset:51200
	ds_read_b128 v[210:213], v147 offset:52224
	ds_read_b128 v[214:217], v147 offset:53248
	ds_read_b128 v[218:221], v147 offset:54272
	ds_read_b128 v[238:241], v147 offset:55296
	ds_read_b128 v[242:245], v147 offset:56320
	global_load_lds_dwordx4 v[148:149], off
	v_lshl_add_u64 v[148:149], v[178:179], 0, s[16:17]
	s_add_i32 m0, s40, 0x2000
	s_add_i32 s40, s70, s44
	global_load_lds_dwordx4 v[148:149], off
	v_lshl_add_u64 v[148:149], v[222:223], 0, s[16:17]
	s_mov_b32 m0, s40
	s_nop 0
	global_load_lds_dwordx4 v[148:149], off
	v_lshl_add_u64 v[148:149], v[246:247], 0, s[16:17]
	s_add_i32 m0, s40, 0x2000
	s_nop 0
	global_load_lds_dwordx4 v[148:149], off
	v_lshl_add_u64 v[148:149], v[248:249], 0, s[16:17]
	s_mov_b32 m0, s49
	s_nop 0
	global_load_lds_dwordx4 v[148:149], off
	v_lshl_add_u64 v[148:149], v[250:251], 0, s[16:17]
	s_mov_b32 m0, s50
	s_nop 0
	global_load_lds_dwordx4 v[148:149], off
	s_waitcnt vmcnt(8)
	s_waitcnt lgkmcnt(0)
	s_setprio 1
	s_barrier
	v_mfma_f32_16x16x32_bf16 v[62:65], v[154:157], v[198:201], v[62:65]
	v_mfma_f32_16x16x32_bf16 v[58:61], v[162:165], v[198:201], v[58:61]
	v_mfma_f32_16x16x32_bf16 v[46:49], v[154:157], v[206:209], v[46:49]
	v_mfma_f32_16x16x32_bf16 v[42:45], v[162:165], v[206:209], v[42:45]
	v_mfma_f32_16x16x32_bf16 v[30:33], v[154:157], v[214:217], v[30:33]
	v_mfma_f32_16x16x32_bf16 v[26:29], v[162:165], v[214:217], v[26:29]
	v_mfma_f32_16x16x32_bf16 v[14:17], v[154:157], v[238:241], v[14:17]
	v_mfma_f32_16x16x32_bf16 v[10:13], v[162:165], v[238:241], v[10:13]
	v_mfma_f32_16x16x32_bf16 v[62:65], v[158:161], v[202:205], v[62:65]
	v_mfma_f32_16x16x32_bf16 v[58:61], v[166:169], v[202:205], v[58:61]
	v_mfma_f32_16x16x32_bf16 v[46:49], v[158:161], v[210:213], v[46:49]
	v_mfma_f32_16x16x32_bf16 v[42:45], v[166:169], v[210:213], v[42:45]
	v_mfma_f32_16x16x32_bf16 v[30:33], v[158:161], v[218:221], v[30:33]
	v_mfma_f32_16x16x32_bf16 v[26:29], v[166:169], v[218:221], v[26:29]
	v_mfma_f32_16x16x32_bf16 v[14:17], v[158:161], v[242:245], v[14:17]
	v_mfma_f32_16x16x32_bf16 v[10:13], v[166:169], v[242:245], v[10:13]
	v_mfma_f32_16x16x32_bf16 v[54:57], v[170:173], v[198:201], v[54:57]
	v_mfma_f32_16x16x32_bf16 v[50:53], v[190:193], v[198:201], v[50:53]
	v_mfma_f32_16x16x32_bf16 v[38:41], v[170:173], v[206:209], v[38:41]
	v_mfma_f32_16x16x32_bf16 v[34:37], v[190:193], v[206:209], v[34:37]
	v_mfma_f32_16x16x32_bf16 v[22:25], v[170:173], v[214:217], v[22:25]
	v_mfma_f32_16x16x32_bf16 v[18:21], v[190:193], v[214:217], v[18:21]
	v_mfma_f32_16x16x32_bf16 v[6:9], v[170:173], v[238:241], v[6:9]
	v_mfma_f32_16x16x32_bf16 v[2:5], v[190:193], v[238:241], v[2:5]
	v_mfma_f32_16x16x32_bf16 v[54:57], v[174:177], v[202:205], v[54:57]
	v_mfma_f32_16x16x32_bf16 v[50:53], v[194:197], v[202:205], v[50:53]
	v_mfma_f32_16x16x32_bf16 v[38:41], v[174:177], v[210:213], v[38:41]
	v_mfma_f32_16x16x32_bf16 v[34:37], v[194:197], v[210:213], v[34:37]
	v_mfma_f32_16x16x32_bf16 v[22:25], v[174:177], v[218:221], v[22:25]
	v_mfma_f32_16x16x32_bf16 v[18:21], v[194:197], v[218:221], v[18:21]
	v_mfma_f32_16x16x32_bf16 v[6:9], v[174:177], v[242:245], v[6:9]
	v_mfma_f32_16x16x32_bf16 v[2:5], v[194:197], v[242:245], v[2:5]
	s_barrier
	s_setprio 0
	s_add_u32 s34, s34, 0x100
	s_addc_u32 s35, s35, 0
	s_add_u32 s62, s62, 0x100
	s_addc_u32 s63, s63, 0
	s_cmp_ge_i32 s64, s51
	s_mov_b32 s40, s64
	s_cbranch_scc0 .LBB0_824
	v_readlane_b32 s64, v255, 40
	s_mov_b32 s68, 0xff61b1e6
	s_mov_b32 s74, 0x24600000
	s_mov_b32 s69, 0xcf800000

.LBB0_937:
	s_add_u32 s34, s30, 0x100
	s_addc_u32 s35, s31, 0
	s_add_i32 s61, 0, 0x10000
	s_cmp_eq_u32 s60, 20
	s_cselect_b32 s43, s27, s35
	s_cselect_b32 s42, s26, s34
	s_cselect_b32 s41, s29, s59
	s_cselect_b32 s40, s28, s58
	s_add_i32 s62, 0, 0x14000
	v_add_u32_e32 v156, s61, v150
	v_add_u32_e32 v172, s62, v150
	ds_read_b128 v[140:143], v156
	ds_read_b128 v[144:147], v156 offset:1024
	ds_read_b128 v[152:155], v156 offset:2048
	ds_read_b128 v[156:159], v156 offset:3072
	ds_read_b128 v[160:163], v172
	ds_read_b128 v[164:167], v172 offset:1024
	ds_read_b128 v[168:171], v172 offset:2048
	ds_read_b128 v[172:175], v172 offset:3072
	v_lshl_add_u64 v[218:219], s[30:31], 0, v[136:137]
	s_add_i32 m0, s44, 0xc000
	ds_read_b128 v[176:179], v151
	ds_read_b128 v[190:193], v151 offset:1024
	ds_read_b128 v[194:197], v151 offset:2048
	ds_read_b128 v[198:201], v151 offset:3072
	ds_read_b128 v[202:205], v151 offset:4096
	ds_read_b128 v[206:209], v151 offset:5120
	ds_read_b128 v[210:213], v151 offset:6144
	ds_read_b128 v[214:217], v151 offset:7168
	global_load_lds_dwordx4 v[218:219], off
	v_lshl_add_u64 v[218:219], s[30:31], 0, v[138:139]
	s_add_i32 m0, s44, 0xe000
	s_nop 0
	global_load_lds_dwordx4 v[218:219], off
	s_waitcnt vmcnt(8)
	s_waitcnt lgkmcnt(0)
	s_setprio 1
	s_barrier
	v_mfma_f32_16x16x32_bf16 v[126:129], v[140:143], v[176:179], v[126:129]
	v_mfma_f32_16x16x32_bf16 v[122:125], v[152:155], v[176:179], v[122:125]
	v_mfma_f32_16x16x32_bf16 v[110:113], v[140:143], v[194:197], v[110:113]
	v_mfma_f32_16x16x32_bf16 v[106:109], v[152:155], v[194:197], v[106:109]
	v_mfma_f32_16x16x32_bf16 v[94:97], v[140:143], v[202:205], v[94:97]
	v_mfma_f32_16x16x32_bf16 v[90:93], v[152:155], v[202:205], v[90:93]
	v_mfma_f32_16x16x32_bf16 v[78:81], v[140:143], v[210:213], v[78:81]
	v_mfma_f32_16x16x32_bf16 v[74:77], v[152:155], v[210:213], v[74:77]
	v_mfma_f32_16x16x32_bf16 v[126:129], v[144:147], v[190:193], v[126:129]
	v_mfma_f32_16x16x32_bf16 v[122:125], v[156:159], v[190:193], v[122:125]
	v_mfma_f32_16x16x32_bf16 v[110:113], v[144:147], v[198:201], v[110:113]
	v_mfma_f32_16x16x32_bf16 v[106:109], v[156:159], v[198:201], v[106:109]
	v_mfma_f32_16x16x32_bf16 v[94:97], v[144:147], v[206:209], v[94:97]
	v_mfma_f32_16x16x32_bf16 v[90:93], v[156:159], v[206:209], v[90:93]
	v_mfma_f32_16x16x32_bf16 v[78:81], v[144:147], v[214:217], v[78:81]
	v_mfma_f32_16x16x32_bf16 v[74:77], v[156:159], v[214:217], v[74:77]
	v_mfma_f32_16x16x32_bf16 v[118:121], v[160:163], v[176:179], v[118:121]
	v_mfma_f32_16x16x32_bf16 v[114:117], v[168:171], v[176:179], v[114:117]
	v_mfma_f32_16x16x32_bf16 v[102:105], v[160:163], v[194:197], v[102:105]
	v_mfma_f32_16x16x32_bf16 v[98:101], v[168:171], v[194:197], v[98:101]
	v_mfma_f32_16x16x32_bf16 v[86:89], v[160:163], v[202:205], v[86:89]
	v_mfma_f32_16x16x32_bf16 v[82:85], v[168:171], v[202:205], v[82:85]
	v_mfma_f32_16x16x32_bf16 v[70:73], v[160:163], v[210:213], v[70:73]
	v_mfma_f32_16x16x32_bf16 v[66:69], v[168:171], v[210:213], v[66:69]
	v_mfma_f32_16x16x32_bf16 v[118:121], v[164:167], v[190:193], v[118:121]
	v_mfma_f32_16x16x32_bf16 v[114:117], v[172:175], v[190:193], v[114:117]
	v_mfma_f32_16x16x32_bf16 v[102:105], v[164:167], v[198:201], v[102:105]
	v_mfma_f32_16x16x32_bf16 v[98:101], v[172:175], v[198:201], v[98:101]
	v_mfma_f32_16x16x32_bf16 v[86:89], v[164:167], v[206:209], v[86:89]
	v_mfma_f32_16x16x32_bf16 v[82:85], v[172:175], v[206:209], v[82:85]
	v_mfma_f32_16x16x32_bf16 v[70:73], v[164:167], v[214:217], v[70:73]
	v_mfma_f32_16x16x32_bf16 v[66:69], v[172:175], v[214:217], v[66:69]
	s_barrier
	s_setprio 0
	s_add_i32 s30, s61, s21
	v_lshl_add_u64 v[218:219], s[40:41], 0, v[180:181]
	s_mov_b32 m0, s30
	ds_read_b128 v[176:179], v151 offset:16384
	ds_read_b128 v[190:193], v151 offset:17408
	ds_read_b128 v[194:197], v151 offset:18432
	ds_read_b128 v[198:201], v151 offset:19456
	ds_read_b128 v[202:205], v151 offset:20480
	ds_read_b128 v[206:209], v151 offset:21504
	ds_read_b128 v[210:213], v151 offset:22528
	ds_read_b128 v[214:217], v151 offset:23552
	global_load_lds_dwordx4 v[218:219], off
	s_add_i32 m0, s30, 0x2000
	s_add_u32 s30, s40, 0x60000
	v_lshl_add_u64 v[220:221], s[40:41], 0, v[134:135]
	s_addc_u32 s31, s41, 0
	s_add_i32 s61, s62, s21
	global_load_lds_dwordx4 v[220:221], off
	v_lshl_add_u64 v[222:223], s[30:31], 0, v[180:181]
	s_mov_b32 m0, s61
	v_lshl_add_u64 v[238:239], s[42:43], 0, v[132:133]
	global_load_lds_dwordx4 v[222:223], off
	v_lshl_add_u64 v[222:223], s[30:31], 0, v[134:135]
	s_add_i32 m0, s61, 0x2000
	s_nop 0
	global_load_lds_dwordx4 v[222:223], off
	v_lshl_add_u64 v[222:223], s[42:43], 0, v[130:131]
	s_mov_b32 m0, s44
	s_nop 0
	global_load_lds_dwordx4 v[222:223], off
	s_mov_b32 m0, s45
	s_nop 0
	global_load_lds_dwordx4 v[238:239], off
	s_waitcnt vmcnt(8)
	s_waitcnt lgkmcnt(0)
	s_setprio 1
	s_barrier
	v_mfma_f32_16x16x32_bf16 v[62:65], v[140:143], v[176:179], v[62:65]
	v_mfma_f32_16x16x32_bf16 v[58:61], v[152:155], v[176:179], v[58:61]
	v_mfma_f32_16x16x32_bf16 v[46:49], v[140:143], v[194:197], v[46:49]
	v_mfma_f32_16x16x32_bf16 v[42:45], v[152:155], v[194:197], v[42:45]
	v_mfma_f32_16x16x32_bf16 v[30:33], v[140:143], v[202:205], v[30:33]
	v_mfma_f32_16x16x32_bf16 v[26:29], v[152:155], v[202:205], v[26:29]
	v_mfma_f32_16x16x32_bf16 v[14:17], v[140:143], v[210:213], v[14:17]
	v_mfma_f32_16x16x32_bf16 v[10:13], v[152:155], v[210:213], v[10:13]
	v_mfma_f32_16x16x32_bf16 v[62:65], v[144:147], v[190:193], v[62:65]
	v_mfma_f32_16x16x32_bf16 v[58:61], v[156:159], v[190:193], v[58:61]
	v_mfma_f32_16x16x32_bf16 v[46:49], v[144:147], v[198:201], v[46:49]
	v_mfma_f32_16x16x32_bf16 v[42:45], v[156:159], v[198:201], v[42:45]
	v_mfma_f32_16x16x32_bf16 v[30:33], v[144:147], v[206:209], v[30:33]
	v_mfma_f32_16x16x32_bf16 v[26:29], v[156:159], v[206:209], v[26:29]
	v_mfma_f32_16x16x32_bf16 v[14:17], v[144:147], v[214:217], v[14:17]
	v_mfma_f32_16x16x32_bf16 v[10:13], v[156:159], v[214:217], v[10:13]
	v_mfma_f32_16x16x32_bf16 v[54:57], v[160:163], v[176:179], v[54:57]
	v_mfma_f32_16x16x32_bf16 v[50:53], v[168:171], v[176:179], v[50:53]
	v_mfma_f32_16x16x32_bf16 v[38:41], v[160:163], v[194:197], v[38:41]
	v_mfma_f32_16x16x32_bf16 v[34:37], v[168:171], v[194:197], v[34:37]
	v_mfma_f32_16x16x32_bf16 v[22:25], v[160:163], v[202:205], v[22:25]
	v_mfma_f32_16x16x32_bf16 v[18:21], v[168:171], v[202:205], v[18:21]
	v_mfma_f32_16x16x32_bf16 v[6:9], v[160:163], v[210:213], v[6:9]
	v_mfma_f32_16x16x32_bf16 v[2:5], v[168:171], v[210:213], v[2:5]
	v_mfma_f32_16x16x32_bf16 v[54:57], v[164:167], v[190:193], v[54:57]
	v_mfma_f32_16x16x32_bf16 v[50:53], v[172:175], v[190:193], v[50:53]
	v_mfma_f32_16x16x32_bf16 v[38:41], v[164:167], v[198:201], v[38:41]
	v_mfma_f32_16x16x32_bf16 v[34:37], v[172:175], v[198:201], v[34:37]
	v_mfma_f32_16x16x32_bf16 v[22:25], v[164:167], v[206:209], v[22:25]
	v_mfma_f32_16x16x32_bf16 v[18:21], v[172:175], v[206:209], v[18:21]
	v_mfma_f32_16x16x32_bf16 v[6:9], v[164:167], v[214:217], v[6:9]
	v_mfma_f32_16x16x32_bf16 v[2:5], v[172:175], v[214:217], v[2:5]
	s_barrier
	s_setprio 0
	s_add_i32 s61, 0, 0x18000
	s_add_i32 s62, 0, 0x1c000
	v_add_u32_e32 v156, s61, v150
	v_add_u32_e32 v172, s62, v150
	ds_read_b128 v[140:143], v156
	ds_read_b128 v[144:147], v156 offset:1024
	ds_read_b128 v[152:155], v156 offset:2048
	ds_read_b128 v[156:159], v156 offset:3072
	ds_read_b128 v[160:163], v172
	ds_read_b128 v[164:167], v172 offset:1024
	ds_read_b128 v[168:171], v172 offset:2048
	ds_read_b128 v[172:175], v172 offset:3072
	s_add_u32 s30, s42, 0x60000
	s_addc_u32 s31, s43, 0
	s_mov_b32 m0, s46
	v_lshl_add_u64 v[240:241], s[30:31], 0, v[130:131]
	ds_read_b128 v[176:179], v151 offset:32768
	ds_read_b128 v[190:193], v151 offset:33792
	ds_read_b128 v[194:197], v151 offset:34816
	ds_read_b128 v[198:201], v151 offset:35840
	ds_read_b128 v[202:205], v151 offset:36864
	ds_read_b128 v[206:209], v151 offset:37888
	ds_read_b128 v[210:213], v151 offset:38912
	ds_read_b128 v[214:217], v151 offset:39936
	global_load_lds_dwordx4 v[240:241], off
	v_lshl_add_u64 v[240:241], s[30:31], 0, v[132:133]
	s_mov_b32 m0, s47
	s_nop 0
	global_load_lds_dwordx4 v[240:241], off
	s_waitcnt vmcnt(8)
	s_waitcnt lgkmcnt(0)
	s_setprio 1
	s_barrier
	v_mfma_f32_16x16x32_bf16 v[126:129], v[140:143], v[176:179], v[126:129]
	v_mfma_f32_16x16x32_bf16 v[122:125], v[152:155], v[176:179], v[122:125]
	v_mfma_f32_16x16x32_bf16 v[110:113], v[140:143], v[194:197], v[110:113]
	v_mfma_f32_16x16x32_bf16 v[106:109], v[152:155], v[194:197], v[106:109]
	v_mfma_f32_16x16x32_bf16 v[94:97], v[140:143], v[202:205], v[94:97]
	v_mfma_f32_16x16x32_bf16 v[90:93], v[152:155], v[202:205], v[90:93]
	v_mfma_f32_16x16x32_bf16 v[78:81], v[140:143], v[210:213], v[78:81]
	v_mfma_f32_16x16x32_bf16 v[74:77], v[152:155], v[210:213], v[74:77]
	v_mfma_f32_16x16x32_bf16 v[126:129], v[144:147], v[190:193], v[126:129]
	v_mfma_f32_16x16x32_bf16 v[122:125], v[156:159], v[190:193], v[122:125]
	v_mfma_f32_16x16x32_bf16 v[110:113], v[144:147], v[198:201], v[110:113]
	v_mfma_f32_16x16x32_bf16 v[106:109], v[156:159], v[198:201], v[106:109]
	v_mfma_f32_16x16x32_bf16 v[94:97], v[144:147], v[206:209], v[94:97]
	v_mfma_f32_16x16x32_bf16 v[90:93], v[156:159], v[206:209], v[90:93]
	v_mfma_f32_16x16x32_bf16 v[78:81], v[144:147], v[214:217], v[78:81]
	v_mfma_f32_16x16x32_bf16 v[74:77], v[156:159], v[214:217], v[74:77]
	v_mfma_f32_16x16x32_bf16 v[118:121], v[160:163], v[176:179], v[118:121]
	v_mfma_f32_16x16x32_bf16 v[114:117], v[168:171], v[176:179], v[114:117]
	v_mfma_f32_16x16x32_bf16 v[102:105], v[160:163], v[194:197], v[102:105]
	v_mfma_f32_16x16x32_bf16 v[98:101], v[168:171], v[194:197], v[98:101]
	v_mfma_f32_16x16x32_bf16 v[86:89], v[160:163], v[202:205], v[86:89]
	v_mfma_f32_16x16x32_bf16 v[82:85], v[168:171], v[202:205], v[82:85]
	v_mfma_f32_16x16x32_bf16 v[70:73], v[160:163], v[210:213], v[70:73]
	v_mfma_f32_16x16x32_bf16 v[66:69], v[168:171], v[210:213], v[66:69]
	v_mfma_f32_16x16x32_bf16 v[118:121], v[164:167], v[190:193], v[118:121]
	v_mfma_f32_16x16x32_bf16 v[114:117], v[172:175], v[190:193], v[114:117]
	v_mfma_f32_16x16x32_bf16 v[102:105], v[164:167], v[198:201], v[102:105]
	v_mfma_f32_16x16x32_bf16 v[98:101], v[172:175], v[198:201], v[98:101]
	v_mfma_f32_16x16x32_bf16 v[86:89], v[164:167], v[206:209], v[86:89]
	v_mfma_f32_16x16x32_bf16 v[82:85], v[172:175], v[206:209], v[82:85]
	v_mfma_f32_16x16x32_bf16 v[70:73], v[164:167], v[214:217], v[70:73]
	v_mfma_f32_16x16x32_bf16 v[66:69], v[172:175], v[214:217], v[66:69]
	s_barrier
	s_setprio 0
	s_add_i32 s30, s61, s21
	v_lshl_add_u64 v[218:219], v[218:219], 0, s[16:17]
	s_mov_b32 m0, s30
	ds_read_b128 v[176:179], v151 offset:49152
	ds_read_b128 v[190:193], v151 offset:50176
	ds_read_b128 v[194:197], v151 offset:51200
	ds_read_b128 v[198:201], v151 offset:52224
	ds_read_b128 v[202:205], v151 offset:53248
	ds_read_b128 v[206:209], v151 offset:54272
	ds_read_b128 v[210:213], v151 offset:55296
	ds_read_b128 v[214:217], v151 offset:56320
	global_load_lds_dwordx4 v[218:219], off
	s_add_i32 m0, s30, 0x2000
	s_add_u32 s30, s40, 0x60080
	v_lshl_add_u64 v[218:219], v[220:221], 0, s[16:17]
	s_addc_u32 s31, s41, 0
	s_add_i32 s40, s62, s21
	global_load_lds_dwordx4 v[218:219], off
	v_lshl_add_u64 v[218:219], s[30:31], 0, v[180:181]
	s_mov_b32 m0, s40
	s_nop 0
	global_load_lds_dwordx4 v[218:219], off
	v_lshl_add_u64 v[218:219], s[30:31], 0, v[134:135]
	s_add_i32 m0, s40, 0x2000
	s_nop 0
	global_load_lds_dwordx4 v[218:219], off
	v_lshl_add_u64 v[218:219], v[222:223], 0, s[16:17]
	s_mov_b32 m0, s49
	s_nop 0
	global_load_lds_dwordx4 v[218:219], off
	v_lshl_add_u64 v[218:219], v[238:239], 0, s[16:17]
	s_mov_b32 m0, s50
	s_nop 0
	global_load_lds_dwordx4 v[218:219], off
	s_waitcnt vmcnt(8)
	s_waitcnt lgkmcnt(0)
	s_setprio 1
	s_barrier
	v_mfma_f32_16x16x32_bf16 v[62:65], v[140:143], v[176:179], v[62:65]
	v_mfma_f32_16x16x32_bf16 v[58:61], v[152:155], v[176:179], v[58:61]
	v_mfma_f32_16x16x32_bf16 v[46:49], v[140:143], v[194:197], v[46:49]
	v_mfma_f32_16x16x32_bf16 v[42:45], v[152:155], v[194:197], v[42:45]
	v_mfma_f32_16x16x32_bf16 v[30:33], v[140:143], v[202:205], v[30:33]
	v_mfma_f32_16x16x32_bf16 v[26:29], v[152:155], v[202:205], v[26:29]
	v_mfma_f32_16x16x32_bf16 v[14:17], v[140:143], v[210:213], v[14:17]
	v_mfma_f32_16x16x32_bf16 v[10:13], v[152:155], v[210:213], v[10:13]
	v_mfma_f32_16x16x32_bf16 v[62:65], v[144:147], v[190:193], v[62:65]
	v_mfma_f32_16x16x32_bf16 v[58:61], v[156:159], v[190:193], v[58:61]
	v_mfma_f32_16x16x32_bf16 v[46:49], v[144:147], v[198:201], v[46:49]
	v_mfma_f32_16x16x32_bf16 v[42:45], v[156:159], v[198:201], v[42:45]
	v_mfma_f32_16x16x32_bf16 v[30:33], v[144:147], v[206:209], v[30:33]
	v_mfma_f32_16x16x32_bf16 v[26:29], v[156:159], v[206:209], v[26:29]
	v_mfma_f32_16x16x32_bf16 v[14:17], v[144:147], v[214:217], v[14:17]
	v_mfma_f32_16x16x32_bf16 v[10:13], v[156:159], v[214:217], v[10:13]
	v_mfma_f32_16x16x32_bf16 v[54:57], v[160:163], v[176:179], v[54:57]
	v_mfma_f32_16x16x32_bf16 v[50:53], v[168:171], v[176:179], v[50:53]
	v_mfma_f32_16x16x32_bf16 v[38:41], v[160:163], v[194:197], v[38:41]
	v_mfma_f32_16x16x32_bf16 v[34:37], v[168:171], v[194:197], v[34:37]
	v_mfma_f32_16x16x32_bf16 v[22:25], v[160:163], v[202:205], v[22:25]
	v_mfma_f32_16x16x32_bf16 v[18:21], v[168:171], v[202:205], v[18:21]
	v_mfma_f32_16x16x32_bf16 v[6:9], v[160:163], v[210:213], v[6:9]
	v_mfma_f32_16x16x32_bf16 v[2:5], v[168:171], v[210:213], v[2:5]
	v_mfma_f32_16x16x32_bf16 v[54:57], v[164:167], v[190:193], v[54:57]
	v_mfma_f32_16x16x32_bf16 v[50:53], v[172:175], v[190:193], v[50:53]
	v_mfma_f32_16x16x32_bf16 v[38:41], v[164:167], v[198:201], v[38:41]
	v_mfma_f32_16x16x32_bf16 v[34:37], v[172:175], v[198:201], v[34:37]
	v_mfma_f32_16x16x32_bf16 v[22:25], v[164:167], v[206:209], v[22:25]
	v_mfma_f32_16x16x32_bf16 v[18:21], v[172:175], v[206:209], v[18:21]
	v_mfma_f32_16x16x32_bf16 v[6:9], v[164:167], v[214:217], v[6:9]
	v_mfma_f32_16x16x32_bf16 v[2:5], v[172:175], v[214:217], v[2:5]
	s_barrier
	s_setprio 0
	s_add_i32 s60, s60, 2
	s_add_u32 s58, s58, 0x100
	s_addc_u32 s59, s59, 0
	s_cmp_gt_u32 s60, 21
	s_mov_b64 s[30:31], s[34:35]
	s_cbranch_scc0 .LBB0_937
	s_and_b64 vcc, exec, s[24:25]
	s_cbranch_vccz .LBB0_940
	s_barrier

.LBB0_1018:
	s_add_u32 s40, s38, 0xfff80080
	s_addc_u32 s41, s39, -1
	s_add_i32 s51, 0, 0x10000
	s_cmp_eq_u32 s49, 28
	s_cselect_b32 s43, s11, s41
	s_cselect_b32 s42, s37, s40
	s_cselect_b32 s41, s44, s47
	s_cselect_b32 s40, s45, s46
	s_add_i32 s83, 0, 0x14000
	v_add_u32_e32 v154, s51, v159
	v_add_u32_e32 v161, s83, v159
	ds_read_b128 v[142:145], v154
	ds_read_b128 v[146:149], v154 offset:1024
	ds_read_b128 v[150:153], v154 offset:2048
	ds_read_b128 v[154:157], v154 offset:3072
	ds_read_b128 v[162:165], v161
	ds_read_b128 v[166:169], v161 offset:1024
	ds_read_b128 v[170:173], v161 offset:2048
	ds_read_b128 v[174:177], v161 offset:3072
	v_lshl_add_u64 v[178:179], s[38:39], 0, v[138:139]
	s_add_i32 m0, s61, 0xc000
	ds_read_b128 v[190:193], v160
	ds_read_b128 v[194:197], v160 offset:1024
	ds_read_b128 v[198:201], v160 offset:2048
	ds_read_b128 v[202:205], v160 offset:3072
	ds_read_b128 v[206:209], v160 offset:4096
	ds_read_b128 v[210:213], v160 offset:5120
	ds_read_b128 v[214:217], v160 offset:6144
	ds_read_b128 v[218:221], v160 offset:7168
	global_load_lds_dwordx4 v[178:179], off
	v_lshl_add_u64 v[178:179], s[38:39], 0, v[140:141]
	s_add_i32 m0, s61, 0xe000
	s_nop 0
	global_load_lds_dwordx4 v[178:179], off
	s_waitcnt vmcnt(8)
	s_waitcnt lgkmcnt(0)
	s_setprio 1
	s_barrier
	v_mfma_f32_16x16x32_bf16 v[126:129], v[142:145], v[190:193], v[126:129]
	v_mfma_f32_16x16x32_bf16 v[122:125], v[150:153], v[190:193], v[122:125]
	v_mfma_f32_16x16x32_bf16 v[110:113], v[142:145], v[198:201], v[110:113]
	v_mfma_f32_16x16x32_bf16 v[106:109], v[150:153], v[198:201], v[106:109]
	v_mfma_f32_16x16x32_bf16 v[94:97], v[142:145], v[206:209], v[94:97]
	v_mfma_f32_16x16x32_bf16 v[90:93], v[150:153], v[206:209], v[90:93]
	v_mfma_f32_16x16x32_bf16 v[78:81], v[142:145], v[214:217], v[78:81]
	v_mfma_f32_16x16x32_bf16 v[74:77], v[150:153], v[214:217], v[74:77]
	v_mfma_f32_16x16x32_bf16 v[126:129], v[146:149], v[194:197], v[126:129]
	v_mfma_f32_16x16x32_bf16 v[122:125], v[154:157], v[194:197], v[122:125]
	v_mfma_f32_16x16x32_bf16 v[110:113], v[146:149], v[202:205], v[110:113]
	v_mfma_f32_16x16x32_bf16 v[106:109], v[154:157], v[202:205], v[106:109]
	v_mfma_f32_16x16x32_bf16 v[94:97], v[146:149], v[210:213], v[94:97]
	v_mfma_f32_16x16x32_bf16 v[90:93], v[154:157], v[210:213], v[90:93]
	v_mfma_f32_16x16x32_bf16 v[78:81], v[146:149], v[218:221], v[78:81]
	v_mfma_f32_16x16x32_bf16 v[74:77], v[154:157], v[218:221], v[74:77]
	v_mfma_f32_16x16x32_bf16 v[118:121], v[162:165], v[190:193], v[118:121]
	v_mfma_f32_16x16x32_bf16 v[114:117], v[170:173], v[190:193], v[114:117]
	v_mfma_f32_16x16x32_bf16 v[102:105], v[162:165], v[198:201], v[102:105]
	v_mfma_f32_16x16x32_bf16 v[98:101], v[170:173], v[198:201], v[98:101]
	v_mfma_f32_16x16x32_bf16 v[86:89], v[162:165], v[206:209], v[86:89]
	v_mfma_f32_16x16x32_bf16 v[82:85], v[170:173], v[206:209], v[82:85]
	v_mfma_f32_16x16x32_bf16 v[70:73], v[162:165], v[214:217], v[70:73]
	v_mfma_f32_16x16x32_bf16 v[66:69], v[170:173], v[214:217], v[66:69]
	v_mfma_f32_16x16x32_bf16 v[118:121], v[166:169], v[194:197], v[118:121]
	v_mfma_f32_16x16x32_bf16 v[114:117], v[174:177], v[194:197], v[114:117]
	v_mfma_f32_16x16x32_bf16 v[102:105], v[166:169], v[202:205], v[102:105]
	v_mfma_f32_16x16x32_bf16 v[98:101], v[174:177], v[202:205], v[98:101]
	v_mfma_f32_16x16x32_bf16 v[86:89], v[166:169], v[210:213], v[86:89]
	v_mfma_f32_16x16x32_bf16 v[82:85], v[174:177], v[210:213], v[82:85]
	v_mfma_f32_16x16x32_bf16 v[70:73], v[166:169], v[218:221], v[70:73]
	v_mfma_f32_16x16x32_bf16 v[66:69], v[174:177], v[218:221], v[66:69]
	s_barrier
	s_setprio 0
	s_add_i32 s51, s51, s60
	v_lshl_add_u64 v[178:179], s[40:41], 0, v[180:181]
	s_mov_b32 m0, s51
	ds_read_b128 v[190:193], v160 offset:16384
	ds_read_b128 v[194:197], v160 offset:17408
	ds_read_b128 v[198:201], v160 offset:18432
	ds_read_b128 v[202:205], v160 offset:19456
	ds_read_b128 v[206:209], v160 offset:20480
	ds_read_b128 v[210:213], v160 offset:21504
	ds_read_b128 v[214:217], v160 offset:22528
	ds_read_b128 v[218:221], v160 offset:23552
	global_load_lds_dwordx4 v[178:179], off
	s_add_i32 m0, s51, 0x2000
	s_add_u32 vcc_lo, s40, 0x80000
	v_lshl_add_u64 v[222:223], s[40:41], 0, v[136:137]
	s_addc_u32 vcc_hi, s41, 0
	s_add_i32 s51, s83, s60
	global_load_lds_dwordx4 v[222:223], off
	v_lshl_add_u64 v[238:239], vcc, 0, v[180:181]
	s_mov_b32 m0, s51
	v_lshl_add_u64 v[240:241], s[42:43], 0, v[134:135]
	global_load_lds_dwordx4 v[238:239], off
	v_lshl_add_u64 v[238:239], vcc, 0, v[136:137]
	s_add_i32 m0, s51, 0x2000
	s_nop 0
	global_load_lds_dwordx4 v[238:239], off
	v_lshl_add_u64 v[238:239], s[42:43], 0, v[132:133]
	s_mov_b32 m0, s61
	s_nop 0
	global_load_lds_dwordx4 v[238:239], off
	s_mov_b32 m0, s62
	s_nop 0
	global_load_lds_dwordx4 v[240:241], off
	s_waitcnt vmcnt(8)
	s_waitcnt lgkmcnt(0)
	s_setprio 1
	s_barrier
	v_mfma_f32_16x16x32_bf16 v[62:65], v[142:145], v[190:193], v[62:65]
	v_mfma_f32_16x16x32_bf16 v[58:61], v[150:153], v[190:193], v[58:61]
	v_mfma_f32_16x16x32_bf16 v[46:49], v[142:145], v[198:201], v[46:49]
	v_mfma_f32_16x16x32_bf16 v[42:45], v[150:153], v[198:201], v[42:45]
	v_mfma_f32_16x16x32_bf16 v[30:33], v[142:145], v[206:209], v[30:33]
	v_mfma_f32_16x16x32_bf16 v[26:29], v[150:153], v[206:209], v[26:29]
	v_mfma_f32_16x16x32_bf16 v[14:17], v[142:145], v[214:217], v[14:17]
	v_mfma_f32_16x16x32_bf16 v[10:13], v[150:153], v[214:217], v[10:13]
	v_mfma_f32_16x16x32_bf16 v[62:65], v[146:149], v[194:197], v[62:65]
	v_mfma_f32_16x16x32_bf16 v[58:61], v[154:157], v[194:197], v[58:61]
	v_mfma_f32_16x16x32_bf16 v[46:49], v[146:149], v[202:205], v[46:49]
	v_mfma_f32_16x16x32_bf16 v[42:45], v[154:157], v[202:205], v[42:45]
	v_mfma_f32_16x16x32_bf16 v[30:33], v[146:149], v[210:213], v[30:33]
	v_mfma_f32_16x16x32_bf16 v[26:29], v[154:157], v[210:213], v[26:29]
	v_mfma_f32_16x16x32_bf16 v[14:17], v[146:149], v[218:221], v[14:17]
	v_mfma_f32_16x16x32_bf16 v[10:13], v[154:157], v[218:221], v[10:13]
	v_mfma_f32_16x16x32_bf16 v[54:57], v[162:165], v[190:193], v[54:57]
	v_mfma_f32_16x16x32_bf16 v[50:53], v[170:173], v[190:193], v[50:53]
	v_mfma_f32_16x16x32_bf16 v[38:41], v[162:165], v[198:201], v[38:41]
	v_mfma_f32_16x16x32_bf16 v[34:37], v[170:173], v[198:201], v[34:37]
	v_mfma_f32_16x16x32_bf16 v[22:25], v[162:165], v[206:209], v[22:25]
	v_mfma_f32_16x16x32_bf16 v[18:21], v[170:173], v[206:209], v[18:21]
	v_mfma_f32_16x16x32_bf16 v[6:9], v[162:165], v[214:217], v[6:9]
	v_mfma_f32_16x16x32_bf16 v[2:5], v[170:173], v[214:217], v[2:5]
	v_mfma_f32_16x16x32_bf16 v[54:57], v[166:169], v[194:197], v[54:57]
	v_mfma_f32_16x16x32_bf16 v[50:53], v[174:177], v[194:197], v[50:53]
	v_mfma_f32_16x16x32_bf16 v[38:41], v[166:169], v[202:205], v[38:41]
	v_mfma_f32_16x16x32_bf16 v[34:37], v[174:177], v[202:205], v[34:37]
	v_mfma_f32_16x16x32_bf16 v[22:25], v[166:169], v[210:213], v[22:25]
	v_mfma_f32_16x16x32_bf16 v[18:21], v[174:177], v[210:213], v[18:21]
	v_mfma_f32_16x16x32_bf16 v[6:9], v[166:169], v[218:221], v[6:9]
	v_mfma_f32_16x16x32_bf16 v[2:5], v[174:177], v[218:221], v[2:5]
	s_barrier
	s_setprio 0
	s_add_i32 s51, 0, 0x18000
	s_add_i32 s83, 0, 0x1c000
	v_add_u32_e32 v154, s51, v159
	v_add_u32_e32 v161, s83, v159
	ds_read_b128 v[142:145], v154
	ds_read_b128 v[146:149], v154 offset:1024
	ds_read_b128 v[150:153], v154 offset:2048
	ds_read_b128 v[154:157], v154 offset:3072
	ds_read_b128 v[162:165], v161
	ds_read_b128 v[166:169], v161 offset:1024
	ds_read_b128 v[170:173], v161 offset:2048
	ds_read_b128 v[174:177], v161 offset:3072
	s_add_u32 s42, s42, 0x80000
	s_addc_u32 s43, s43, 0
	s_mov_b32 m0, s63
	v_lshl_add_u64 v[242:243], s[42:43], 0, v[132:133]
	ds_read_b128 v[190:193], v160 offset:32768
	ds_read_b128 v[194:197], v160 offset:33792
	ds_read_b128 v[198:201], v160 offset:34816
	ds_read_b128 v[202:205], v160 offset:35840
	ds_read_b128 v[206:209], v160 offset:36864
	ds_read_b128 v[210:213], v160 offset:37888
	ds_read_b128 v[214:217], v160 offset:38912
	ds_read_b128 v[218:221], v160 offset:39936
	global_load_lds_dwordx4 v[242:243], off
	v_lshl_add_u64 v[242:243], s[42:43], 0, v[134:135]
	s_mov_b32 m0, s64
	s_nop 0
	global_load_lds_dwordx4 v[242:243], off
	s_waitcnt vmcnt(8)
	s_waitcnt lgkmcnt(0)
	s_setprio 1
	s_barrier
	v_mfma_f32_16x16x32_bf16 v[126:129], v[142:145], v[190:193], v[126:129]
	v_mfma_f32_16x16x32_bf16 v[122:125], v[150:153], v[190:193], v[122:125]
	v_mfma_f32_16x16x32_bf16 v[110:113], v[142:145], v[198:201], v[110:113]
	v_mfma_f32_16x16x32_bf16 v[106:109], v[150:153], v[198:201], v[106:109]
	v_mfma_f32_16x16x32_bf16 v[94:97], v[142:145], v[206:209], v[94:97]
	v_mfma_f32_16x16x32_bf16 v[90:93], v[150:153], v[206:209], v[90:93]
	v_mfma_f32_16x16x32_bf16 v[78:81], v[142:145], v[214:217], v[78:81]
	v_mfma_f32_16x16x32_bf16 v[74:77], v[150:153], v[214:217], v[74:77]
	v_mfma_f32_16x16x32_bf16 v[126:129], v[146:149], v[194:197], v[126:129]
	v_mfma_f32_16x16x32_bf16 v[122:125], v[154:157], v[194:197], v[122:125]
	v_mfma_f32_16x16x32_bf16 v[110:113], v[146:149], v[202:205], v[110:113]
	v_mfma_f32_16x16x32_bf16 v[106:109], v[154:157], v[202:205], v[106:109]
	v_mfma_f32_16x16x32_bf16 v[94:97], v[146:149], v[210:213], v[94:97]
	v_mfma_f32_16x16x32_bf16 v[90:93], v[154:157], v[210:213], v[90:93]
	v_mfma_f32_16x16x32_bf16 v[78:81], v[146:149], v[218:221], v[78:81]
	v_mfma_f32_16x16x32_bf16 v[74:77], v[154:157], v[218:221], v[74:77]
	v_mfma_f32_16x16x32_bf16 v[118:121], v[162:165], v[190:193], v[118:121]
	v_mfma_f32_16x16x32_bf16 v[114:117], v[170:173], v[190:193], v[114:117]
	v_mfma_f32_16x16x32_bf16 v[102:105], v[162:165], v[198:201], v[102:105]
	v_mfma_f32_16x16x32_bf16 v[98:101], v[170:173], v[198:201], v[98:101]
	v_mfma_f32_16x16x32_bf16 v[86:89], v[162:165], v[206:209], v[86:89]
	v_mfma_f32_16x16x32_bf16 v[82:85], v[170:173], v[206:209], v[82:85]
	v_mfma_f32_16x16x32_bf16 v[70:73], v[162:165], v[214:217], v[70:73]
	v_mfma_f32_16x16x32_bf16 v[66:69], v[170:173], v[214:217], v[66:69]
	v_mfma_f32_16x16x32_bf16 v[118:121], v[166:169], v[194:197], v[118:121]
	v_mfma_f32_16x16x32_bf16 v[114:117], v[174:177], v[194:197], v[114:117]
	v_mfma_f32_16x16x32_bf16 v[102:105], v[166:169], v[202:205], v[102:105]
	v_mfma_f32_16x16x32_bf16 v[98:101], v[174:177], v[202:205], v[98:101]
	v_mfma_f32_16x16x32_bf16 v[86:89], v[166:169], v[210:213], v[86:89]
	v_mfma_f32_16x16x32_bf16 v[82:85], v[174:177], v[210:213], v[82:85]
	v_mfma_f32_16x16x32_bf16 v[70:73], v[166:169], v[218:221], v[70:73]
	v_mfma_f32_16x16x32_bf16 v[66:69], v[174:177], v[218:221], v[66:69]
	s_barrier
	s_setprio 0
	s_add_i32 s42, s51, s60
	v_lshl_add_u64 v[178:179], v[178:179], 0, s[16:17]
	s_mov_b32 m0, s42
	ds_read_b128 v[190:193], v160 offset:49152
	ds_read_b128 v[194:197], v160 offset:50176
	ds_read_b128 v[198:201], v160 offset:51200
	ds_read_b128 v[202:205], v160 offset:52224
	ds_read_b128 v[206:209], v160 offset:53248
	ds_read_b128 v[210:213], v160 offset:54272
	ds_read_b128 v[214:217], v160 offset:55296
	ds_read_b128 v[218:221], v160 offset:56320
	global_load_lds_dwordx4 v[178:179], off
	s_add_i32 m0, s42, 0x2000
	s_add_u32 s40, s40, 0x80080
	v_lshl_add_u64 v[178:179], v[222:223], 0, s[16:17]
	s_addc_u32 s41, s41, 0
	s_add_i32 s42, s83, s60
	global_load_lds_dwordx4 v[178:179], off
	v_lshl_add_u64 v[178:179], s[40:41], 0, v[180:181]
	s_mov_b32 m0, s42
	s_nop 0
	global_load_lds_dwordx4 v[178:179], off
	v_lshl_add_u64 v[178:179], s[40:41], 0, v[136:137]
	s_add_i32 m0, s42, 0x2000
	s_nop 0
	global_load_lds_dwordx4 v[178:179], off
	v_lshl_add_u64 v[178:179], v[238:239], 0, s[16:17]
	s_mov_b32 m0, s74
	s_nop 0
	global_load_lds_dwordx4 v[178:179], off
	v_lshl_add_u64 v[178:179], v[240:241], 0, s[16:17]
	s_mov_b32 m0, s75
	s_nop 0
	global_load_lds_dwordx4 v[178:179], off
	s_waitcnt vmcnt(8)
	s_waitcnt lgkmcnt(0)
	s_setprio 1
	s_barrier
	v_mfma_f32_16x16x32_bf16 v[62:65], v[142:145], v[190:193], v[62:65]
	v_mfma_f32_16x16x32_bf16 v[58:61], v[150:153], v[190:193], v[58:61]
	v_mfma_f32_16x16x32_bf16 v[46:49], v[142:145], v[198:201], v[46:49]
	v_mfma_f32_16x16x32_bf16 v[42:45], v[150:153], v[198:201], v[42:45]
	v_mfma_f32_16x16x32_bf16 v[30:33], v[142:145], v[206:209], v[30:33]
	v_mfma_f32_16x16x32_bf16 v[26:29], v[150:153], v[206:209], v[26:29]
	v_mfma_f32_16x16x32_bf16 v[14:17], v[142:145], v[214:217], v[14:17]
	v_mfma_f32_16x16x32_bf16 v[10:13], v[150:153], v[214:217], v[10:13]
	v_mfma_f32_16x16x32_bf16 v[62:65], v[146:149], v[194:197], v[62:65]
	v_mfma_f32_16x16x32_bf16 v[58:61], v[154:157], v[194:197], v[58:61]
	v_mfma_f32_16x16x32_bf16 v[46:49], v[146:149], v[202:205], v[46:49]
	v_mfma_f32_16x16x32_bf16 v[42:45], v[154:157], v[202:205], v[42:45]
	v_mfma_f32_16x16x32_bf16 v[30:33], v[146:149], v[210:213], v[30:33]
	v_mfma_f32_16x16x32_bf16 v[26:29], v[154:157], v[210:213], v[26:29]
	v_mfma_f32_16x16x32_bf16 v[14:17], v[146:149], v[218:221], v[14:17]
	v_mfma_f32_16x16x32_bf16 v[10:13], v[154:157], v[218:221], v[10:13]
	v_mfma_f32_16x16x32_bf16 v[54:57], v[162:165], v[190:193], v[54:57]
	v_mfma_f32_16x16x32_bf16 v[50:53], v[170:173], v[190:193], v[50:53]
	v_mfma_f32_16x16x32_bf16 v[38:41], v[162:165], v[198:201], v[38:41]
	v_mfma_f32_16x16x32_bf16 v[34:37], v[170:173], v[198:201], v[34:37]
	v_mfma_f32_16x16x32_bf16 v[22:25], v[162:165], v[206:209], v[22:25]
	v_mfma_f32_16x16x32_bf16 v[18:21], v[170:173], v[206:209], v[18:21]
	v_mfma_f32_16x16x32_bf16 v[6:9], v[162:165], v[214:217], v[6:9]
	v_mfma_f32_16x16x32_bf16 v[2:5], v[170:173], v[214:217], v[2:5]
	v_mfma_f32_16x16x32_bf16 v[54:57], v[166:169], v[194:197], v[54:57]
	v_mfma_f32_16x16x32_bf16 v[50:53], v[174:177], v[194:197], v[50:53]
	v_mfma_f32_16x16x32_bf16 v[38:41], v[166:169], v[202:205], v[38:41]
	v_mfma_f32_16x16x32_bf16 v[34:37], v[174:177], v[202:205], v[34:37]
	v_mfma_f32_16x16x32_bf16 v[22:25], v[166:169], v[210:213], v[22:25]
	v_mfma_f32_16x16x32_bf16 v[18:21], v[174:177], v[210:213], v[18:21]
	v_mfma_f32_16x16x32_bf16 v[6:9], v[166:169], v[218:221], v[6:9]
	v_mfma_f32_16x16x32_bf16 v[2:5], v[174:177], v[218:221], v[2:5]
	s_barrier
	s_setprio 0
	s_add_i32 s49, s49, 2
	s_add_u32 s38, s38, 0x100
	s_addc_u32 s39, s39, 0
	s_add_u32 s46, s46, 0x100
	s_addc_u32 s47, s47, 0
	s_cmp_gt_u32 s49, 29
	s_cbranch_scc0 .LBB0_1018
	s_and_b64 vcc, exec, s[34:35]
	s_cbranch_vccz .LBB0_1021
	s_barrier

.LBB0_1230:
	s_add_u32 s38, s36, 0xfff80080
	s_addc_u32 s39, s37, -1
	s_add_i32 s64, 0, 0x10000
	s_cmp_eq_u32 s63, 28
	s_cselect_b32 s41, s57, s39
	s_cselect_b32 s40, s58, s38
	v_add_u32_e32 v155, s64, v153
	s_cselect_b32 s39, s59, s62
	s_cselect_b32 s38, s60, s61
	s_add_i32 s74, 0, 0x14000
	ds_read_b128 v[140:143], v155
	ds_read_b128 v[144:147], v155 offset:1024
	ds_read_b128 v[148:151], v155 offset:2048
	ds_read_b128 v[156:159], v155 offset:3072
	v_add_u32_e32 v155, s74, v153
	ds_read_b128 v[160:163], v155
	ds_read_b128 v[164:167], v155 offset:1024
	ds_read_b128 v[168:171], v155 offset:2048
	ds_read_b128 v[172:175], v155 offset:3072
	v_lshl_add_u64 v[218:219], s[36:37], 0, v[136:137]
	s_add_i32 m0, s11, 0xc000
	ds_read_b128 v[176:179], v154
	ds_read_b128 v[190:193], v154 offset:1024
	ds_read_b128 v[194:197], v154 offset:2048
	ds_read_b128 v[198:201], v154 offset:3072
	ds_read_b128 v[202:205], v154 offset:4096
	ds_read_b128 v[206:209], v154 offset:5120
	ds_read_b128 v[210:213], v154 offset:6144
	ds_read_b128 v[214:217], v154 offset:7168
	global_load_lds_dwordx4 v[218:219], off
	v_lshl_add_u64 v[218:219], s[36:37], 0, v[138:139]
	s_add_i32 m0, s11, 0xe000
	s_nop 0
	global_load_lds_dwordx4 v[218:219], off
	s_waitcnt vmcnt(8)
	s_waitcnt lgkmcnt(0)
	s_setprio 1
	s_barrier
	v_mfma_f32_16x16x32_bf16 v[126:129], v[140:143], v[176:179], v[126:129]
	v_mfma_f32_16x16x32_bf16 v[122:125], v[148:151], v[176:179], v[122:125]
	v_mfma_f32_16x16x32_bf16 v[110:113], v[140:143], v[194:197], v[110:113]
	v_mfma_f32_16x16x32_bf16 v[106:109], v[148:151], v[194:197], v[106:109]
	v_mfma_f32_16x16x32_bf16 v[94:97], v[140:143], v[202:205], v[94:97]
	v_mfma_f32_16x16x32_bf16 v[90:93], v[148:151], v[202:205], v[90:93]
	v_mfma_f32_16x16x32_bf16 v[78:81], v[140:143], v[210:213], v[78:81]
	v_mfma_f32_16x16x32_bf16 v[74:77], v[148:151], v[210:213], v[74:77]
	v_mfma_f32_16x16x32_bf16 v[126:129], v[144:147], v[190:193], v[126:129]
	v_mfma_f32_16x16x32_bf16 v[122:125], v[156:159], v[190:193], v[122:125]
	v_mfma_f32_16x16x32_bf16 v[110:113], v[144:147], v[198:201], v[110:113]
	v_mfma_f32_16x16x32_bf16 v[106:109], v[156:159], v[198:201], v[106:109]
	v_mfma_f32_16x16x32_bf16 v[94:97], v[144:147], v[206:209], v[94:97]
	v_mfma_f32_16x16x32_bf16 v[90:93], v[156:159], v[206:209], v[90:93]
	v_mfma_f32_16x16x32_bf16 v[78:81], v[144:147], v[214:217], v[78:81]
	v_mfma_f32_16x16x32_bf16 v[74:77], v[156:159], v[214:217], v[74:77]
	v_mfma_f32_16x16x32_bf16 v[118:121], v[160:163], v[176:179], v[118:121]
	v_mfma_f32_16x16x32_bf16 v[114:117], v[168:171], v[176:179], v[114:117]
	v_mfma_f32_16x16x32_bf16 v[102:105], v[160:163], v[194:197], v[102:105]
	v_mfma_f32_16x16x32_bf16 v[98:101], v[168:171], v[194:197], v[98:101]
	v_mfma_f32_16x16x32_bf16 v[86:89], v[160:163], v[202:205], v[86:89]
	v_mfma_f32_16x16x32_bf16 v[82:85], v[168:171], v[202:205], v[82:85]
	v_mfma_f32_16x16x32_bf16 v[70:73], v[160:163], v[210:213], v[70:73]
	v_mfma_f32_16x16x32_bf16 v[66:69], v[168:171], v[210:213], v[66:69]
	v_mfma_f32_16x16x32_bf16 v[118:121], v[164:167], v[190:193], v[118:121]
	v_mfma_f32_16x16x32_bf16 v[114:117], v[172:175], v[190:193], v[114:117]
	v_mfma_f32_16x16x32_bf16 v[102:105], v[164:167], v[198:201], v[102:105]
	v_mfma_f32_16x16x32_bf16 v[98:101], v[172:175], v[198:201], v[98:101]
	v_mfma_f32_16x16x32_bf16 v[86:89], v[164:167], v[206:209], v[86:89]
	v_mfma_f32_16x16x32_bf16 v[82:85], v[172:175], v[206:209], v[82:85]
	v_mfma_f32_16x16x32_bf16 v[70:73], v[164:167], v[214:217], v[70:73]
	v_mfma_f32_16x16x32_bf16 v[66:69], v[172:175], v[214:217], v[66:69]
	s_barrier
	s_setprio 0
	s_add_i32 s64, s64, s43
	v_lshl_add_u64 v[218:219], s[38:39], 0, v[134:135]
	s_mov_b32 m0, s64
	ds_read_b128 v[176:179], v154 offset:16384
	ds_read_b128 v[190:193], v154 offset:17408
	ds_read_b128 v[194:197], v154 offset:18432
	ds_read_b128 v[198:201], v154 offset:19456
	ds_read_b128 v[202:205], v154 offset:20480
	ds_read_b128 v[206:209], v154 offset:21504
	ds_read_b128 v[210:213], v154 offset:22528
	ds_read_b128 v[214:217], v154 offset:23552
	global_load_lds_dwordx4 v[218:219], off
	s_add_i32 m0, s64, 0x2000
	s_add_u32 s70, s38, 0x80000
	v_lshl_add_u64 v[220:221], s[38:39], 0, v[132:133]
	s_addc_u32 s71, s39, 0
	s_add_i32 s64, s74, s43
	global_load_lds_dwordx4 v[220:221], off
	v_lshl_add_u64 v[222:223], s[70:71], 0, v[134:135]
	s_mov_b32 m0, s64
	v_lshl_add_u64 v[238:239], s[40:41], 0, v[132:133]
	global_load_lds_dwordx4 v[222:223], off
	v_lshl_add_u64 v[222:223], s[70:71], 0, v[132:133]
	s_add_i32 m0, s64, 0x2000
	s_nop 0
	global_load_lds_dwordx4 v[222:223], off
	v_lshl_add_u64 v[222:223], s[40:41], 0, v[134:135]
	s_mov_b32 m0, s11
	s_nop 0
	global_load_lds_dwordx4 v[222:223], off
	s_mov_b32 m0, s45
	s_nop 0
	global_load_lds_dwordx4 v[238:239], off
	s_waitcnt vmcnt(8)
	s_waitcnt lgkmcnt(0)
	s_setprio 1
	s_barrier
	v_mfma_f32_16x16x32_bf16 v[62:65], v[140:143], v[176:179], v[62:65]
	v_mfma_f32_16x16x32_bf16 v[58:61], v[148:151], v[176:179], v[58:61]
	v_mfma_f32_16x16x32_bf16 v[46:49], v[140:143], v[194:197], v[46:49]
	v_mfma_f32_16x16x32_bf16 v[42:45], v[148:151], v[194:197], v[42:45]
	v_mfma_f32_16x16x32_bf16 v[30:33], v[140:143], v[202:205], v[30:33]
	v_mfma_f32_16x16x32_bf16 v[26:29], v[148:151], v[202:205], v[26:29]
	v_mfma_f32_16x16x32_bf16 v[14:17], v[140:143], v[210:213], v[14:17]
	v_mfma_f32_16x16x32_bf16 v[10:13], v[148:151], v[210:213], v[10:13]
	v_mfma_f32_16x16x32_bf16 v[62:65], v[144:147], v[190:193], v[62:65]
	v_mfma_f32_16x16x32_bf16 v[58:61], v[156:159], v[190:193], v[58:61]
	v_mfma_f32_16x16x32_bf16 v[46:49], v[144:147], v[198:201], v[46:49]
	v_mfma_f32_16x16x32_bf16 v[42:45], v[156:159], v[198:201], v[42:45]
	v_mfma_f32_16x16x32_bf16 v[30:33], v[144:147], v[206:209], v[30:33]
	v_mfma_f32_16x16x32_bf16 v[26:29], v[156:159], v[206:209], v[26:29]
	v_mfma_f32_16x16x32_bf16 v[14:17], v[144:147], v[214:217], v[14:17]
	v_mfma_f32_16x16x32_bf16 v[10:13], v[156:159], v[214:217], v[10:13]
	v_mfma_f32_16x16x32_bf16 v[54:57], v[160:163], v[176:179], v[54:57]
	v_mfma_f32_16x16x32_bf16 v[50:53], v[168:171], v[176:179], v[50:53]
	v_mfma_f32_16x16x32_bf16 v[38:41], v[160:163], v[194:197], v[38:41]
	v_mfma_f32_16x16x32_bf16 v[34:37], v[168:171], v[194:197], v[34:37]
	v_mfma_f32_16x16x32_bf16 v[22:25], v[160:163], v[202:205], v[22:25]
	v_mfma_f32_16x16x32_bf16 v[18:21], v[168:171], v[202:205], v[18:21]
	v_mfma_f32_16x16x32_bf16 v[6:9], v[160:163], v[210:213], v[6:9]
	v_mfma_f32_16x16x32_bf16 v[2:5], v[168:171], v[210:213], v[2:5]
	v_mfma_f32_16x16x32_bf16 v[54:57], v[164:167], v[190:193], v[54:57]
	v_mfma_f32_16x16x32_bf16 v[50:53], v[172:175], v[190:193], v[50:53]
	v_mfma_f32_16x16x32_bf16 v[38:41], v[164:167], v[198:201], v[38:41]
	v_mfma_f32_16x16x32_bf16 v[34:37], v[172:175], v[198:201], v[34:37]
	v_mfma_f32_16x16x32_bf16 v[22:25], v[164:167], v[206:209], v[22:25]
	v_mfma_f32_16x16x32_bf16 v[18:21], v[172:175], v[206:209], v[18:21]
	v_mfma_f32_16x16x32_bf16 v[6:9], v[164:167], v[214:217], v[6:9]
	v_mfma_f32_16x16x32_bf16 v[2:5], v[172:175], v[214:217], v[2:5]
	s_barrier
	s_setprio 0
	s_add_i32 s64, 0, 0x18000
	v_add_u32_e32 v155, s64, v153
	s_add_i32 s70, 0, 0x1c000
	ds_read_b128 v[140:143], v155
	ds_read_b128 v[144:147], v155 offset:1024
	ds_read_b128 v[148:151], v155 offset:2048
	ds_read_b128 v[156:159], v155 offset:3072
	v_add_u32_e32 v155, s70, v153
	ds_read_b128 v[160:163], v155
	ds_read_b128 v[164:167], v155 offset:1024
	ds_read_b128 v[168:171], v155 offset:2048
	ds_read_b128 v[172:175], v155 offset:3072
	s_add_u32 s40, s40, 0x80000
	s_addc_u32 s41, s41, 0
	s_mov_b32 m0, s46
	v_lshl_add_u64 v[240:241], s[40:41], 0, v[134:135]
	ds_read_b128 v[176:179], v154 offset:32768
	ds_read_b128 v[190:193], v154 offset:33792
	ds_read_b128 v[194:197], v154 offset:34816
	ds_read_b128 v[198:201], v154 offset:35840
	ds_read_b128 v[202:205], v154 offset:36864
	ds_read_b128 v[206:209], v154 offset:37888
	ds_read_b128 v[210:213], v154 offset:38912
	ds_read_b128 v[214:217], v154 offset:39936
	global_load_lds_dwordx4 v[240:241], off
	v_lshl_add_u64 v[240:241], s[40:41], 0, v[132:133]
	s_mov_b32 m0, s47
	s_nop 0
	global_load_lds_dwordx4 v[240:241], off
	s_waitcnt vmcnt(8)
	s_waitcnt lgkmcnt(0)
	s_setprio 1
	s_barrier
	v_mfma_f32_16x16x32_bf16 v[126:129], v[140:143], v[176:179], v[126:129]
	v_mfma_f32_16x16x32_bf16 v[122:125], v[148:151], v[176:179], v[122:125]
	v_mfma_f32_16x16x32_bf16 v[110:113], v[140:143], v[194:197], v[110:113]
	v_mfma_f32_16x16x32_bf16 v[106:109], v[148:151], v[194:197], v[106:109]
	v_mfma_f32_16x16x32_bf16 v[94:97], v[140:143], v[202:205], v[94:97]
	v_mfma_f32_16x16x32_bf16 v[90:93], v[148:151], v[202:205], v[90:93]
	v_mfma_f32_16x16x32_bf16 v[78:81], v[140:143], v[210:213], v[78:81]
	v_mfma_f32_16x16x32_bf16 v[74:77], v[148:151], v[210:213], v[74:77]
	v_mfma_f32_16x16x32_bf16 v[126:129], v[144:147], v[190:193], v[126:129]
	v_mfma_f32_16x16x32_bf16 v[122:125], v[156:159], v[190:193], v[122:125]
	v_mfma_f32_16x16x32_bf16 v[110:113], v[144:147], v[198:201], v[110:113]
	v_mfma_f32_16x16x32_bf16 v[106:109], v[156:159], v[198:201], v[106:109]
	v_mfma_f32_16x16x32_bf16 v[94:97], v[144:147], v[206:209], v[94:97]
	v_mfma_f32_16x16x32_bf16 v[90:93], v[156:159], v[206:209], v[90:93]
	v_mfma_f32_16x16x32_bf16 v[78:81], v[144:147], v[214:217], v[78:81]
	v_mfma_f32_16x16x32_bf16 v[74:77], v[156:159], v[214:217], v[74:77]
	v_mfma_f32_16x16x32_bf16 v[118:121], v[160:163], v[176:179], v[118:121]
	v_mfma_f32_16x16x32_bf16 v[114:117], v[168:171], v[176:179], v[114:117]
	v_mfma_f32_16x16x32_bf16 v[102:105], v[160:163], v[194:197], v[102:105]
	v_mfma_f32_16x16x32_bf16 v[98:101], v[168:171], v[194:197], v[98:101]
	v_mfma_f32_16x16x32_bf16 v[86:89], v[160:163], v[202:205], v[86:89]
	v_mfma_f32_16x16x32_bf16 v[82:85], v[168:171], v[202:205], v[82:85]
	v_mfma_f32_16x16x32_bf16 v[70:73], v[160:163], v[210:213], v[70:73]
	v_mfma_f32_16x16x32_bf16 v[66:69], v[168:171], v[210:213], v[66:69]
	v_mfma_f32_16x16x32_bf16 v[118:121], v[164:167], v[190:193], v[118:121]
	v_mfma_f32_16x16x32_bf16 v[114:117], v[172:175], v[190:193], v[114:117]
	v_mfma_f32_16x16x32_bf16 v[102:105], v[164:167], v[198:201], v[102:105]
	v_mfma_f32_16x16x32_bf16 v[98:101], v[172:175], v[198:201], v[98:101]
	v_mfma_f32_16x16x32_bf16 v[86:89], v[164:167], v[206:209], v[86:89]
	v_mfma_f32_16x16x32_bf16 v[82:85], v[172:175], v[206:209], v[82:85]
	v_mfma_f32_16x16x32_bf16 v[70:73], v[164:167], v[214:217], v[70:73]
	v_mfma_f32_16x16x32_bf16 v[66:69], v[172:175], v[214:217], v[66:69]
	s_barrier
	s_setprio 0
	s_add_i32 s40, s64, s43
	v_lshl_add_u64 v[218:219], v[218:219], 0, s[16:17]
	s_mov_b32 m0, s40
	ds_read_b128 v[176:179], v154 offset:49152
	ds_read_b128 v[190:193], v154 offset:50176
	ds_read_b128 v[194:197], v154 offset:51200
	ds_read_b128 v[198:201], v154 offset:52224
	ds_read_b128 v[202:205], v154 offset:53248
	ds_read_b128 v[206:209], v154 offset:54272
	ds_read_b128 v[210:213], v154 offset:55296
	ds_read_b128 v[214:217], v154 offset:56320
	global_load_lds_dwordx4 v[218:219], off
	s_add_i32 m0, s40, 0x2000
	s_add_u32 s38, s38, 0x80080
	v_lshl_add_u64 v[218:219], v[220:221], 0, s[16:17]
	s_addc_u32 s39, s39, 0
	s_add_i32 s40, s70, s43
	global_load_lds_dwordx4 v[218:219], off
	v_lshl_add_u64 v[218:219], s[38:39], 0, v[134:135]
	s_mov_b32 m0, s40
	s_nop 0
	global_load_lds_dwordx4 v[218:219], off
	v_lshl_add_u64 v[218:219], s[38:39], 0, v[132:133]
	s_add_i32 m0, s40, 0x2000
	s_nop 0
	global_load_lds_dwordx4 v[218:219], off
	v_lshl_add_u64 v[218:219], v[222:223], 0, s[16:17]
	s_mov_b32 m0, s50
	s_nop 0
	global_load_lds_dwordx4 v[218:219], off
	v_lshl_add_u64 v[218:219], v[238:239], 0, s[16:17]
	s_mov_b32 m0, s51
	s_nop 0
	global_load_lds_dwordx4 v[218:219], off
	s_waitcnt vmcnt(8)
	s_waitcnt lgkmcnt(0)
	s_setprio 1
	s_barrier
	v_mfma_f32_16x16x32_bf16 v[62:65], v[140:143], v[176:179], v[62:65]
	v_mfma_f32_16x16x32_bf16 v[58:61], v[148:151], v[176:179], v[58:61]
	v_mfma_f32_16x16x32_bf16 v[46:49], v[140:143], v[194:197], v[46:49]
	v_mfma_f32_16x16x32_bf16 v[42:45], v[148:151], v[194:197], v[42:45]
	v_mfma_f32_16x16x32_bf16 v[30:33], v[140:143], v[202:205], v[30:33]
	v_mfma_f32_16x16x32_bf16 v[26:29], v[148:151], v[202:205], v[26:29]
	v_mfma_f32_16x16x32_bf16 v[14:17], v[140:143], v[210:213], v[14:17]
	v_mfma_f32_16x16x32_bf16 v[10:13], v[148:151], v[210:213], v[10:13]
	v_mfma_f32_16x16x32_bf16 v[62:65], v[144:147], v[190:193], v[62:65]
	v_mfma_f32_16x16x32_bf16 v[58:61], v[156:159], v[190:193], v[58:61]
	v_mfma_f32_16x16x32_bf16 v[46:49], v[144:147], v[198:201], v[46:49]
	v_mfma_f32_16x16x32_bf16 v[42:45], v[156:159], v[198:201], v[42:45]
	v_mfma_f32_16x16x32_bf16 v[30:33], v[144:147], v[206:209], v[30:33]
	v_mfma_f32_16x16x32_bf16 v[26:29], v[156:159], v[206:209], v[26:29]
	v_mfma_f32_16x16x32_bf16 v[14:17], v[144:147], v[214:217], v[14:17]
	v_mfma_f32_16x16x32_bf16 v[10:13], v[156:159], v[214:217], v[10:13]
	v_mfma_f32_16x16x32_bf16 v[54:57], v[160:163], v[176:179], v[54:57]
	v_mfma_f32_16x16x32_bf16 v[50:53], v[168:171], v[176:179], v[50:53]
	v_mfma_f32_16x16x32_bf16 v[38:41], v[160:163], v[194:197], v[38:41]
	v_mfma_f32_16x16x32_bf16 v[34:37], v[168:171], v[194:197], v[34:37]
	v_mfma_f32_16x16x32_bf16 v[22:25], v[160:163], v[202:205], v[22:25]
	v_mfma_f32_16x16x32_bf16 v[18:21], v[168:171], v[202:205], v[18:21]
	v_mfma_f32_16x16x32_bf16 v[6:9], v[160:163], v[210:213], v[6:9]
	v_mfma_f32_16x16x32_bf16 v[2:5], v[168:171], v[210:213], v[2:5]
	v_mfma_f32_16x16x32_bf16 v[54:57], v[164:167], v[190:193], v[54:57]
	v_mfma_f32_16x16x32_bf16 v[50:53], v[172:175], v[190:193], v[50:53]
	v_mfma_f32_16x16x32_bf16 v[38:41], v[164:167], v[198:201], v[38:41]
	v_mfma_f32_16x16x32_bf16 v[34:37], v[172:175], v[198:201], v[34:37]
	v_mfma_f32_16x16x32_bf16 v[22:25], v[164:167], v[206:209], v[22:25]
	v_mfma_f32_16x16x32_bf16 v[18:21], v[172:175], v[206:209], v[18:21]
	v_mfma_f32_16x16x32_bf16 v[6:9], v[164:167], v[214:217], v[6:9]
	v_mfma_f32_16x16x32_bf16 v[2:5], v[172:175], v[214:217], v[2:5]
	s_barrier
	s_setprio 0
	s_add_i32 s63, s63, 2
	s_add_u32 s36, s36, 0x100
	s_addc_u32 s37, s37, 0
	s_add_u32 s61, s61, 0x100
	s_addc_u32 s62, s62, 0
	s_cmp_gt_u32 s63, 29
	s_cbranch_scc0 .LBB0_1230
	s_and_b64 vcc, exec, s[30:31]
	s_cbranch_vccz .LBB0_1233
	s_barrier

.LBB0_1583:
	s_add_u32 s46, s48, 0xfff80080
	s_addc_u32 s47, s49, -1
	s_add_i32 s68, 0, 0x10000
	s_cmp_eq_u32 s67, 28
	s_cselect_b32 s51, s35, s47
	s_cselect_b32 s50, s39, s46
	s_cselect_b32 s47, s31, s66
	s_cselect_b32 s46, s45, s64
	s_add_i32 s70, 0, 0x14000
	v_add_u32_e32 v162, s68, v152
	v_add_u32_e32 v178, s70, v152
	ds_read_b128 v[144:147], v162
	ds_read_b128 v[154:157], v162 offset:1024
	ds_read_b128 v[158:161], v162 offset:2048
	ds_read_b128 v[162:165], v162 offset:3072
	ds_read_b128 v[166:169], v178
	ds_read_b128 v[170:173], v178 offset:1024
	ds_read_b128 v[174:177], v178 offset:2048
	ds_read_b128 v[190:193], v178 offset:3072
	v_lshl_add_u64 v[178:179], s[48:49], 0, v[140:141]
	s_add_i32 m0, s56, 0xc000
	ds_read_b128 v[194:197], v153
	ds_read_b128 v[198:201], v153 offset:1024
	ds_read_b128 v[202:205], v153 offset:2048
	ds_read_b128 v[206:209], v153 offset:3072
	ds_read_b128 v[210:213], v153 offset:4096
	ds_read_b128 v[214:217], v153 offset:5120
	ds_read_b128 v[218:221], v153 offset:6144
	ds_read_b128 v[238:241], v153 offset:7168
	global_load_lds_dwordx4 v[178:179], off
	v_lshl_add_u64 v[178:179], s[48:49], 0, v[142:143]
	s_add_i32 m0, s56, 0xe000
	s_nop 0
	global_load_lds_dwordx4 v[178:179], off
	s_waitcnt vmcnt(8)
	s_waitcnt lgkmcnt(0)
	s_setprio 1
	s_barrier
	v_mfma_f32_16x16x32_bf16 v[126:129], v[144:147], v[194:197], v[126:129]
	v_mfma_f32_16x16x32_bf16 v[114:117], v[158:161], v[194:197], v[114:117]
	v_mfma_f32_16x16x32_bf16 v[106:109], v[144:147], v[202:205], v[106:109]
	v_mfma_f32_16x16x32_bf16 v[98:101], v[158:161], v[202:205], v[98:101]
	v_mfma_f32_16x16x32_bf16 v[90:93], v[144:147], v[210:213], v[90:93]
	v_mfma_f32_16x16x32_bf16 v[82:85], v[158:161], v[210:213], v[82:85]
	v_mfma_f32_16x16x32_bf16 v[74:77], v[144:147], v[218:221], v[74:77]
	v_mfma_f32_16x16x32_bf16 v[54:57], v[158:161], v[218:221], v[54:57]
	v_mfma_f32_16x16x32_bf16 v[126:129], v[154:157], v[198:201], v[126:129]
	v_mfma_f32_16x16x32_bf16 v[114:117], v[162:165], v[198:201], v[114:117]
	v_mfma_f32_16x16x32_bf16 v[106:109], v[154:157], v[206:209], v[106:109]
	v_mfma_f32_16x16x32_bf16 v[98:101], v[162:165], v[206:209], v[98:101]
	v_mfma_f32_16x16x32_bf16 v[90:93], v[154:157], v[214:217], v[90:93]
	v_mfma_f32_16x16x32_bf16 v[82:85], v[162:165], v[214:217], v[82:85]
	v_mfma_f32_16x16x32_bf16 v[74:77], v[154:157], v[238:241], v[74:77]
	v_mfma_f32_16x16x32_bf16 v[54:57], v[162:165], v[238:241], v[54:57]
	v_mfma_f32_16x16x32_bf16 v[118:121], v[166:169], v[194:197], v[118:121]
	v_mfma_f32_16x16x32_bf16 v[122:125], v[174:177], v[194:197], v[122:125]
	v_mfma_f32_16x16x32_bf16 v[102:105], v[166:169], v[202:205], v[102:105]
	v_mfma_f32_16x16x32_bf16 v[110:113], v[174:177], v[202:205], v[110:113]
	v_mfma_f32_16x16x32_bf16 v[86:89], v[166:169], v[210:213], v[86:89]
	v_mfma_f32_16x16x32_bf16 v[94:97], v[174:177], v[210:213], v[94:97]
	v_mfma_f32_16x16x32_bf16 v[70:73], v[166:169], v[218:221], v[70:73]
	v_mfma_f32_16x16x32_bf16 v[78:81], v[174:177], v[218:221], v[78:81]
	v_mfma_f32_16x16x32_bf16 v[118:121], v[170:173], v[198:201], v[118:121]
	v_mfma_f32_16x16x32_bf16 v[122:125], v[190:193], v[198:201], v[122:125]
	v_mfma_f32_16x16x32_bf16 v[102:105], v[170:173], v[206:209], v[102:105]
	v_mfma_f32_16x16x32_bf16 v[110:113], v[190:193], v[206:209], v[110:113]
	v_mfma_f32_16x16x32_bf16 v[86:89], v[170:173], v[214:217], v[86:89]
	v_mfma_f32_16x16x32_bf16 v[94:97], v[190:193], v[214:217], v[94:97]
	v_mfma_f32_16x16x32_bf16 v[70:73], v[170:173], v[238:241], v[70:73]
	v_mfma_f32_16x16x32_bf16 v[78:81], v[190:193], v[238:241], v[78:81]
	s_barrier
	s_setprio 0
	s_add_i32 s68, s68, s8
	v_lshl_add_u64 v[178:179], s[46:47], 0, v[134:135]
	s_mov_b32 m0, s68
	ds_read_b128 v[194:197], v153 offset:16384
	ds_read_b128 v[198:201], v153 offset:17408
	ds_read_b128 v[202:205], v153 offset:18432
	ds_read_b128 v[206:209], v153 offset:19456
	ds_read_b128 v[210:213], v153 offset:20480
	ds_read_b128 v[214:217], v153 offset:21504
	ds_read_b128 v[218:221], v153 offset:22528
	ds_read_b128 v[238:241], v153 offset:23552
	global_load_lds_dwordx4 v[178:179], off
	s_add_i32 m0, s68, 0x2000
	s_add_u32 s68, s46, 0x80000
	v_lshl_add_u64 v[222:223], s[46:47], 0, v[138:139]
	s_addc_u32 s69, s47, 0
	s_add_i32 s70, s70, s8
	global_load_lds_dwordx4 v[222:223], off
	v_lshl_add_u64 v[242:243], s[68:69], 0, v[134:135]
	s_mov_b32 m0, s70
	v_lshl_add_u64 v[244:245], s[50:51], 0, v[136:137]
	global_load_lds_dwordx4 v[242:243], off
	v_lshl_add_u64 v[242:243], s[68:69], 0, v[138:139]
	s_add_i32 m0, s70, 0x2000
	s_nop 0
	global_load_lds_dwordx4 v[242:243], off
	v_lshl_add_u64 v[242:243], s[50:51], 0, v[132:133]
	s_mov_b32 m0, s56
	s_nop 0
	global_load_lds_dwordx4 v[242:243], off
	s_mov_b32 m0, s57
	s_nop 0
	global_load_lds_dwordx4 v[244:245], off
	s_waitcnt vmcnt(8)
	s_waitcnt lgkmcnt(0)
	s_setprio 1
	s_barrier
	v_mfma_f32_16x16x32_bf16 v[50:53], v[144:147], v[194:197], v[50:53]
	v_mfma_f32_16x16x32_bf16 v[38:41], v[158:161], v[194:197], v[38:41]
	v_mfma_f32_16x16x32_bf16 v[22:25], v[144:147], v[202:205], v[22:25]
	v_mfma_f32_16x16x32_bf16 v[42:45], v[158:161], v[202:205], v[42:45]
	v_mfma_f32_16x16x32_bf16 v[30:33], v[144:147], v[210:213], v[30:33]
	v_mfma_f32_16x16x32_bf16 v[18:21], v[158:161], v[210:213], v[18:21]
	v_mfma_f32_16x16x32_bf16 v[10:13], v[144:147], v[218:221], v[10:13]
	v_mfma_f32_16x16x32_bf16 v[2:5], v[158:161], v[218:221], v[2:5]
	v_mfma_f32_16x16x32_bf16 v[50:53], v[154:157], v[198:201], v[50:53]
	v_mfma_f32_16x16x32_bf16 v[38:41], v[162:165], v[198:201], v[38:41]
	v_mfma_f32_16x16x32_bf16 v[22:25], v[154:157], v[206:209], v[22:25]
	v_mfma_f32_16x16x32_bf16 v[42:45], v[162:165], v[206:209], v[42:45]
	v_mfma_f32_16x16x32_bf16 v[30:33], v[154:157], v[214:217], v[30:33]
	v_mfma_f32_16x16x32_bf16 v[18:21], v[162:165], v[214:217], v[18:21]
	v_mfma_f32_16x16x32_bf16 v[10:13], v[154:157], v[238:241], v[10:13]
	v_mfma_f32_16x16x32_bf16 v[2:5], v[162:165], v[238:241], v[2:5]
	v_mfma_f32_16x16x32_bf16 v[46:49], v[166:169], v[194:197], v[46:49]
	v_mfma_f32_16x16x32_bf16 v[58:61], v[174:177], v[194:197], v[58:61]
	v_mfma_f32_16x16x32_bf16 v[62:65], v[166:169], v[202:205], v[62:65]
	v_mfma_f32_16x16x32_bf16 v[66:69], v[174:177], v[202:205], v[66:69]
	v_mfma_f32_16x16x32_bf16 v[26:29], v[166:169], v[210:213], v[26:29]
	v_mfma_f32_16x16x32_bf16 v[34:37], v[174:177], v[210:213], v[34:37]
	v_mfma_f32_16x16x32_bf16 v[6:9], v[166:169], v[218:221], v[6:9]
	v_mfma_f32_16x16x32_bf16 v[14:17], v[174:177], v[218:221], v[14:17]
	v_mfma_f32_16x16x32_bf16 v[46:49], v[170:173], v[198:201], v[46:49]
	v_mfma_f32_16x16x32_bf16 v[58:61], v[190:193], v[198:201], v[58:61]
	v_mfma_f32_16x16x32_bf16 v[62:65], v[170:173], v[206:209], v[62:65]
	v_mfma_f32_16x16x32_bf16 v[66:69], v[190:193], v[206:209], v[66:69]
	v_mfma_f32_16x16x32_bf16 v[26:29], v[170:173], v[214:217], v[26:29]
	v_mfma_f32_16x16x32_bf16 v[34:37], v[190:193], v[214:217], v[34:37]
	v_mfma_f32_16x16x32_bf16 v[6:9], v[170:173], v[238:241], v[6:9]
	v_mfma_f32_16x16x32_bf16 v[14:17], v[190:193], v[238:241], v[14:17]
	s_barrier
	s_setprio 0
	s_add_i32 s68, 0, 0x18000
	s_add_i32 s69, 0, 0x1c000
	v_add_u32_e32 v162, s68, v152
	v_add_u32_e32 v190, s69, v152
	ds_read_b128 v[144:147], v162
	ds_read_b128 v[154:157], v162 offset:1024
	ds_read_b128 v[158:161], v162 offset:2048
	ds_read_b128 v[162:165], v162 offset:3072
	ds_read_b128 v[166:169], v190
	ds_read_b128 v[170:173], v190 offset:1024
	ds_read_b128 v[174:177], v190 offset:2048
	ds_read_b128 v[190:193], v190 offset:3072
	s_add_u32 s50, s50, 0x80000
	s_addc_u32 s51, s51, 0
	s_mov_b32 m0, s58
	v_lshl_add_u64 v[246:247], s[50:51], 0, v[132:133]
	ds_read_b128 v[194:197], v153 offset:32768
	ds_read_b128 v[198:201], v153 offset:33792
	ds_read_b128 v[202:205], v153 offset:34816
	ds_read_b128 v[206:209], v153 offset:35840
	ds_read_b128 v[210:213], v153 offset:36864
	ds_read_b128 v[214:217], v153 offset:37888
	ds_read_b128 v[218:221], v153 offset:38912
	ds_read_b128 v[238:241], v153 offset:39936
	global_load_lds_dwordx4 v[246:247], off
	v_lshl_add_u64 v[246:247], s[50:51], 0, v[136:137]
	s_mov_b32 m0, s59
	s_nop 0
	global_load_lds_dwordx4 v[246:247], off
	s_waitcnt vmcnt(8)
	s_waitcnt lgkmcnt(0)
	s_setprio 1
	s_barrier
	v_mfma_f32_16x16x32_bf16 v[126:129], v[144:147], v[194:197], v[126:129]
	v_mfma_f32_16x16x32_bf16 v[114:117], v[158:161], v[194:197], v[114:117]
	v_mfma_f32_16x16x32_bf16 v[106:109], v[144:147], v[202:205], v[106:109]
	v_mfma_f32_16x16x32_bf16 v[98:101], v[158:161], v[202:205], v[98:101]
	v_mfma_f32_16x16x32_bf16 v[90:93], v[144:147], v[210:213], v[90:93]
	v_mfma_f32_16x16x32_bf16 v[82:85], v[158:161], v[210:213], v[82:85]
	v_mfma_f32_16x16x32_bf16 v[74:77], v[144:147], v[218:221], v[74:77]
	v_mfma_f32_16x16x32_bf16 v[54:57], v[158:161], v[218:221], v[54:57]
	v_mfma_f32_16x16x32_bf16 v[126:129], v[154:157], v[198:201], v[126:129]
	v_mfma_f32_16x16x32_bf16 v[114:117], v[162:165], v[198:201], v[114:117]
	v_mfma_f32_16x16x32_bf16 v[106:109], v[154:157], v[206:209], v[106:109]
	v_mfma_f32_16x16x32_bf16 v[98:101], v[162:165], v[206:209], v[98:101]
	v_mfma_f32_16x16x32_bf16 v[90:93], v[154:157], v[214:217], v[90:93]
	v_mfma_f32_16x16x32_bf16 v[82:85], v[162:165], v[214:217], v[82:85]
	v_mfma_f32_16x16x32_bf16 v[74:77], v[154:157], v[238:241], v[74:77]
	v_mfma_f32_16x16x32_bf16 v[54:57], v[162:165], v[238:241], v[54:57]
	v_mfma_f32_16x16x32_bf16 v[118:121], v[166:169], v[194:197], v[118:121]
	v_mfma_f32_16x16x32_bf16 v[122:125], v[174:177], v[194:197], v[122:125]
	v_mfma_f32_16x16x32_bf16 v[102:105], v[166:169], v[202:205], v[102:105]
	v_mfma_f32_16x16x32_bf16 v[110:113], v[174:177], v[202:205], v[110:113]
	v_mfma_f32_16x16x32_bf16 v[86:89], v[166:169], v[210:213], v[86:89]
	v_mfma_f32_16x16x32_bf16 v[94:97], v[174:177], v[210:213], v[94:97]
	v_mfma_f32_16x16x32_bf16 v[70:73], v[166:169], v[218:221], v[70:73]
	v_mfma_f32_16x16x32_bf16 v[78:81], v[174:177], v[218:221], v[78:81]
	v_mfma_f32_16x16x32_bf16 v[118:121], v[170:173], v[198:201], v[118:121]
	v_mfma_f32_16x16x32_bf16 v[122:125], v[190:193], v[198:201], v[122:125]
	v_mfma_f32_16x16x32_bf16 v[102:105], v[170:173], v[206:209], v[102:105]
	v_mfma_f32_16x16x32_bf16 v[110:113], v[190:193], v[206:209], v[110:113]
	v_mfma_f32_16x16x32_bf16 v[86:89], v[170:173], v[214:217], v[86:89]
	v_mfma_f32_16x16x32_bf16 v[94:97], v[190:193], v[214:217], v[94:97]
	v_mfma_f32_16x16x32_bf16 v[70:73], v[170:173], v[238:241], v[70:73]
	v_mfma_f32_16x16x32_bf16 v[78:81], v[190:193], v[238:241], v[78:81]
	s_barrier
	s_setprio 0
	s_add_i32 s50, s68, s8
	v_lshl_add_u64 v[178:179], v[178:179], 0, s[16:17]
	s_mov_b32 m0, s50
	ds_read_b128 v[194:197], v153 offset:49152
	ds_read_b128 v[198:201], v153 offset:50176
	ds_read_b128 v[202:205], v153 offset:51200
	ds_read_b128 v[206:209], v153 offset:52224
	ds_read_b128 v[210:213], v153 offset:53248
	ds_read_b128 v[214:217], v153 offset:54272
	ds_read_b128 v[218:221], v153 offset:55296
	ds_read_b128 v[238:241], v153 offset:56320
	global_load_lds_dwordx4 v[178:179], off
	s_add_i32 m0, s50, 0x2000
	s_add_u32 s46, s46, 0x80080
	v_lshl_add_u64 v[178:179], v[222:223], 0, s[16:17]
	s_addc_u32 s47, s47, 0
	s_add_i32 s50, s69, s8
	global_load_lds_dwordx4 v[178:179], off
	v_lshl_add_u64 v[178:179], s[46:47], 0, v[134:135]
	s_mov_b32 m0, s50
	s_nop 0
	global_load_lds_dwordx4 v[178:179], off
	v_lshl_add_u64 v[178:179], s[46:47], 0, v[138:139]
	s_add_i32 m0, s50, 0x2000
	s_nop 0
	global_load_lds_dwordx4 v[178:179], off
	v_lshl_add_u64 v[178:179], v[242:243], 0, s[16:17]
	s_mov_b32 m0, s60
	s_nop 0
	global_load_lds_dwordx4 v[178:179], off
	v_lshl_add_u64 v[178:179], v[244:245], 0, s[16:17]
	s_mov_b32 m0, s61
	s_nop 0
	global_load_lds_dwordx4 v[178:179], off
	s_waitcnt vmcnt(8)
	s_waitcnt lgkmcnt(0)
	s_setprio 1
	s_barrier
	v_mfma_f32_16x16x32_bf16 v[50:53], v[144:147], v[194:197], v[50:53]
	v_mfma_f32_16x16x32_bf16 v[38:41], v[158:161], v[194:197], v[38:41]
	v_mfma_f32_16x16x32_bf16 v[22:25], v[144:147], v[202:205], v[22:25]
	v_mfma_f32_16x16x32_bf16 v[42:45], v[158:161], v[202:205], v[42:45]
	v_mfma_f32_16x16x32_bf16 v[30:33], v[144:147], v[210:213], v[30:33]
	v_mfma_f32_16x16x32_bf16 v[18:21], v[158:161], v[210:213], v[18:21]
	v_mfma_f32_16x16x32_bf16 v[10:13], v[144:147], v[218:221], v[10:13]
	v_mfma_f32_16x16x32_bf16 v[2:5], v[158:161], v[218:221], v[2:5]
	v_mfma_f32_16x16x32_bf16 v[50:53], v[154:157], v[198:201], v[50:53]
	v_mfma_f32_16x16x32_bf16 v[38:41], v[162:165], v[198:201], v[38:41]
	v_mfma_f32_16x16x32_bf16 v[22:25], v[154:157], v[206:209], v[22:25]
	v_mfma_f32_16x16x32_bf16 v[42:45], v[162:165], v[206:209], v[42:45]
	v_mfma_f32_16x16x32_bf16 v[30:33], v[154:157], v[214:217], v[30:33]
	v_mfma_f32_16x16x32_bf16 v[18:21], v[162:165], v[214:217], v[18:21]
	v_mfma_f32_16x16x32_bf16 v[10:13], v[154:157], v[238:241], v[10:13]
	v_mfma_f32_16x16x32_bf16 v[2:5], v[162:165], v[238:241], v[2:5]
	v_mfma_f32_16x16x32_bf16 v[46:49], v[166:169], v[194:197], v[46:49]
	v_mfma_f32_16x16x32_bf16 v[58:61], v[174:177], v[194:197], v[58:61]
	v_mfma_f32_16x16x32_bf16 v[62:65], v[166:169], v[202:205], v[62:65]
	v_mfma_f32_16x16x32_bf16 v[66:69], v[174:177], v[202:205], v[66:69]
	v_mfma_f32_16x16x32_bf16 v[26:29], v[166:169], v[210:213], v[26:29]
	v_mfma_f32_16x16x32_bf16 v[34:37], v[174:177], v[210:213], v[34:37]
	v_mfma_f32_16x16x32_bf16 v[6:9], v[166:169], v[218:221], v[6:9]
	v_mfma_f32_16x16x32_bf16 v[14:17], v[174:177], v[218:221], v[14:17]
	v_mfma_f32_16x16x32_bf16 v[46:49], v[170:173], v[198:201], v[46:49]
	v_mfma_f32_16x16x32_bf16 v[58:61], v[190:193], v[198:201], v[58:61]
	v_mfma_f32_16x16x32_bf16 v[62:65], v[170:173], v[206:209], v[62:65]
	v_mfma_f32_16x16x32_bf16 v[66:69], v[190:193], v[206:209], v[66:69]
	v_mfma_f32_16x16x32_bf16 v[26:29], v[170:173], v[214:217], v[26:29]
	v_mfma_f32_16x16x32_bf16 v[34:37], v[190:193], v[214:217], v[34:37]
	v_mfma_f32_16x16x32_bf16 v[6:9], v[170:173], v[238:241], v[6:9]
	v_mfma_f32_16x16x32_bf16 v[14:17], v[190:193], v[238:241], v[14:17]
	s_barrier
	s_setprio 0
	s_add_i32 s67, s67, 2
	s_add_u32 s48, s48, 0x100
	s_addc_u32 s49, s49, 0
	s_add_u32 s64, s64, 0x100
	s_addc_u32 s66, s66, 0
	s_cmp_gt_u32 s67, 29
	s_cbranch_scc0 .LBB0_1583
	s_and_b64 vcc, exec, s[28:29]
	s_cbranch_vccz .LBB0_1586
	s_barrier

.LBB0_1685:
	s_add_u32 s42, s40, 0xfff80080
	s_addc_u32 s43, s41, -1
	s_and_b64 s[26:27], s[26:27], exec
	s_cselect_b32 s43, s19, s43
	s_cselect_b32 s42, s45, s42
	s_cselect_b32 s27, s50, s39
	s_cselect_b32 s26, s51, s37
	s_add_i32 s47, 0, 0x10000
	s_add_i32 s69, 0, 0x14000
	v_add_u32_e32 v146, s47, v239
	v_add_u32_e32 v162, s69, v239
	ds_read_b128 v[114:117], v146
	ds_read_b128 v[118:121], v146 offset:1024
	ds_read_b128 v[122:125], v146 offset:2048
	ds_read_b128 v[146:149], v146 offset:3072
	ds_read_b128 v[150:153], v162
	ds_read_b128 v[154:157], v162 offset:1024
	ds_read_b128 v[158:161], v162 offset:2048
	ds_read_b128 v[162:165], v162 offset:3072
	v_lshl_add_u64 v[178:179], s[40:41], 0, v[202:203]
	s_add_i32 m0, s6, 0xc000
	ds_read_b128 v[166:169], v240
	ds_read_b128 v[170:173], v240 offset:1024
	ds_read_b128 v[174:177], v240 offset:2048
	ds_read_b128 v[206:209], v240 offset:3072
	ds_read_b128 v[210:213], v240 offset:4096
	ds_read_b128 v[214:217], v240 offset:5120
	ds_read_b128 v[218:221], v240 offset:6144
	ds_read_b128 v[242:245], v240 offset:7168
	global_load_lds_dwordx4 v[178:179], off
	v_lshl_add_u64 v[178:179], s[40:41], 0, v[204:205]
	s_add_i32 m0, s6, 0xe000
	s_nop 0
	global_load_lds_dwordx4 v[178:179], off
	s_waitcnt vmcnt(8)
	s_waitcnt lgkmcnt(0)
	s_setprio 1
	s_barrier
	v_mfma_f32_16x16x32_bf16 v[142:145], v[114:117], v[166:169], v[142:145]
	v_mfma_f32_16x16x32_bf16 v[62:65], v[122:125], v[166:169], v[62:65]
	v_mfma_f32_16x16x32_bf16 v[134:137], v[114:117], v[174:177], v[134:137]
	v_mfma_f32_16x16x32_bf16 v[54:57], v[122:125], v[174:177], v[54:57]
	v_mfma_f32_16x16x32_bf16 v[126:129], v[114:117], v[210:213], v[126:129]
	v_mfma_f32_16x16x32_bf16 v[46:49], v[122:125], v[210:213], v[46:49]
	v_mfma_f32_16x16x32_bf16 v[102:105], v[114:117], v[218:221], v[102:105]
	v_mfma_f32_16x16x32_bf16 v[38:41], v[122:125], v[218:221], v[38:41]
	v_mfma_f32_16x16x32_bf16 v[142:145], v[118:121], v[170:173], v[142:145]
	v_mfma_f32_16x16x32_bf16 v[62:65], v[146:149], v[170:173], v[62:65]
	v_mfma_f32_16x16x32_bf16 v[134:137], v[118:121], v[206:209], v[134:137]
	v_mfma_f32_16x16x32_bf16 v[54:57], v[146:149], v[206:209], v[54:57]
	v_mfma_f32_16x16x32_bf16 v[126:129], v[118:121], v[214:217], v[126:129]
	v_mfma_f32_16x16x32_bf16 v[46:49], v[146:149], v[214:217], v[46:49]
	v_mfma_f32_16x16x32_bf16 v[102:105], v[118:121], v[242:245], v[102:105]
	v_mfma_f32_16x16x32_bf16 v[38:41], v[146:149], v[242:245], v[38:41]
	v_mfma_f32_16x16x32_bf16 v[138:141], v[150:153], v[166:169], v[138:141]
	v_mfma_f32_16x16x32_bf16 v[58:61], v[158:161], v[166:169], v[58:61]
	v_mfma_f32_16x16x32_bf16 v[130:133], v[150:153], v[174:177], v[130:133]
	v_mfma_f32_16x16x32_bf16 v[50:53], v[158:161], v[174:177], v[50:53]
	v_mfma_f32_16x16x32_bf16 v[106:109], v[150:153], v[210:213], v[106:109]
	v_mfma_f32_16x16x32_bf16 v[42:45], v[158:161], v[210:213], v[42:45]
	v_mfma_f32_16x16x32_bf16 v[98:101], v[150:153], v[218:221], v[98:101]
	v_mfma_f32_16x16x32_bf16 v[34:37], v[158:161], v[218:221], v[34:37]
	v_mfma_f32_16x16x32_bf16 v[138:141], v[154:157], v[170:173], v[138:141]
	v_mfma_f32_16x16x32_bf16 v[58:61], v[162:165], v[170:173], v[58:61]
	v_mfma_f32_16x16x32_bf16 v[130:133], v[154:157], v[206:209], v[130:133]
	v_mfma_f32_16x16x32_bf16 v[50:53], v[162:165], v[206:209], v[50:53]
	v_mfma_f32_16x16x32_bf16 v[106:109], v[154:157], v[214:217], v[106:109]
	v_mfma_f32_16x16x32_bf16 v[42:45], v[162:165], v[214:217], v[42:45]
	v_mfma_f32_16x16x32_bf16 v[98:101], v[154:157], v[242:245], v[98:101]
	v_mfma_f32_16x16x32_bf16 v[34:37], v[162:165], v[242:245], v[34:37]
	s_barrier
	s_setprio 0
	s_add_i32 s47, s47, s23
	v_lshl_add_u64 v[178:179], s[26:27], 0, v[180:181]
	s_mov_b32 m0, s47
	ds_read_b128 v[166:169], v240 offset:16384
	ds_read_b128 v[170:173], v240 offset:17408
	ds_read_b128 v[174:177], v240 offset:18432
	ds_read_b128 v[206:209], v240 offset:19456
	ds_read_b128 v[210:213], v240 offset:20480
	ds_read_b128 v[214:217], v240 offset:21504
	ds_read_b128 v[218:221], v240 offset:22528
	ds_read_b128 v[242:245], v240 offset:23552
	global_load_lds_dwordx4 v[178:179], off
	s_add_i32 m0, s47, 0x2000
	s_add_u32 s48, s26, 0x80000
	v_lshl_add_u64 v[222:223], s[26:27], 0, v[196:197]
	s_addc_u32 s49, s27, 0
	s_add_i32 s47, s69, s23
	global_load_lds_dwordx4 v[222:223], off
	v_lshl_add_u64 v[246:247], s[48:49], 0, v[180:181]
	s_mov_b32 m0, s47
	v_lshl_add_u64 v[248:249], s[42:43], 0, v[194:195]
	global_load_lds_dwordx4 v[246:247], off
	v_lshl_add_u64 v[246:247], s[48:49], 0, v[196:197]
	s_add_i32 m0, s47, 0x2000
	s_nop 0
	global_load_lds_dwordx4 v[246:247], off
	v_lshl_add_u64 v[246:247], s[42:43], 0, v[192:193]
	s_mov_b32 m0, s6
	s_nop 0
	global_load_lds_dwordx4 v[246:247], off
	s_mov_b32 m0, s9
	s_nop 0
	global_load_lds_dwordx4 v[248:249], off
	s_waitcnt vmcnt(8)
	s_waitcnt lgkmcnt(0)
	s_setprio 1
	s_barrier
	v_mfma_f32_16x16x32_bf16 v[94:97], v[114:117], v[166:169], v[94:97]
	v_mfma_f32_16x16x32_bf16 v[30:33], v[122:125], v[166:169], v[30:33]
	v_mfma_f32_16x16x32_bf16 v[86:89], v[114:117], v[174:177], v[86:89]
	v_mfma_f32_16x16x32_bf16 v[22:25], v[122:125], v[174:177], v[22:25]
	v_mfma_f32_16x16x32_bf16 v[78:81], v[114:117], v[210:213], v[78:81]
	v_mfma_f32_16x16x32_bf16 v[14:17], v[122:125], v[210:213], v[14:17]
	v_mfma_f32_16x16x32_bf16 v[70:73], v[114:117], v[218:221], v[70:73]
	v_mfma_f32_16x16x32_bf16 v[6:9], v[122:125], v[218:221], v[6:9]
	v_mfma_f32_16x16x32_bf16 v[94:97], v[118:121], v[170:173], v[94:97]
	v_mfma_f32_16x16x32_bf16 v[30:33], v[146:149], v[170:173], v[30:33]
	v_mfma_f32_16x16x32_bf16 v[86:89], v[118:121], v[206:209], v[86:89]
	v_mfma_f32_16x16x32_bf16 v[22:25], v[146:149], v[206:209], v[22:25]
	v_mfma_f32_16x16x32_bf16 v[78:81], v[118:121], v[214:217], v[78:81]
	v_mfma_f32_16x16x32_bf16 v[14:17], v[146:149], v[214:217], v[14:17]
	v_mfma_f32_16x16x32_bf16 v[70:73], v[118:121], v[242:245], v[70:73]
	v_mfma_f32_16x16x32_bf16 v[6:9], v[146:149], v[242:245], v[6:9]
	v_mfma_f32_16x16x32_bf16 v[90:93], v[150:153], v[166:169], v[90:93]
	v_mfma_f32_16x16x32_bf16 v[26:29], v[158:161], v[166:169], v[26:29]
	v_mfma_f32_16x16x32_bf16 v[82:85], v[150:153], v[174:177], v[82:85]
	v_mfma_f32_16x16x32_bf16 v[18:21], v[158:161], v[174:177], v[18:21]
	v_mfma_f32_16x16x32_bf16 v[74:77], v[150:153], v[210:213], v[74:77]
	v_mfma_f32_16x16x32_bf16 v[10:13], v[158:161], v[210:213], v[10:13]
	v_mfma_f32_16x16x32_bf16 v[66:69], v[150:153], v[218:221], v[66:69]
	v_mfma_f32_16x16x32_bf16 v[2:5], v[158:161], v[218:221], v[2:5]
	v_mfma_f32_16x16x32_bf16 v[90:93], v[154:157], v[170:173], v[90:93]
	v_mfma_f32_16x16x32_bf16 v[26:29], v[162:165], v[170:173], v[26:29]
	v_mfma_f32_16x16x32_bf16 v[82:85], v[154:157], v[206:209], v[82:85]
	v_mfma_f32_16x16x32_bf16 v[18:21], v[162:165], v[206:209], v[18:21]
	v_mfma_f32_16x16x32_bf16 v[74:77], v[154:157], v[214:217], v[74:77]
	v_mfma_f32_16x16x32_bf16 v[10:13], v[162:165], v[214:217], v[10:13]
	v_mfma_f32_16x16x32_bf16 v[66:69], v[154:157], v[242:245], v[66:69]
	v_mfma_f32_16x16x32_bf16 v[2:5], v[162:165], v[242:245], v[2:5]
	s_barrier
	s_setprio 0
	s_add_i32 s47, 0, 0x18000
	s_add_i32 s48, 0, 0x1c000
	v_add_u32_e32 v146, s47, v239
	v_add_u32_e32 v162, s48, v239
	ds_read_b128 v[114:117], v146
	ds_read_b128 v[118:121], v146 offset:1024
	ds_read_b128 v[122:125], v146 offset:2048
	ds_read_b128 v[146:149], v146 offset:3072
	ds_read_b128 v[150:153], v162
	ds_read_b128 v[154:157], v162 offset:1024
	ds_read_b128 v[158:161], v162 offset:2048
	ds_read_b128 v[162:165], v162 offset:3072
	s_add_u32 s42, s42, 0x80000
	s_addc_u32 s43, s43, 0
	s_mov_b32 m0, s21
	v_lshl_add_u64 v[250:251], s[42:43], 0, v[192:193]
	ds_read_b128 v[166:169], v240 offset:32768
	ds_read_b128 v[170:173], v240 offset:33792
	ds_read_b128 v[174:177], v240 offset:34816
	ds_read_b128 v[206:209], v240 offset:35840
	ds_read_b128 v[210:213], v240 offset:36864
	ds_read_b128 v[214:217], v240 offset:37888
	ds_read_b128 v[218:221], v240 offset:38912
	ds_read_b128 v[242:245], v240 offset:39936
	global_load_lds_dwordx4 v[250:251], off
	v_lshl_add_u64 v[250:251], s[42:43], 0, v[194:195]
	s_mov_b32 m0, s7
	s_nop 0
	global_load_lds_dwordx4 v[250:251], off
	s_waitcnt vmcnt(8)
	s_waitcnt lgkmcnt(0)
	s_setprio 1
	s_barrier
	v_mfma_f32_16x16x32_bf16 v[142:145], v[114:117], v[166:169], v[142:145]
	v_mfma_f32_16x16x32_bf16 v[62:65], v[122:125], v[166:169], v[62:65]
	v_mfma_f32_16x16x32_bf16 v[134:137], v[114:117], v[174:177], v[134:137]
	v_mfma_f32_16x16x32_bf16 v[54:57], v[122:125], v[174:177], v[54:57]
	v_mfma_f32_16x16x32_bf16 v[126:129], v[114:117], v[210:213], v[126:129]
	v_mfma_f32_16x16x32_bf16 v[46:49], v[122:125], v[210:213], v[46:49]
	v_mfma_f32_16x16x32_bf16 v[102:105], v[114:117], v[218:221], v[102:105]
	v_mfma_f32_16x16x32_bf16 v[38:41], v[122:125], v[218:221], v[38:41]
	v_mfma_f32_16x16x32_bf16 v[142:145], v[118:121], v[170:173], v[142:145]
	v_mfma_f32_16x16x32_bf16 v[62:65], v[146:149], v[170:173], v[62:65]
	v_mfma_f32_16x16x32_bf16 v[134:137], v[118:121], v[206:209], v[134:137]
	v_mfma_f32_16x16x32_bf16 v[54:57], v[146:149], v[206:209], v[54:57]
	v_mfma_f32_16x16x32_bf16 v[126:129], v[118:121], v[214:217], v[126:129]
	v_mfma_f32_16x16x32_bf16 v[46:49], v[146:149], v[214:217], v[46:49]
	v_mfma_f32_16x16x32_bf16 v[102:105], v[118:121], v[242:245], v[102:105]
	v_mfma_f32_16x16x32_bf16 v[38:41], v[146:149], v[242:245], v[38:41]
	v_mfma_f32_16x16x32_bf16 v[138:141], v[150:153], v[166:169], v[138:141]
	v_mfma_f32_16x16x32_bf16 v[58:61], v[158:161], v[166:169], v[58:61]
	v_mfma_f32_16x16x32_bf16 v[130:133], v[150:153], v[174:177], v[130:133]
	v_mfma_f32_16x16x32_bf16 v[50:53], v[158:161], v[174:177], v[50:53]
	v_mfma_f32_16x16x32_bf16 v[106:109], v[150:153], v[210:213], v[106:109]
	v_mfma_f32_16x16x32_bf16 v[42:45], v[158:161], v[210:213], v[42:45]
	v_mfma_f32_16x16x32_bf16 v[98:101], v[150:153], v[218:221], v[98:101]
	v_mfma_f32_16x16x32_bf16 v[34:37], v[158:161], v[218:221], v[34:37]
	v_mfma_f32_16x16x32_bf16 v[138:141], v[154:157], v[170:173], v[138:141]
	v_mfma_f32_16x16x32_bf16 v[58:61], v[162:165], v[170:173], v[58:61]
	v_mfma_f32_16x16x32_bf16 v[130:133], v[154:157], v[206:209], v[130:133]
	v_mfma_f32_16x16x32_bf16 v[50:53], v[162:165], v[206:209], v[50:53]
	v_mfma_f32_16x16x32_bf16 v[106:109], v[154:157], v[214:217], v[106:109]
	v_mfma_f32_16x16x32_bf16 v[42:45], v[162:165], v[214:217], v[42:45]
	v_mfma_f32_16x16x32_bf16 v[98:101], v[154:157], v[242:245], v[98:101]
	v_mfma_f32_16x16x32_bf16 v[34:37], v[162:165], v[242:245], v[34:37]
	s_barrier
	s_setprio 0
	s_add_i32 s42, s47, s23
	v_lshl_add_u64 v[178:179], v[178:179], 0, s[16:17]
	s_mov_b32 m0, s42
	ds_read_b128 v[166:169], v240 offset:49152
	ds_read_b128 v[170:173], v240 offset:50176
	ds_read_b128 v[174:177], v240 offset:51200
	ds_read_b128 v[206:209], v240 offset:52224
	ds_read_b128 v[210:213], v240 offset:53248
	ds_read_b128 v[214:217], v240 offset:54272
	ds_read_b128 v[218:221], v240 offset:55296
	ds_read_b128 v[242:245], v240 offset:56320
	global_load_lds_dwordx4 v[178:179], off
	s_add_i32 m0, s42, 0x2000
	s_add_u32 s26, s26, 0x80080
	v_lshl_add_u64 v[178:179], v[222:223], 0, s[16:17]
	s_addc_u32 s27, s27, 0
	s_add_i32 s42, s48, s23
	global_load_lds_dwordx4 v[178:179], off
	v_lshl_add_u64 v[178:179], s[26:27], 0, v[180:181]
	s_mov_b32 m0, s42
	s_nop 0
	global_load_lds_dwordx4 v[178:179], off
	v_lshl_add_u64 v[178:179], s[26:27], 0, v[196:197]
	s_add_i32 m0, s42, 0x2000
	s_nop 0
	global_load_lds_dwordx4 v[178:179], off
	v_lshl_add_u64 v[178:179], v[246:247], 0, s[16:17]
	s_mov_b32 m0, s54
	s_nop 0
	global_load_lds_dwordx4 v[178:179], off
	v_lshl_add_u64 v[178:179], v[248:249], 0, s[16:17]
	s_mov_b32 m0, s55
	s_nop 0
	global_load_lds_dwordx4 v[178:179], off
	s_waitcnt vmcnt(8)
	s_waitcnt lgkmcnt(0)
	s_setprio 1
	s_barrier
	v_mfma_f32_16x16x32_bf16 v[94:97], v[114:117], v[166:169], v[94:97]
	v_mfma_f32_16x16x32_bf16 v[30:33], v[122:125], v[166:169], v[30:33]
	v_mfma_f32_16x16x32_bf16 v[86:89], v[114:117], v[174:177], v[86:89]
	v_mfma_f32_16x16x32_bf16 v[22:25], v[122:125], v[174:177], v[22:25]
	v_mfma_f32_16x16x32_bf16 v[78:81], v[114:117], v[210:213], v[78:81]
	v_mfma_f32_16x16x32_bf16 v[14:17], v[122:125], v[210:213], v[14:17]
	v_mfma_f32_16x16x32_bf16 v[70:73], v[114:117], v[218:221], v[70:73]
	v_mfma_f32_16x16x32_bf16 v[6:9], v[122:125], v[218:221], v[6:9]
	v_mfma_f32_16x16x32_bf16 v[94:97], v[118:121], v[170:173], v[94:97]
	v_mfma_f32_16x16x32_bf16 v[30:33], v[146:149], v[170:173], v[30:33]
	v_mfma_f32_16x16x32_bf16 v[86:89], v[118:121], v[206:209], v[86:89]
	v_mfma_f32_16x16x32_bf16 v[22:25], v[146:149], v[206:209], v[22:25]
	v_mfma_f32_16x16x32_bf16 v[78:81], v[118:121], v[214:217], v[78:81]
	v_mfma_f32_16x16x32_bf16 v[14:17], v[146:149], v[214:217], v[14:17]
	v_mfma_f32_16x16x32_bf16 v[70:73], v[118:121], v[242:245], v[70:73]
	v_mfma_f32_16x16x32_bf16 v[6:9], v[146:149], v[242:245], v[6:9]
	v_mfma_f32_16x16x32_bf16 v[90:93], v[150:153], v[166:169], v[90:93]
	v_mfma_f32_16x16x32_bf16 v[26:29], v[158:161], v[166:169], v[26:29]
	v_mfma_f32_16x16x32_bf16 v[82:85], v[150:153], v[174:177], v[82:85]
	v_mfma_f32_16x16x32_bf16 v[18:21], v[158:161], v[174:177], v[18:21]
	v_mfma_f32_16x16x32_bf16 v[74:77], v[150:153], v[210:213], v[74:77]
	v_mfma_f32_16x16x32_bf16 v[10:13], v[158:161], v[210:213], v[10:13]
	v_mfma_f32_16x16x32_bf16 v[66:69], v[150:153], v[218:221], v[66:69]
	v_mfma_f32_16x16x32_bf16 v[2:5], v[158:161], v[218:221], v[2:5]
	v_mfma_f32_16x16x32_bf16 v[90:93], v[154:157], v[170:173], v[90:93]
	v_mfma_f32_16x16x32_bf16 v[26:29], v[162:165], v[170:173], v[26:29]
	v_mfma_f32_16x16x32_bf16 v[82:85], v[154:157], v[206:209], v[82:85]
	v_mfma_f32_16x16x32_bf16 v[18:21], v[162:165], v[206:209], v[18:21]
	v_mfma_f32_16x16x32_bf16 v[74:77], v[154:157], v[214:217], v[74:77]
	v_mfma_f32_16x16x32_bf16 v[10:13], v[162:165], v[214:217], v[10:13]
	v_mfma_f32_16x16x32_bf16 v[66:69], v[154:157], v[242:245], v[66:69]
	v_mfma_f32_16x16x32_bf16 v[2:5], v[162:165], v[242:245], v[2:5]
	s_barrier
	s_setprio 0
	s_add_i32 s46, s46, 2
	s_add_u32 s40, s40, 0x100
	s_addc_u32 s41, s41, 0
	s_add_u32 s37, s37, 0x100
	s_addc_u32 s39, s39, 0
	s_cmp_gt_u32 s46, 29
	s_cbranch_scc1 .LBB0_1688

.LBB0_1761:
	s_add_u32 s26, s38, 0xfff80080
	s_addc_u32 s27, s39, -1
	s_add_i32 s64, 0, 0x10000
	s_cmp_eq_u32 s63, 28
	s_cselect_b32 s41, s57, s27
	s_cselect_b32 s40, s58, s26
	v_add_u32_e32 v155, s64, v153
	s_cselect_b32 s27, s59, s62
	s_cselect_b32 s26, s60, s61
	s_add_i32 s68, 0, 0x14000
	ds_read_b128 v[138:141], v155
	ds_read_b128 v[142:145], v155 offset:1024
	ds_read_b128 v[146:149], v155 offset:2048
	ds_read_b128 v[156:159], v155 offset:3072
	v_add_u32_e32 v155, s68, v153
	ds_read_b128 v[160:163], v155
	ds_read_b128 v[164:167], v155 offset:1024
	ds_read_b128 v[168:171], v155 offset:2048
	ds_read_b128 v[172:175], v155 offset:3072
	v_lshl_add_u64 v[220:221], s[38:39], 0, v[134:135]
	s_add_i32 m0, s3, 0xc000
	ds_read_b128 v[176:179], v154
	ds_read_b128 v[192:195], v154 offset:1024
	ds_read_b128 v[196:199], v154 offset:2048
	ds_read_b128 v[200:203], v154 offset:3072
	ds_read_b128 v[204:207], v154 offset:4096
	ds_read_b128 v[208:211], v154 offset:5120
	ds_read_b128 v[212:215], v154 offset:6144
	ds_read_b128 v[216:219], v154 offset:7168
	global_load_lds_dwordx4 v[220:221], off
	v_lshl_add_u64 v[220:221], s[38:39], 0, v[136:137]
	s_add_i32 m0, s3, 0xe000
	s_nop 0
	global_load_lds_dwordx4 v[220:221], off
	s_waitcnt vmcnt(8)
	s_waitcnt lgkmcnt(0)
	s_setprio 1
	s_barrier
	v_mfma_f32_16x16x32_bf16 v[126:129], v[138:141], v[176:179], v[126:129]
	v_mfma_f32_16x16x32_bf16 v[122:125], v[146:149], v[176:179], v[122:125]
	v_mfma_f32_16x16x32_bf16 v[110:113], v[138:141], v[196:199], v[110:113]
	v_mfma_f32_16x16x32_bf16 v[106:109], v[146:149], v[196:199], v[106:109]
	v_mfma_f32_16x16x32_bf16 v[94:97], v[138:141], v[204:207], v[94:97]
	v_mfma_f32_16x16x32_bf16 v[90:93], v[146:149], v[204:207], v[90:93]
	v_mfma_f32_16x16x32_bf16 v[78:81], v[138:141], v[212:215], v[78:81]
	v_mfma_f32_16x16x32_bf16 v[74:77], v[146:149], v[212:215], v[74:77]
	v_mfma_f32_16x16x32_bf16 v[126:129], v[142:145], v[192:195], v[126:129]
	v_mfma_f32_16x16x32_bf16 v[122:125], v[156:159], v[192:195], v[122:125]
	v_mfma_f32_16x16x32_bf16 v[110:113], v[142:145], v[200:203], v[110:113]
	v_mfma_f32_16x16x32_bf16 v[106:109], v[156:159], v[200:203], v[106:109]
	v_mfma_f32_16x16x32_bf16 v[94:97], v[142:145], v[208:211], v[94:97]
	v_mfma_f32_16x16x32_bf16 v[90:93], v[156:159], v[208:211], v[90:93]
	v_mfma_f32_16x16x32_bf16 v[78:81], v[142:145], v[216:219], v[78:81]
	v_mfma_f32_16x16x32_bf16 v[74:77], v[156:159], v[216:219], v[74:77]
	v_mfma_f32_16x16x32_bf16 v[118:121], v[160:163], v[176:179], v[118:121]
	v_mfma_f32_16x16x32_bf16 v[114:117], v[168:171], v[176:179], v[114:117]
	v_mfma_f32_16x16x32_bf16 v[102:105], v[160:163], v[196:199], v[102:105]
	v_mfma_f32_16x16x32_bf16 v[98:101], v[168:171], v[196:199], v[98:101]
	v_mfma_f32_16x16x32_bf16 v[86:89], v[160:163], v[204:207], v[86:89]
	v_mfma_f32_16x16x32_bf16 v[82:85], v[168:171], v[204:207], v[82:85]
	v_mfma_f32_16x16x32_bf16 v[70:73], v[160:163], v[212:215], v[70:73]
	v_mfma_f32_16x16x32_bf16 v[66:69], v[168:171], v[212:215], v[66:69]
	v_mfma_f32_16x16x32_bf16 v[118:121], v[164:167], v[192:195], v[118:121]
	v_mfma_f32_16x16x32_bf16 v[114:117], v[172:175], v[192:195], v[114:117]
	v_mfma_f32_16x16x32_bf16 v[102:105], v[164:167], v[200:203], v[102:105]
	v_mfma_f32_16x16x32_bf16 v[98:101], v[172:175], v[200:203], v[98:101]
	v_mfma_f32_16x16x32_bf16 v[86:89], v[164:167], v[208:211], v[86:89]
	v_mfma_f32_16x16x32_bf16 v[82:85], v[172:175], v[208:211], v[82:85]
	v_mfma_f32_16x16x32_bf16 v[70:73], v[164:167], v[216:219], v[70:73]
	v_mfma_f32_16x16x32_bf16 v[66:69], v[172:175], v[216:219], v[66:69]
	s_barrier
	s_setprio 0
	s_add_i32 s64, s64, s43
	v_lshl_add_u64 v[220:221], s[26:27], 0, v[132:133]
	s_mov_b32 m0, s64
	ds_read_b128 v[176:179], v154 offset:16384
	ds_read_b128 v[192:195], v154 offset:17408
	ds_read_b128 v[196:199], v154 offset:18432
	ds_read_b128 v[200:203], v154 offset:19456
	ds_read_b128 v[204:207], v154 offset:20480
	ds_read_b128 v[208:211], v154 offset:21504
	ds_read_b128 v[212:215], v154 offset:22528
	ds_read_b128 v[216:219], v154 offset:23552
	global_load_lds_dwordx4 v[220:221], off
	s_add_i32 m0, s64, 0x2000
	s_add_u32 s66, s26, 0x80000
	v_lshl_add_u64 v[222:223], s[26:27], 0, v[130:131]
	s_addc_u32 s67, s27, 0
	s_add_i32 s64, s68, s43
	global_load_lds_dwordx4 v[222:223], off
	v_lshl_add_u64 v[238:239], s[66:67], 0, v[132:133]
	s_mov_b32 m0, s64
	v_lshl_add_u64 v[240:241], s[40:41], 0, v[130:131]
	global_load_lds_dwordx4 v[238:239], off
	v_lshl_add_u64 v[238:239], s[66:67], 0, v[130:131]
	s_add_i32 m0, s64, 0x2000
	s_nop 0
	global_load_lds_dwordx4 v[238:239], off
	v_lshl_add_u64 v[238:239], s[40:41], 0, v[132:133]
	s_mov_b32 m0, s3
	s_nop 0
	global_load_lds_dwordx4 v[238:239], off
	s_mov_b32 m0, s45
	s_nop 0
	global_load_lds_dwordx4 v[240:241], off
	s_waitcnt vmcnt(8)
	s_waitcnt lgkmcnt(0)
	s_setprio 1
	s_barrier
	v_mfma_f32_16x16x32_bf16 v[62:65], v[138:141], v[176:179], v[62:65]
	v_mfma_f32_16x16x32_bf16 v[58:61], v[146:149], v[176:179], v[58:61]
	v_mfma_f32_16x16x32_bf16 v[46:49], v[138:141], v[196:199], v[46:49]
	v_mfma_f32_16x16x32_bf16 v[42:45], v[146:149], v[196:199], v[42:45]
	v_mfma_f32_16x16x32_bf16 v[30:33], v[138:141], v[204:207], v[30:33]
	v_mfma_f32_16x16x32_bf16 v[26:29], v[146:149], v[204:207], v[26:29]
	v_mfma_f32_16x16x32_bf16 v[14:17], v[138:141], v[212:215], v[14:17]
	v_mfma_f32_16x16x32_bf16 v[10:13], v[146:149], v[212:215], v[10:13]
	v_mfma_f32_16x16x32_bf16 v[62:65], v[142:145], v[192:195], v[62:65]
	v_mfma_f32_16x16x32_bf16 v[58:61], v[156:159], v[192:195], v[58:61]
	v_mfma_f32_16x16x32_bf16 v[46:49], v[142:145], v[200:203], v[46:49]
	v_mfma_f32_16x16x32_bf16 v[42:45], v[156:159], v[200:203], v[42:45]
	v_mfma_f32_16x16x32_bf16 v[30:33], v[142:145], v[208:211], v[30:33]
	v_mfma_f32_16x16x32_bf16 v[26:29], v[156:159], v[208:211], v[26:29]
	v_mfma_f32_16x16x32_bf16 v[14:17], v[142:145], v[216:219], v[14:17]
	v_mfma_f32_16x16x32_bf16 v[10:13], v[156:159], v[216:219], v[10:13]
	v_mfma_f32_16x16x32_bf16 v[54:57], v[160:163], v[176:179], v[54:57]
	v_mfma_f32_16x16x32_bf16 v[50:53], v[168:171], v[176:179], v[50:53]
	v_mfma_f32_16x16x32_bf16 v[38:41], v[160:163], v[196:199], v[38:41]
	v_mfma_f32_16x16x32_bf16 v[34:37], v[168:171], v[196:199], v[34:37]
	v_mfma_f32_16x16x32_bf16 v[22:25], v[160:163], v[204:207], v[22:25]
	v_mfma_f32_16x16x32_bf16 v[18:21], v[168:171], v[204:207], v[18:21]
	v_mfma_f32_16x16x32_bf16 v[6:9], v[160:163], v[212:215], v[6:9]
	v_mfma_f32_16x16x32_bf16 v[2:5], v[168:171], v[212:215], v[2:5]
	v_mfma_f32_16x16x32_bf16 v[54:57], v[164:167], v[192:195], v[54:57]
	v_mfma_f32_16x16x32_bf16 v[50:53], v[172:175], v[192:195], v[50:53]
	v_mfma_f32_16x16x32_bf16 v[38:41], v[164:167], v[200:203], v[38:41]
	v_mfma_f32_16x16x32_bf16 v[34:37], v[172:175], v[200:203], v[34:37]
	v_mfma_f32_16x16x32_bf16 v[22:25], v[164:167], v[208:211], v[22:25]
	v_mfma_f32_16x16x32_bf16 v[18:21], v[172:175], v[208:211], v[18:21]
	v_mfma_f32_16x16x32_bf16 v[6:9], v[164:167], v[216:219], v[6:9]
	v_mfma_f32_16x16x32_bf16 v[2:5], v[172:175], v[216:219], v[2:5]
	s_barrier
	s_setprio 0
	s_add_i32 s64, 0, 0x18000
	v_add_u32_e32 v155, s64, v153
	s_add_i32 s66, 0, 0x1c000
	ds_read_b128 v[138:141], v155
	ds_read_b128 v[142:145], v155 offset:1024
	ds_read_b128 v[146:149], v155 offset:2048
	ds_read_b128 v[156:159], v155 offset:3072
	v_add_u32_e32 v155, s66, v153
	ds_read_b128 v[160:163], v155
	ds_read_b128 v[164:167], v155 offset:1024
	ds_read_b128 v[168:171], v155 offset:2048
	ds_read_b128 v[172:175], v155 offset:3072
	s_add_u32 s40, s40, 0x80000
	s_addc_u32 s41, s41, 0
	s_mov_b32 m0, s46
	v_lshl_add_u64 v[242:243], s[40:41], 0, v[132:133]
	ds_read_b128 v[176:179], v154 offset:32768
	ds_read_b128 v[192:195], v154 offset:33792
	ds_read_b128 v[196:199], v154 offset:34816
	ds_read_b128 v[200:203], v154 offset:35840
	ds_read_b128 v[204:207], v154 offset:36864
	ds_read_b128 v[208:211], v154 offset:37888
	ds_read_b128 v[212:215], v154 offset:38912
	ds_read_b128 v[216:219], v154 offset:39936
	global_load_lds_dwordx4 v[242:243], off
	v_lshl_add_u64 v[242:243], s[40:41], 0, v[130:131]
	s_mov_b32 m0, s47
	s_nop 0
	global_load_lds_dwordx4 v[242:243], off
	s_waitcnt vmcnt(8)
	s_waitcnt lgkmcnt(0)
	s_setprio 1
	s_barrier
	v_mfma_f32_16x16x32_bf16 v[126:129], v[138:141], v[176:179], v[126:129]
	v_mfma_f32_16x16x32_bf16 v[122:125], v[146:149], v[176:179], v[122:125]
	v_mfma_f32_16x16x32_bf16 v[110:113], v[138:141], v[196:199], v[110:113]
	v_mfma_f32_16x16x32_bf16 v[106:109], v[146:149], v[196:199], v[106:109]
	v_mfma_f32_16x16x32_bf16 v[94:97], v[138:141], v[204:207], v[94:97]
	v_mfma_f32_16x16x32_bf16 v[90:93], v[146:149], v[204:207], v[90:93]
	v_mfma_f32_16x16x32_bf16 v[78:81], v[138:141], v[212:215], v[78:81]
	v_mfma_f32_16x16x32_bf16 v[74:77], v[146:149], v[212:215], v[74:77]
	v_mfma_f32_16x16x32_bf16 v[126:129], v[142:145], v[192:195], v[126:129]
	v_mfma_f32_16x16x32_bf16 v[122:125], v[156:159], v[192:195], v[122:125]
	v_mfma_f32_16x16x32_bf16 v[110:113], v[142:145], v[200:203], v[110:113]
	v_mfma_f32_16x16x32_bf16 v[106:109], v[156:159], v[200:203], v[106:109]
	v_mfma_f32_16x16x32_bf16 v[94:97], v[142:145], v[208:211], v[94:97]
	v_mfma_f32_16x16x32_bf16 v[90:93], v[156:159], v[208:211], v[90:93]
	v_mfma_f32_16x16x32_bf16 v[78:81], v[142:145], v[216:219], v[78:81]
	v_mfma_f32_16x16x32_bf16 v[74:77], v[156:159], v[216:219], v[74:77]
	v_mfma_f32_16x16x32_bf16 v[118:121], v[160:163], v[176:179], v[118:121]
	v_mfma_f32_16x16x32_bf16 v[114:117], v[168:171], v[176:179], v[114:117]
	v_mfma_f32_16x16x32_bf16 v[102:105], v[160:163], v[196:199], v[102:105]
	v_mfma_f32_16x16x32_bf16 v[98:101], v[168:171], v[196:199], v[98:101]
	v_mfma_f32_16x16x32_bf16 v[86:89], v[160:163], v[204:207], v[86:89]
	v_mfma_f32_16x16x32_bf16 v[82:85], v[168:171], v[204:207], v[82:85]
	v_mfma_f32_16x16x32_bf16 v[70:73], v[160:163], v[212:215], v[70:73]
	v_mfma_f32_16x16x32_bf16 v[66:69], v[168:171], v[212:215], v[66:69]
	v_mfma_f32_16x16x32_bf16 v[118:121], v[164:167], v[192:195], v[118:121]
	v_mfma_f32_16x16x32_bf16 v[114:117], v[172:175], v[192:195], v[114:117]
	v_mfma_f32_16x16x32_bf16 v[102:105], v[164:167], v[200:203], v[102:105]
	v_mfma_f32_16x16x32_bf16 v[98:101], v[172:175], v[200:203], v[98:101]
	v_mfma_f32_16x16x32_bf16 v[86:89], v[164:167], v[208:211], v[86:89]
	v_mfma_f32_16x16x32_bf16 v[82:85], v[172:175], v[208:211], v[82:85]
	v_mfma_f32_16x16x32_bf16 v[70:73], v[164:167], v[216:219], v[70:73]
	v_mfma_f32_16x16x32_bf16 v[66:69], v[172:175], v[216:219], v[66:69]
	s_barrier
	s_setprio 0
	s_add_i32 s40, s64, s43
	v_lshl_add_u64 v[220:221], v[220:221], 0, s[16:17]
	s_mov_b32 m0, s40
	ds_read_b128 v[176:179], v154 offset:49152
	ds_read_b128 v[192:195], v154 offset:50176
	ds_read_b128 v[196:199], v154 offset:51200
	ds_read_b128 v[200:203], v154 offset:52224
	ds_read_b128 v[204:207], v154 offset:53248
	ds_read_b128 v[208:211], v154 offset:54272
	ds_read_b128 v[212:215], v154 offset:55296
	ds_read_b128 v[216:219], v154 offset:56320
	global_load_lds_dwordx4 v[220:221], off
	s_add_i32 m0, s40, 0x2000
	s_add_u32 s26, s26, 0x80080
	v_lshl_add_u64 v[220:221], v[222:223], 0, s[16:17]
	s_addc_u32 s27, s27, 0
	s_add_i32 s40, s66, s43
	global_load_lds_dwordx4 v[220:221], off
	v_lshl_add_u64 v[220:221], s[26:27], 0, v[132:133]
	s_mov_b32 m0, s40
	s_nop 0
	global_load_lds_dwordx4 v[220:221], off
	v_lshl_add_u64 v[220:221], s[26:27], 0, v[130:131]
	s_add_i32 m0, s40, 0x2000
	s_nop 0
	global_load_lds_dwordx4 v[220:221], off
	v_lshl_add_u64 v[220:221], v[238:239], 0, s[16:17]
	s_mov_b32 m0, s50
	s_nop 0
	global_load_lds_dwordx4 v[220:221], off
	v_lshl_add_u64 v[220:221], v[240:241], 0, s[16:17]
	s_mov_b32 m0, s51
	s_nop 0
	global_load_lds_dwordx4 v[220:221], off
	s_waitcnt vmcnt(8)
	s_waitcnt lgkmcnt(0)
	s_setprio 1
	s_barrier
	v_mfma_f32_16x16x32_bf16 v[62:65], v[138:141], v[176:179], v[62:65]
	v_mfma_f32_16x16x32_bf16 v[58:61], v[146:149], v[176:179], v[58:61]
	v_mfma_f32_16x16x32_bf16 v[46:49], v[138:141], v[196:199], v[46:49]
	v_mfma_f32_16x16x32_bf16 v[42:45], v[146:149], v[196:199], v[42:45]
	v_mfma_f32_16x16x32_bf16 v[30:33], v[138:141], v[204:207], v[30:33]
	v_mfma_f32_16x16x32_bf16 v[26:29], v[146:149], v[204:207], v[26:29]
	v_mfma_f32_16x16x32_bf16 v[14:17], v[138:141], v[212:215], v[14:17]
	v_mfma_f32_16x16x32_bf16 v[10:13], v[146:149], v[212:215], v[10:13]
	v_mfma_f32_16x16x32_bf16 v[62:65], v[142:145], v[192:195], v[62:65]
	v_mfma_f32_16x16x32_bf16 v[58:61], v[156:159], v[192:195], v[58:61]
	v_mfma_f32_16x16x32_bf16 v[46:49], v[142:145], v[200:203], v[46:49]
	v_mfma_f32_16x16x32_bf16 v[42:45], v[156:159], v[200:203], v[42:45]
	v_mfma_f32_16x16x32_bf16 v[30:33], v[142:145], v[208:211], v[30:33]
	v_mfma_f32_16x16x32_bf16 v[26:29], v[156:159], v[208:211], v[26:29]
	v_mfma_f32_16x16x32_bf16 v[14:17], v[142:145], v[216:219], v[14:17]
	v_mfma_f32_16x16x32_bf16 v[10:13], v[156:159], v[216:219], v[10:13]
	v_mfma_f32_16x16x32_bf16 v[54:57], v[160:163], v[176:179], v[54:57]
	v_mfma_f32_16x16x32_bf16 v[50:53], v[168:171], v[176:179], v[50:53]
	v_mfma_f32_16x16x32_bf16 v[38:41], v[160:163], v[196:199], v[38:41]
	v_mfma_f32_16x16x32_bf16 v[34:37], v[168:171], v[196:199], v[34:37]
	v_mfma_f32_16x16x32_bf16 v[22:25], v[160:163], v[204:207], v[22:25]
	v_mfma_f32_16x16x32_bf16 v[18:21], v[168:171], v[204:207], v[18:21]
	v_mfma_f32_16x16x32_bf16 v[6:9], v[160:163], v[212:215], v[6:9]
	v_mfma_f32_16x16x32_bf16 v[2:5], v[168:171], v[212:215], v[2:5]
	v_mfma_f32_16x16x32_bf16 v[54:57], v[164:167], v[192:195], v[54:57]
	v_mfma_f32_16x16x32_bf16 v[50:53], v[172:175], v[192:195], v[50:53]
	v_mfma_f32_16x16x32_bf16 v[38:41], v[164:167], v[200:203], v[38:41]
	v_mfma_f32_16x16x32_bf16 v[34:37], v[172:175], v[200:203], v[34:37]
	v_mfma_f32_16x16x32_bf16 v[22:25], v[164:167], v[208:211], v[22:25]
	v_mfma_f32_16x16x32_bf16 v[18:21], v[172:175], v[208:211], v[18:21]
	v_mfma_f32_16x16x32_bf16 v[6:9], v[164:167], v[216:219], v[6:9]
	v_mfma_f32_16x16x32_bf16 v[2:5], v[172:175], v[216:219], v[2:5]
	s_barrier
	s_setprio 0
	s_add_i32 s63, s63, 2
	s_add_u32 s38, s38, 0x100
	s_addc_u32 s39, s39, 0
	s_add_u32 s61, s61, 0x100
	s_addc_u32 s62, s62, 0
	s_cmp_gt_u32 s63, 29
	s_cbranch_scc0 .LBB0_1761
	s_and_b64 vcc, exec, s[34:35]
	s_cbranch_vccz .LBB0_1764
	s_barrier

.LBB0_2241:
	s_add_u32 s28, s26, 0x100
	s_addc_u32 s29, s27, 0
	s_add_i32 s58, 0, 0x10000
	s_cmpk_eq_i32 s57, 0x52
	s_cselect_b32 s35, s23, s29
	s_cselect_b32 s34, s22, s28
	s_cselect_b32 s31, s25, s39
	s_cselect_b32 s30, s24, s38
	s_add_i32 s59, 0, 0x14000
	v_add_u32_e32 v166, s58, v156
	v_add_u32_e32 v178, s59, v156
	ds_read_b128 v[148:151], v166
	ds_read_b128 v[158:161], v166 offset:1024
	ds_read_b128 v[162:165], v166 offset:2048
	ds_read_b128 v[166:169], v166 offset:3072
	ds_read_b128 v[170:173], v178
	ds_read_b128 v[174:177], v178 offset:1024
	ds_read_b128 v[190:193], v178 offset:2048
	ds_read_b128 v[194:197], v178 offset:3072
	v_lshl_add_u64 v[178:179], s[26:27], 0, v[144:145]
	s_add_i32 m0, s43, 0xc000
	ds_read_b128 v[198:201], v157
	ds_read_b128 v[202:205], v157 offset:1024
	ds_read_b128 v[206:209], v157 offset:2048
	ds_read_b128 v[210:213], v157 offset:3072
	ds_read_b128 v[214:217], v157 offset:4096
	ds_read_b128 v[218:221], v157 offset:5120
	ds_read_b128 v[238:241], v157 offset:6144
	ds_read_b128 v[242:245], v157 offset:7168
	global_load_lds_dwordx4 v[178:179], off
	v_lshl_add_u64 v[178:179], s[26:27], 0, v[146:147]
	s_add_i32 m0, s43, 0xe000
	s_nop 0
	global_load_lds_dwordx4 v[178:179], off
	s_waitcnt vmcnt(8)
	s_waitcnt lgkmcnt(0)
	s_setprio 1
	s_barrier
	v_mfma_f32_16x16x32_bf16 v[126:129], v[148:151], v[198:201], v[126:129]
	v_mfma_f32_16x16x32_bf16 v[114:117], v[162:165], v[198:201], v[114:117]
	v_mfma_f32_16x16x32_bf16 v[106:109], v[148:151], v[206:209], v[106:109]
	v_mfma_f32_16x16x32_bf16 v[98:101], v[162:165], v[206:209], v[98:101]
	v_mfma_f32_16x16x32_bf16 v[90:93], v[148:151], v[214:217], v[90:93]
	v_mfma_f32_16x16x32_bf16 v[82:85], v[162:165], v[214:217], v[82:85]
	v_mfma_f32_16x16x32_bf16 v[74:77], v[148:151], v[238:241], v[74:77]
	v_mfma_f32_16x16x32_bf16 v[54:57], v[162:165], v[238:241], v[54:57]
	v_mfma_f32_16x16x32_bf16 v[126:129], v[158:161], v[202:205], v[126:129]
	v_mfma_f32_16x16x32_bf16 v[114:117], v[166:169], v[202:205], v[114:117]
	v_mfma_f32_16x16x32_bf16 v[106:109], v[158:161], v[210:213], v[106:109]
	v_mfma_f32_16x16x32_bf16 v[98:101], v[166:169], v[210:213], v[98:101]
	v_mfma_f32_16x16x32_bf16 v[90:93], v[158:161], v[218:221], v[90:93]
	v_mfma_f32_16x16x32_bf16 v[82:85], v[166:169], v[218:221], v[82:85]
	v_mfma_f32_16x16x32_bf16 v[74:77], v[158:161], v[242:245], v[74:77]
	v_mfma_f32_16x16x32_bf16 v[54:57], v[166:169], v[242:245], v[54:57]
	v_mfma_f32_16x16x32_bf16 v[118:121], v[170:173], v[198:201], v[118:121]
	v_mfma_f32_16x16x32_bf16 v[122:125], v[190:193], v[198:201], v[122:125]
	v_mfma_f32_16x16x32_bf16 v[102:105], v[170:173], v[206:209], v[102:105]
	v_mfma_f32_16x16x32_bf16 v[110:113], v[190:193], v[206:209], v[110:113]
	v_mfma_f32_16x16x32_bf16 v[86:89], v[170:173], v[214:217], v[86:89]
	v_mfma_f32_16x16x32_bf16 v[94:97], v[190:193], v[214:217], v[94:97]
	v_mfma_f32_16x16x32_bf16 v[70:73], v[170:173], v[238:241], v[70:73]
	v_mfma_f32_16x16x32_bf16 v[78:81], v[190:193], v[238:241], v[78:81]
	v_mfma_f32_16x16x32_bf16 v[118:121], v[174:177], v[202:205], v[118:121]
	v_mfma_f32_16x16x32_bf16 v[122:125], v[194:197], v[202:205], v[122:125]
	v_mfma_f32_16x16x32_bf16 v[102:105], v[174:177], v[210:213], v[102:105]
	v_mfma_f32_16x16x32_bf16 v[110:113], v[194:197], v[210:213], v[110:113]
	v_mfma_f32_16x16x32_bf16 v[86:89], v[174:177], v[218:221], v[86:89]
	v_mfma_f32_16x16x32_bf16 v[94:97], v[194:197], v[218:221], v[94:97]
	v_mfma_f32_16x16x32_bf16 v[70:73], v[174:177], v[242:245], v[70:73]
	v_mfma_f32_16x16x32_bf16 v[78:81], v[194:197], v[242:245], v[78:81]
	s_barrier
	s_setprio 0
	s_add_i32 s26, s58, s40
	v_lshl_add_u64 v[178:179], s[30:31], 0, v[136:137]
	s_mov_b32 m0, s26
	ds_read_b128 v[198:201], v157 offset:16384
	ds_read_b128 v[202:205], v157 offset:17408
	ds_read_b128 v[206:209], v157 offset:18432
	ds_read_b128 v[210:213], v157 offset:19456
	ds_read_b128 v[214:217], v157 offset:20480
	ds_read_b128 v[218:221], v157 offset:21504
	ds_read_b128 v[238:241], v157 offset:22528
	ds_read_b128 v[242:245], v157 offset:23552
	global_load_lds_dwordx4 v[178:179], off
	s_add_i32 m0, s26, 0x2000
	s_add_u32 s26, s30, 0x158000
	v_lshl_add_u64 v[222:223], s[30:31], 0, v[140:141]
	s_addc_u32 s27, s31, 0
	s_add_i32 s58, s59, s40
	global_load_lds_dwordx4 v[222:223], off
	v_lshl_add_u64 v[246:247], s[26:27], 0, v[136:137]
	s_mov_b32 m0, s58
	v_lshl_add_u64 v[248:249], s[34:35], 0, v[138:139]
	global_load_lds_dwordx4 v[246:247], off
	v_lshl_add_u64 v[246:247], s[26:27], 0, v[140:141]
	s_add_i32 m0, s58, 0x2000
	s_nop 0
	global_load_lds_dwordx4 v[246:247], off
	v_lshl_add_u64 v[246:247], s[34:35], 0, v[134:135]
	s_mov_b32 m0, s43
	s_nop 0
	global_load_lds_dwordx4 v[246:247], off
	s_mov_b32 m0, s44
	s_nop 0
	global_load_lds_dwordx4 v[248:249], off
	s_waitcnt vmcnt(8)
	s_waitcnt lgkmcnt(0)
	s_setprio 1
	s_barrier
	v_mfma_f32_16x16x32_bf16 v[50:53], v[148:151], v[198:201], v[50:53]
	v_mfma_f32_16x16x32_bf16 v[38:41], v[162:165], v[198:201], v[38:41]
	v_mfma_f32_16x16x32_bf16 v[22:25], v[148:151], v[206:209], v[22:25]
	v_mfma_f32_16x16x32_bf16 v[42:45], v[162:165], v[206:209], v[42:45]
	v_mfma_f32_16x16x32_bf16 v[30:33], v[148:151], v[214:217], v[30:33]
	v_mfma_f32_16x16x32_bf16 v[18:21], v[162:165], v[214:217], v[18:21]
	v_mfma_f32_16x16x32_bf16 v[10:13], v[148:151], v[238:241], v[10:13]
	v_mfma_f32_16x16x32_bf16 v[2:5], v[162:165], v[238:241], v[2:5]
	v_mfma_f32_16x16x32_bf16 v[50:53], v[158:161], v[202:205], v[50:53]
	v_mfma_f32_16x16x32_bf16 v[38:41], v[166:169], v[202:205], v[38:41]
	v_mfma_f32_16x16x32_bf16 v[22:25], v[158:161], v[210:213], v[22:25]
	v_mfma_f32_16x16x32_bf16 v[42:45], v[166:169], v[210:213], v[42:45]
	v_mfma_f32_16x16x32_bf16 v[30:33], v[158:161], v[218:221], v[30:33]
	v_mfma_f32_16x16x32_bf16 v[18:21], v[166:169], v[218:221], v[18:21]
	v_mfma_f32_16x16x32_bf16 v[10:13], v[158:161], v[242:245], v[10:13]
	v_mfma_f32_16x16x32_bf16 v[2:5], v[166:169], v[242:245], v[2:5]
	v_mfma_f32_16x16x32_bf16 v[46:49], v[170:173], v[198:201], v[46:49]
	v_mfma_f32_16x16x32_bf16 v[58:61], v[190:193], v[198:201], v[58:61]
	v_mfma_f32_16x16x32_bf16 v[62:65], v[170:173], v[206:209], v[62:65]
	v_mfma_f32_16x16x32_bf16 v[66:69], v[190:193], v[206:209], v[66:69]
	v_mfma_f32_16x16x32_bf16 v[26:29], v[170:173], v[214:217], v[26:29]
	v_mfma_f32_16x16x32_bf16 v[34:37], v[190:193], v[214:217], v[34:37]
	v_mfma_f32_16x16x32_bf16 v[6:9], v[170:173], v[238:241], v[6:9]
	v_mfma_f32_16x16x32_bf16 v[14:17], v[190:193], v[238:241], v[14:17]
	v_mfma_f32_16x16x32_bf16 v[46:49], v[174:177], v[202:205], v[46:49]
	v_mfma_f32_16x16x32_bf16 v[58:61], v[194:197], v[202:205], v[58:61]
	v_mfma_f32_16x16x32_bf16 v[62:65], v[174:177], v[210:213], v[62:65]
	v_mfma_f32_16x16x32_bf16 v[66:69], v[194:197], v[210:213], v[66:69]
	v_mfma_f32_16x16x32_bf16 v[26:29], v[174:177], v[218:221], v[26:29]
	v_mfma_f32_16x16x32_bf16 v[34:37], v[194:197], v[218:221], v[34:37]
	v_mfma_f32_16x16x32_bf16 v[6:9], v[174:177], v[242:245], v[6:9]
	v_mfma_f32_16x16x32_bf16 v[14:17], v[194:197], v[242:245], v[14:17]
	s_barrier
	s_setprio 0
	s_add_i32 s58, 0, 0x18000
	s_add_i32 s59, 0, 0x1c000
	v_add_u32_e32 v166, s58, v156
	v_add_u32_e32 v194, s59, v156
	ds_read_b128 v[148:151], v166
	ds_read_b128 v[158:161], v166 offset:1024
	ds_read_b128 v[162:165], v166 offset:2048
	ds_read_b128 v[166:169], v166 offset:3072
	ds_read_b128 v[170:173], v194
	ds_read_b128 v[174:177], v194 offset:1024
	ds_read_b128 v[190:193], v194 offset:2048
	ds_read_b128 v[194:197], v194 offset:3072
	s_add_u32 s26, s34, 0x158000
	s_addc_u32 s27, s35, 0
	s_mov_b32 m0, s45
	v_lshl_add_u64 v[250:251], s[26:27], 0, v[134:135]
	ds_read_b128 v[198:201], v157 offset:32768
	ds_read_b128 v[202:205], v157 offset:33792
	ds_read_b128 v[206:209], v157 offset:34816
	ds_read_b128 v[210:213], v157 offset:35840
	ds_read_b128 v[214:217], v157 offset:36864
	ds_read_b128 v[218:221], v157 offset:37888
	ds_read_b128 v[238:241], v157 offset:38912
	ds_read_b128 v[242:245], v157 offset:39936
	global_load_lds_dwordx4 v[250:251], off
	v_lshl_add_u64 v[250:251], s[26:27], 0, v[138:139]
	s_mov_b32 m0, s47
	s_nop 0
	global_load_lds_dwordx4 v[250:251], off
	s_waitcnt vmcnt(8)
	s_waitcnt lgkmcnt(0)
	s_setprio 1
	s_barrier
	v_mfma_f32_16x16x32_bf16 v[126:129], v[148:151], v[198:201], v[126:129]
	v_mfma_f32_16x16x32_bf16 v[114:117], v[162:165], v[198:201], v[114:117]
	v_mfma_f32_16x16x32_bf16 v[106:109], v[148:151], v[206:209], v[106:109]
	v_mfma_f32_16x16x32_bf16 v[98:101], v[162:165], v[206:209], v[98:101]
	v_mfma_f32_16x16x32_bf16 v[90:93], v[148:151], v[214:217], v[90:93]
	v_mfma_f32_16x16x32_bf16 v[82:85], v[162:165], v[214:217], v[82:85]
	v_mfma_f32_16x16x32_bf16 v[74:77], v[148:151], v[238:241], v[74:77]
	v_mfma_f32_16x16x32_bf16 v[54:57], v[162:165], v[238:241], v[54:57]
	v_mfma_f32_16x16x32_bf16 v[126:129], v[158:161], v[202:205], v[126:129]
	v_mfma_f32_16x16x32_bf16 v[114:117], v[166:169], v[202:205], v[114:117]
	v_mfma_f32_16x16x32_bf16 v[106:109], v[158:161], v[210:213], v[106:109]
	v_mfma_f32_16x16x32_bf16 v[98:101], v[166:169], v[210:213], v[98:101]
	v_mfma_f32_16x16x32_bf16 v[90:93], v[158:161], v[218:221], v[90:93]
	v_mfma_f32_16x16x32_bf16 v[82:85], v[166:169], v[218:221], v[82:85]
	v_mfma_f32_16x16x32_bf16 v[74:77], v[158:161], v[242:245], v[74:77]
	v_mfma_f32_16x16x32_bf16 v[54:57], v[166:169], v[242:245], v[54:57]
	v_mfma_f32_16x16x32_bf16 v[118:121], v[170:173], v[198:201], v[118:121]
	v_mfma_f32_16x16x32_bf16 v[122:125], v[190:193], v[198:201], v[122:125]
	v_mfma_f32_16x16x32_bf16 v[102:105], v[170:173], v[206:209], v[102:105]
	v_mfma_f32_16x16x32_bf16 v[110:113], v[190:193], v[206:209], v[110:113]
	v_mfma_f32_16x16x32_bf16 v[86:89], v[170:173], v[214:217], v[86:89]
	v_mfma_f32_16x16x32_bf16 v[94:97], v[190:193], v[214:217], v[94:97]
	v_mfma_f32_16x16x32_bf16 v[70:73], v[170:173], v[238:241], v[70:73]
	v_mfma_f32_16x16x32_bf16 v[78:81], v[190:193], v[238:241], v[78:81]
	v_mfma_f32_16x16x32_bf16 v[118:121], v[174:177], v[202:205], v[118:121]
	v_mfma_f32_16x16x32_bf16 v[122:125], v[194:197], v[202:205], v[122:125]
	v_mfma_f32_16x16x32_bf16 v[102:105], v[174:177], v[210:213], v[102:105]
	v_mfma_f32_16x16x32_bf16 v[110:113], v[194:197], v[210:213], v[110:113]
	v_mfma_f32_16x16x32_bf16 v[86:89], v[174:177], v[218:221], v[86:89]
	v_mfma_f32_16x16x32_bf16 v[94:97], v[194:197], v[218:221], v[94:97]
	v_mfma_f32_16x16x32_bf16 v[70:73], v[174:177], v[242:245], v[70:73]
	v_mfma_f32_16x16x32_bf16 v[78:81], v[194:197], v[242:245], v[78:81]
	s_barrier
	s_setprio 0
	s_add_i32 s26, s58, s40
	v_lshl_add_u64 v[178:179], v[178:179], 0, s[16:17]
	s_mov_b32 m0, s26
	ds_read_b128 v[198:201], v157 offset:49152
	ds_read_b128 v[202:205], v157 offset:50176
	ds_read_b128 v[206:209], v157 offset:51200
	ds_read_b128 v[210:213], v157 offset:52224
	ds_read_b128 v[214:217], v157 offset:53248
	ds_read_b128 v[218:221], v157 offset:54272
	ds_read_b128 v[238:241], v157 offset:55296
	ds_read_b128 v[242:245], v157 offset:56320
	global_load_lds_dwordx4 v[178:179], off
	s_add_i32 m0, s26, 0x2000
	s_add_u32 s26, s30, 0x158080
	v_lshl_add_u64 v[178:179], v[222:223], 0, s[16:17]
	s_addc_u32 s27, s31, 0
	s_add_i32 s30, s59, s40
	global_load_lds_dwordx4 v[178:179], off
	v_lshl_add_u64 v[178:179], s[26:27], 0, v[136:137]
	s_mov_b32 m0, s30
	s_nop 0
	global_load_lds_dwordx4 v[178:179], off
	v_lshl_add_u64 v[178:179], s[26:27], 0, v[140:141]
	s_add_i32 m0, s30, 0x2000
	s_nop 0
	global_load_lds_dwordx4 v[178:179], off
	v_lshl_add_u64 v[178:179], v[246:247], 0, s[16:17]
	s_mov_b32 m0, s48
	s_nop 0
	global_load_lds_dwordx4 v[178:179], off
	v_lshl_add_u64 v[178:179], v[248:249], 0, s[16:17]
	s_mov_b32 m0, s49
	s_nop 0
	global_load_lds_dwordx4 v[178:179], off
	s_waitcnt vmcnt(8)
	s_waitcnt lgkmcnt(0)
	s_setprio 1
	s_barrier
	v_mfma_f32_16x16x32_bf16 v[50:53], v[148:151], v[198:201], v[50:53]
	v_mfma_f32_16x16x32_bf16 v[38:41], v[162:165], v[198:201], v[38:41]
	v_mfma_f32_16x16x32_bf16 v[22:25], v[148:151], v[206:209], v[22:25]
	v_mfma_f32_16x16x32_bf16 v[42:45], v[162:165], v[206:209], v[42:45]
	v_mfma_f32_16x16x32_bf16 v[30:33], v[148:151], v[214:217], v[30:33]
	v_mfma_f32_16x16x32_bf16 v[18:21], v[162:165], v[214:217], v[18:21]
	v_mfma_f32_16x16x32_bf16 v[10:13], v[148:151], v[238:241], v[10:13]
	v_mfma_f32_16x16x32_bf16 v[2:5], v[162:165], v[238:241], v[2:5]
	v_mfma_f32_16x16x32_bf16 v[50:53], v[158:161], v[202:205], v[50:53]
	v_mfma_f32_16x16x32_bf16 v[38:41], v[166:169], v[202:205], v[38:41]
	v_mfma_f32_16x16x32_bf16 v[22:25], v[158:161], v[210:213], v[22:25]
	v_mfma_f32_16x16x32_bf16 v[42:45], v[166:169], v[210:213], v[42:45]
	v_mfma_f32_16x16x32_bf16 v[30:33], v[158:161], v[218:221], v[30:33]
	v_mfma_f32_16x16x32_bf16 v[18:21], v[166:169], v[218:221], v[18:21]
	v_mfma_f32_16x16x32_bf16 v[10:13], v[158:161], v[242:245], v[10:13]
	v_mfma_f32_16x16x32_bf16 v[2:5], v[166:169], v[242:245], v[2:5]
	v_mfma_f32_16x16x32_bf16 v[46:49], v[170:173], v[198:201], v[46:49]
	v_mfma_f32_16x16x32_bf16 v[58:61], v[190:193], v[198:201], v[58:61]
	v_mfma_f32_16x16x32_bf16 v[62:65], v[170:173], v[206:209], v[62:65]
	v_mfma_f32_16x16x32_bf16 v[66:69], v[190:193], v[206:209], v[66:69]
	v_mfma_f32_16x16x32_bf16 v[26:29], v[170:173], v[214:217], v[26:29]
	v_mfma_f32_16x16x32_bf16 v[34:37], v[190:193], v[214:217], v[34:37]
	v_mfma_f32_16x16x32_bf16 v[6:9], v[170:173], v[238:241], v[6:9]
	v_mfma_f32_16x16x32_bf16 v[14:17], v[190:193], v[238:241], v[14:17]
	v_mfma_f32_16x16x32_bf16 v[46:49], v[174:177], v[202:205], v[46:49]
	v_mfma_f32_16x16x32_bf16 v[58:61], v[194:197], v[202:205], v[58:61]
	v_mfma_f32_16x16x32_bf16 v[62:65], v[174:177], v[210:213], v[62:65]
	v_mfma_f32_16x16x32_bf16 v[66:69], v[194:197], v[210:213], v[66:69]
	v_mfma_f32_16x16x32_bf16 v[26:29], v[174:177], v[218:221], v[26:29]
	v_mfma_f32_16x16x32_bf16 v[34:37], v[194:197], v[218:221], v[34:37]
	v_mfma_f32_16x16x32_bf16 v[6:9], v[174:177], v[242:245], v[6:9]
	v_mfma_f32_16x16x32_bf16 v[14:17], v[194:197], v[242:245], v[14:17]
	s_barrier
	s_setprio 0
	s_add_i32 s57, s57, 2
	s_add_u32 s38, s38, 0x100
	s_addc_u32 s39, s39, 0
	s_cmpk_gt_u32 s57, 0x53
	s_mov_b64 s[26:27], s[28:29]
	s_cbranch_scc0 .LBB0_2241
	s_and_b64 vcc, exec, s[18:19]
	s_cbranch_vccz .LBB0_2244
	s_barrier

.LBB0_2293:
	s_add_u32 s30, s28, 0x100
	s_addc_u32 s31, s29, 0
	s_add_i32 s46, 0, 0x10000
	s_cmpk_eq_i32 s45, 0x52
	s_cselect_b32 s39, s25, s31
	s_cselect_b32 s38, s24, s30
	s_cselect_b32 s35, s27, s44
	s_cselect_b32 s34, s26, s43
	s_add_i32 s47, 0, 0x14000
	v_add_u32_e32 v142, s46, v200
	v_add_u32_e32 v176, s47, v200
	ds_read_b128 v[130:133], v142
	ds_read_b128 v[134:137], v142 offset:1024
	ds_read_b128 v[138:141], v142 offset:2048
	ds_read_b128 v[142:145], v142 offset:3072
	ds_read_b128 v[164:167], v176
	ds_read_b128 v[168:171], v176 offset:1024
	ds_read_b128 v[172:175], v176 offset:2048
	ds_read_b128 v[176:179], v176 offset:3072
	v_lshl_add_u64 v[222:223], s[28:29], 0, v[160:161]
	s_add_i32 m0, s56, 0xc000
	ds_read_b128 v[190:193], v201
	ds_read_b128 v[202:205], v201 offset:1024
	ds_read_b128 v[206:209], v201 offset:2048
	ds_read_b128 v[210:213], v201 offset:3072
	ds_read_b128 v[214:217], v201 offset:4096
	ds_read_b128 v[218:221], v201 offset:5120
	ds_read_b128 v[238:241], v201 offset:6144
	ds_read_b128 v[242:245], v201 offset:7168
	global_load_lds_dwordx4 v[222:223], off
	v_lshl_add_u64 v[222:223], s[28:29], 0, v[162:163]
	s_add_i32 m0, s56, 0xe000
	s_nop 0
	global_load_lds_dwordx4 v[222:223], off
	s_waitcnt vmcnt(8)
	s_waitcnt lgkmcnt(0)
	s_setprio 1
	s_barrier
	v_mfma_f32_16x16x32_bf16 v[118:121], v[130:133], v[190:193], v[118:121]
	v_mfma_f32_16x16x32_bf16 v[114:117], v[138:141], v[190:193], v[114:117]
	v_mfma_f32_16x16x32_bf16 v[98:101], v[130:133], v[206:209], v[98:101]
	v_mfma_f32_16x16x32_bf16 v[102:105], v[138:141], v[206:209], v[102:105]
	v_mfma_f32_16x16x32_bf16 v[70:73], v[130:133], v[214:217], v[70:73]
	v_mfma_f32_16x16x32_bf16 v[74:77], v[138:141], v[214:217], v[74:77]
	v_mfma_f32_16x16x32_bf16 v[30:33], v[130:133], v[238:241], v[30:33]
	v_mfma_f32_16x16x32_bf16 v[34:37], v[138:141], v[238:241], v[34:37]
	v_mfma_f32_16x16x32_bf16 v[118:121], v[134:137], v[202:205], v[118:121]
	v_mfma_f32_16x16x32_bf16 v[114:117], v[142:145], v[202:205], v[114:117]
	v_mfma_f32_16x16x32_bf16 v[98:101], v[134:137], v[210:213], v[98:101]
	v_mfma_f32_16x16x32_bf16 v[102:105], v[142:145], v[210:213], v[102:105]
	v_mfma_f32_16x16x32_bf16 v[70:73], v[134:137], v[218:221], v[70:73]
	v_mfma_f32_16x16x32_bf16 v[74:77], v[142:145], v[218:221], v[74:77]
	v_mfma_f32_16x16x32_bf16 v[30:33], v[134:137], v[242:245], v[30:33]
	v_mfma_f32_16x16x32_bf16 v[34:37], v[142:145], v[242:245], v[34:37]
	v_mfma_f32_16x16x32_bf16 v[126:129], v[164:167], v[190:193], v[126:129]
	v_mfma_f32_16x16x32_bf16 v[122:125], v[172:175], v[190:193], v[122:125]
	v_mfma_f32_16x16x32_bf16 v[106:109], v[164:167], v[206:209], v[106:109]
	v_mfma_f32_16x16x32_bf16 v[110:113], v[172:175], v[206:209], v[110:113]
	v_mfma_f32_16x16x32_bf16 v[82:85], v[164:167], v[214:217], v[82:85]
	v_mfma_f32_16x16x32_bf16 v[86:89], v[172:175], v[214:217], v[86:89]
	v_mfma_f32_16x16x32_bf16 v[54:57], v[164:167], v[238:241], v[54:57]
	v_mfma_f32_16x16x32_bf16 v[58:61], v[172:175], v[238:241], v[58:61]
	v_mfma_f32_16x16x32_bf16 v[126:129], v[168:171], v[202:205], v[126:129]
	v_mfma_f32_16x16x32_bf16 v[122:125], v[176:179], v[202:205], v[122:125]
	v_mfma_f32_16x16x32_bf16 v[106:109], v[168:171], v[210:213], v[106:109]
	v_mfma_f32_16x16x32_bf16 v[110:113], v[176:179], v[210:213], v[110:113]
	v_mfma_f32_16x16x32_bf16 v[82:85], v[168:171], v[218:221], v[82:85]
	v_mfma_f32_16x16x32_bf16 v[86:89], v[176:179], v[218:221], v[86:89]
	v_mfma_f32_16x16x32_bf16 v[54:57], v[168:171], v[242:245], v[54:57]
	v_mfma_f32_16x16x32_bf16 v[58:61], v[176:179], v[242:245], v[58:61]
	s_barrier
	s_setprio 0
	s_add_i32 s28, s46, s21
	v_lshl_add_u64 v[222:223], s[34:35], 0, v[150:151]
	s_mov_b32 m0, s28
	ds_read_b128 v[190:193], v201 offset:16384
	ds_read_b128 v[202:205], v201 offset:17408
	ds_read_b128 v[206:209], v201 offset:18432
	ds_read_b128 v[210:213], v201 offset:19456
	ds_read_b128 v[214:217], v201 offset:20480
	ds_read_b128 v[218:221], v201 offset:21504
	ds_read_b128 v[238:241], v201 offset:22528
	ds_read_b128 v[242:245], v201 offset:23552
	global_load_lds_dwordx4 v[222:223], off
	s_add_i32 m0, s28, 0x2000
	s_add_u32 s28, s34, 0x158000
	v_lshl_add_u64 v[246:247], s[34:35], 0, v[154:155]
	s_addc_u32 s29, s35, 0
	s_add_i32 s46, s47, s21
	global_load_lds_dwordx4 v[246:247], off
	v_lshl_add_u64 v[248:249], s[28:29], 0, v[150:151]
	s_mov_b32 m0, s46
	v_lshl_add_u64 v[250:251], s[38:39], 0, v[152:153]
	global_load_lds_dwordx4 v[248:249], off
	v_lshl_add_u64 v[248:249], s[28:29], 0, v[154:155]
	s_add_i32 m0, s46, 0x2000
	s_nop 0
	global_load_lds_dwordx4 v[248:249], off
	v_lshl_add_u64 v[248:249], s[38:39], 0, v[148:149]
	s_mov_b32 m0, s56
	s_nop 0
	global_load_lds_dwordx4 v[248:249], off
	s_mov_b32 m0, s57
	s_nop 0
	global_load_lds_dwordx4 v[250:251], off
	s_waitcnt vmcnt(8)
	s_waitcnt lgkmcnt(0)
	s_setprio 1
	s_barrier
	v_mfma_f32_16x16x32_bf16 v[22:25], v[130:133], v[190:193], v[22:25]
	v_mfma_f32_16x16x32_bf16 v[26:29], v[138:141], v[190:193], v[26:29]
	v_mfma_f32_16x16x32_bf16 v[10:13], v[130:133], v[206:209], v[10:13]
	v_mfma_f32_16x16x32_bf16 v[78:81], v[138:141], v[206:209], v[78:81]
	v_mfma_f32_16x16x32_bf16 v[38:41], v[130:133], v[214:217], v[38:41]
	v_mfma_f32_16x16x32_bf16 v[42:45], v[138:141], v[214:217], v[42:45]
	v_mfma_f32_16x16x32_bf16 v[2:5], v[130:133], v[238:241], v[2:5]
	v_mfma_f32_16x16x32_bf16 v[6:9], v[138:141], v[238:241], v[6:9]
	v_mfma_f32_16x16x32_bf16 v[22:25], v[134:137], v[202:205], v[22:25]
	v_mfma_f32_16x16x32_bf16 v[26:29], v[142:145], v[202:205], v[26:29]
	v_mfma_f32_16x16x32_bf16 v[10:13], v[134:137], v[210:213], v[10:13]
	v_mfma_f32_16x16x32_bf16 v[78:81], v[142:145], v[210:213], v[78:81]
	v_mfma_f32_16x16x32_bf16 v[38:41], v[134:137], v[218:221], v[38:41]
	v_mfma_f32_16x16x32_bf16 v[42:45], v[142:145], v[218:221], v[42:45]
	v_mfma_f32_16x16x32_bf16 v[2:5], v[134:137], v[242:245], v[2:5]
	v_mfma_f32_16x16x32_bf16 v[6:9], v[142:145], v[242:245], v[6:9]
	v_mfma_f32_16x16x32_bf16 v[46:49], v[164:167], v[190:193], v[46:49]
	v_mfma_f32_16x16x32_bf16 v[50:53], v[172:175], v[190:193], v[50:53]
	v_mfma_f32_16x16x32_bf16 v[90:93], v[164:167], v[206:209], v[90:93]
	v_mfma_f32_16x16x32_bf16 v[94:97], v[172:175], v[206:209], v[94:97]
	v_mfma_f32_16x16x32_bf16 v[62:65], v[164:167], v[214:217], v[62:65]
	v_mfma_f32_16x16x32_bf16 v[66:69], v[172:175], v[214:217], v[66:69]
	v_mfma_f32_16x16x32_bf16 v[14:17], v[164:167], v[238:241], v[14:17]
	v_mfma_f32_16x16x32_bf16 v[18:21], v[172:175], v[238:241], v[18:21]
	v_mfma_f32_16x16x32_bf16 v[46:49], v[168:171], v[202:205], v[46:49]
	v_mfma_f32_16x16x32_bf16 v[50:53], v[176:179], v[202:205], v[50:53]
	v_mfma_f32_16x16x32_bf16 v[90:93], v[168:171], v[210:213], v[90:93]
	v_mfma_f32_16x16x32_bf16 v[94:97], v[176:179], v[210:213], v[94:97]
	v_mfma_f32_16x16x32_bf16 v[62:65], v[168:171], v[218:221], v[62:65]
	v_mfma_f32_16x16x32_bf16 v[66:69], v[176:179], v[218:221], v[66:69]
	v_mfma_f32_16x16x32_bf16 v[14:17], v[168:171], v[242:245], v[14:17]
	v_mfma_f32_16x16x32_bf16 v[18:21], v[176:179], v[242:245], v[18:21]
	s_barrier
	s_setprio 0
	s_add_i32 s46, 0, 0x18000
	s_add_i32 s47, 0, 0x1c000
	v_add_u32_e32 v142, s46, v200
	v_add_u32_e32 v176, s47, v200
	ds_read_b128 v[130:133], v142
	ds_read_b128 v[134:137], v142 offset:1024
	ds_read_b128 v[138:141], v142 offset:2048
	ds_read_b128 v[142:145], v142 offset:3072
	ds_read_b128 v[164:167], v176
	ds_read_b128 v[168:171], v176 offset:1024
	ds_read_b128 v[172:175], v176 offset:2048
	ds_read_b128 v[176:179], v176 offset:3072
	s_add_u32 s28, s38, 0x158000
	s_addc_u32 s29, s39, 0
	s_mov_b32 m0, s58
	v_lshl_add_u64 v[252:253], s[28:29], 0, v[148:149]
	ds_read_b128 v[190:193], v201 offset:32768
	ds_read_b128 v[202:205], v201 offset:33792
	ds_read_b128 v[206:209], v201 offset:34816
	ds_read_b128 v[210:213], v201 offset:35840
	ds_read_b128 v[214:217], v201 offset:36864
	ds_read_b128 v[218:221], v201 offset:37888
	ds_read_b128 v[238:241], v201 offset:38912
	ds_read_b128 v[242:245], v201 offset:39936
	global_load_lds_dwordx4 v[252:253], off
	v_lshl_add_u64 v[252:253], s[28:29], 0, v[152:153]
	s_mov_b32 m0, s59
	s_nop 0
	global_load_lds_dwordx4 v[252:253], off
	s_waitcnt vmcnt(8)
	s_waitcnt lgkmcnt(0)
	s_setprio 1
	s_barrier
	v_mfma_f32_16x16x32_bf16 v[118:121], v[130:133], v[190:193], v[118:121]
	v_mfma_f32_16x16x32_bf16 v[114:117], v[138:141], v[190:193], v[114:117]
	v_mfma_f32_16x16x32_bf16 v[98:101], v[130:133], v[206:209], v[98:101]
	v_mfma_f32_16x16x32_bf16 v[102:105], v[138:141], v[206:209], v[102:105]
	v_mfma_f32_16x16x32_bf16 v[70:73], v[130:133], v[214:217], v[70:73]
	v_mfma_f32_16x16x32_bf16 v[74:77], v[138:141], v[214:217], v[74:77]
	v_mfma_f32_16x16x32_bf16 v[30:33], v[130:133], v[238:241], v[30:33]
	v_mfma_f32_16x16x32_bf16 v[34:37], v[138:141], v[238:241], v[34:37]
	v_mfma_f32_16x16x32_bf16 v[118:121], v[134:137], v[202:205], v[118:121]
	v_mfma_f32_16x16x32_bf16 v[114:117], v[142:145], v[202:205], v[114:117]
	v_mfma_f32_16x16x32_bf16 v[98:101], v[134:137], v[210:213], v[98:101]
	v_mfma_f32_16x16x32_bf16 v[102:105], v[142:145], v[210:213], v[102:105]
	v_mfma_f32_16x16x32_bf16 v[70:73], v[134:137], v[218:221], v[70:73]
	v_mfma_f32_16x16x32_bf16 v[74:77], v[142:145], v[218:221], v[74:77]
	v_mfma_f32_16x16x32_bf16 v[30:33], v[134:137], v[242:245], v[30:33]
	v_mfma_f32_16x16x32_bf16 v[34:37], v[142:145], v[242:245], v[34:37]
	v_mfma_f32_16x16x32_bf16 v[126:129], v[164:167], v[190:193], v[126:129]
	v_mfma_f32_16x16x32_bf16 v[122:125], v[172:175], v[190:193], v[122:125]
	v_mfma_f32_16x16x32_bf16 v[106:109], v[164:167], v[206:209], v[106:109]
	v_mfma_f32_16x16x32_bf16 v[110:113], v[172:175], v[206:209], v[110:113]
	v_mfma_f32_16x16x32_bf16 v[82:85], v[164:167], v[214:217], v[82:85]
	v_mfma_f32_16x16x32_bf16 v[86:89], v[172:175], v[214:217], v[86:89]
	v_mfma_f32_16x16x32_bf16 v[54:57], v[164:167], v[238:241], v[54:57]
	v_mfma_f32_16x16x32_bf16 v[58:61], v[172:175], v[238:241], v[58:61]
	v_mfma_f32_16x16x32_bf16 v[126:129], v[168:171], v[202:205], v[126:129]
	v_mfma_f32_16x16x32_bf16 v[122:125], v[176:179], v[202:205], v[122:125]
	v_mfma_f32_16x16x32_bf16 v[106:109], v[168:171], v[210:213], v[106:109]
	v_mfma_f32_16x16x32_bf16 v[110:113], v[176:179], v[210:213], v[110:113]
	v_mfma_f32_16x16x32_bf16 v[82:85], v[168:171], v[218:221], v[82:85]
	v_mfma_f32_16x16x32_bf16 v[86:89], v[176:179], v[218:221], v[86:89]
	v_mfma_f32_16x16x32_bf16 v[54:57], v[168:171], v[242:245], v[54:57]
	v_mfma_f32_16x16x32_bf16 v[58:61], v[176:179], v[242:245], v[58:61]
	s_barrier
	s_setprio 0
	s_add_i32 s28, s46, s21
	v_lshl_add_u64 v[222:223], v[222:223], 0, s[16:17]
	s_mov_b32 m0, s28
	ds_read_b128 v[190:193], v201 offset:49152
	ds_read_b128 v[202:205], v201 offset:50176
	ds_read_b128 v[206:209], v201 offset:51200
	ds_read_b128 v[210:213], v201 offset:52224
	ds_read_b128 v[214:217], v201 offset:53248
	ds_read_b128 v[218:221], v201 offset:54272
	ds_read_b128 v[238:241], v201 offset:55296
	ds_read_b128 v[242:245], v201 offset:56320
	global_load_lds_dwordx4 v[222:223], off
	s_add_i32 m0, s28, 0x2000
	s_add_u32 s28, s34, 0x158080
	v_lshl_add_u64 v[222:223], v[246:247], 0, s[16:17]
	s_addc_u32 s29, s35, 0
	s_add_i32 s34, s47, s21
	global_load_lds_dwordx4 v[222:223], off
	v_lshl_add_u64 v[222:223], s[28:29], 0, v[150:151]
	s_mov_b32 m0, s34
	s_nop 0
	global_load_lds_dwordx4 v[222:223], off
	v_lshl_add_u64 v[222:223], s[28:29], 0, v[154:155]
	s_add_i32 m0, s34, 0x2000
	s_nop 0
	global_load_lds_dwordx4 v[222:223], off
	v_lshl_add_u64 v[222:223], v[248:249], 0, s[16:17]
	s_mov_b32 m0, s60
	s_nop 0
	global_load_lds_dwordx4 v[222:223], off
	v_lshl_add_u64 v[222:223], v[250:251], 0, s[16:17]
	s_mov_b32 m0, s61
	s_nop 0
	global_load_lds_dwordx4 v[222:223], off
	s_waitcnt vmcnt(8)
	s_waitcnt lgkmcnt(0)
	s_setprio 1
	s_barrier
	v_mfma_f32_16x16x32_bf16 v[22:25], v[130:133], v[190:193], v[22:25]
	v_mfma_f32_16x16x32_bf16 v[26:29], v[138:141], v[190:193], v[26:29]
	v_mfma_f32_16x16x32_bf16 v[10:13], v[130:133], v[206:209], v[10:13]
	v_mfma_f32_16x16x32_bf16 v[78:81], v[138:141], v[206:209], v[78:81]
	v_mfma_f32_16x16x32_bf16 v[38:41], v[130:133], v[214:217], v[38:41]
	v_mfma_f32_16x16x32_bf16 v[42:45], v[138:141], v[214:217], v[42:45]
	v_mfma_f32_16x16x32_bf16 v[2:5], v[130:133], v[238:241], v[2:5]
	v_mfma_f32_16x16x32_bf16 v[6:9], v[138:141], v[238:241], v[6:9]
	v_mfma_f32_16x16x32_bf16 v[22:25], v[134:137], v[202:205], v[22:25]
	v_mfma_f32_16x16x32_bf16 v[26:29], v[142:145], v[202:205], v[26:29]
	v_mfma_f32_16x16x32_bf16 v[10:13], v[134:137], v[210:213], v[10:13]
	v_mfma_f32_16x16x32_bf16 v[78:81], v[142:145], v[210:213], v[78:81]
	v_mfma_f32_16x16x32_bf16 v[38:41], v[134:137], v[218:221], v[38:41]
	v_mfma_f32_16x16x32_bf16 v[42:45], v[142:145], v[218:221], v[42:45]
	v_mfma_f32_16x16x32_bf16 v[2:5], v[134:137], v[242:245], v[2:5]
	v_mfma_f32_16x16x32_bf16 v[6:9], v[142:145], v[242:245], v[6:9]
	v_mfma_f32_16x16x32_bf16 v[46:49], v[164:167], v[190:193], v[46:49]
	v_mfma_f32_16x16x32_bf16 v[50:53], v[172:175], v[190:193], v[50:53]
	v_mfma_f32_16x16x32_bf16 v[90:93], v[164:167], v[206:209], v[90:93]
	v_mfma_f32_16x16x32_bf16 v[94:97], v[172:175], v[206:209], v[94:97]
	v_mfma_f32_16x16x32_bf16 v[62:65], v[164:167], v[214:217], v[62:65]
	v_mfma_f32_16x16x32_bf16 v[66:69], v[172:175], v[214:217], v[66:69]
	v_mfma_f32_16x16x32_bf16 v[14:17], v[164:167], v[238:241], v[14:17]
	v_mfma_f32_16x16x32_bf16 v[18:21], v[172:175], v[238:241], v[18:21]
	v_mfma_f32_16x16x32_bf16 v[46:49], v[168:171], v[202:205], v[46:49]
	v_mfma_f32_16x16x32_bf16 v[50:53], v[176:179], v[202:205], v[50:53]
	v_mfma_f32_16x16x32_bf16 v[90:93], v[168:171], v[210:213], v[90:93]
	v_mfma_f32_16x16x32_bf16 v[94:97], v[176:179], v[210:213], v[94:97]
	v_mfma_f32_16x16x32_bf16 v[62:65], v[168:171], v[218:221], v[62:65]
	v_mfma_f32_16x16x32_bf16 v[66:69], v[176:179], v[218:221], v[66:69]
	v_mfma_f32_16x16x32_bf16 v[14:17], v[168:171], v[242:245], v[14:17]
	v_mfma_f32_16x16x32_bf16 v[18:21], v[176:179], v[242:245], v[18:21]
	s_barrier
	s_setprio 0
	s_add_i32 s45, s45, 2
	s_add_u32 s43, s43, 0x100
	s_addc_u32 s44, s44, 0
	s_cmpk_gt_u32 s45, 0x53
	s_mov_b64 s[28:29], s[30:31]
	s_cbranch_scc0 .LBB0_2293
	s_and_b64 vcc, exec, s[22:23]
	s_cbranch_vccz .LBB0_2296
	s_barrier
